# v28: gelu |v| and -|v| taken as source modifiers of scalar fma (no separate abs instructions, no abs registers), same operations per lane
# baseline (speedup 1.0000x reference)
; __device__ __forceinline__ f32x4 gelu4(f32x4 v) { f32x2 a = gelu_pk((f32x2){v[0], v[1]}), b = gelu_pk((f32x2){v[2], v[3]}); return (f32x4){a.x, a.y, b.x, b.y}; }
; __device__ __forceinline__ f32x2 gelu_pk(f32x2 v) {
;     const f32x2 av = __builtin_elementwise_abs(v), d = av * 0.2316418882f + 1.0f;
;     f32x2 t; t.x = __builtin_amdgcn_rcpf(d.x); t.y = __builtin_amdgcn_rcpf(d.y);
;     f32x2 q = t * 0.5307027145f + (-0.7265760135f); q = q * t + 0.7107068705f; q = q * t + (-0.142248368f); q = q * t + 0.127414796f; q = q * t;
;     const f32x2 s = (v * v) * (-0.72134752044f);
;     f32x2 e; e.x = __builtin_amdgcn_exp2f(s.x); e.y = __builtin_amdgcn_exp2f(s.y);
;     const f32x2 m = v * (q * e), r = v - m;
;     f32x2 o; o.x = v.x < 0.f ? m.x : r.x; o.y = v.y < 0.f ? m.y : r.y; return o;
;     __device__ __forceinline__ void operator()(const f32x4 (&acc)[2][2][4][2], const pg8::Unit& u, int wr, int wc, int fr, int fq) const {
;     ...
;                         else if (act == 1) { v0 = gelu4(v0); v1 = gelu4(v1); }
.LBB0_195:
	s_andn2_b64 vcc, exec, s[16:17]
	s_cbranch_vccnz .LBB0_197
	v_fma_f32 v148, |v124|, s28, 1.0
	v_fma_f32 v149, |v125|, s28, 1.0
	v_mov_b64_e32 v[152:153], s[34:35]
	v_rcp_f32_e32 v148, v148
	v_rcp_f32_e32 v149, v149
	v_pk_mul_f32 v[156:157], v[126:127], v[126:127]
	v_pk_mul_f32 v[160:161], v[118:119], v[118:119]
	v_pk_fma_f32 v[154:155], v[148:149], s[30:31], v[152:153] op_sel_hi:[1,0,0]
	v_pk_mul_f32 v[156:157], v[156:157], s[74:75] op_sel_hi:[1,0]
	v_pk_fma_f32 v[154:155], v[148:149], v[154:155], s[36:37] op_sel_hi:[1,1,0]
	v_exp_f32_e32 v156, v156
	v_pk_fma_f32 v[154:155], v[148:149], v[154:155], s[50:51] op_sel_hi:[1,1,0]
	v_exp_f32_e32 v157, v157
	v_pk_fma_f32 v[154:155], v[148:149], v[154:155], s[72:73] op_sel_hi:[1,1,0]
	s_nop 0
	v_pk_mul_f32 v[148:149], v[148:149], v[154:155]
	v_pk_mul_f32 v[154:155], v[124:125], v[124:125]
	s_nop 0
	v_pk_mul_f32 v[154:155], v[154:155], s[74:75] op_sel_hi:[1,0]
	s_nop 0
	v_exp_f32_e32 v154, v154
	v_exp_f32_e32 v155, v155
	s_nop 0
	v_pk_mul_f32 v[148:149], v[154:155], v[148:149]
	s_nop 0
	v_max_f32_e32 v240, 0, v124
	v_max_f32_e32 v241, 0, v125
	v_fma_f32 v154, -|v124|, v148, v240
	v_fma_f32 v155, -|v125|, v149, v241
	s_nop 0
	s_nop 0
	v_fma_f32 v148, |v126|, s28, 1.0
	v_fma_f32 v149, |v127|, s28, 1.0
	s_nop 0
	v_rcp_f32_e32 v148, v148
	v_rcp_f32_e32 v149, v149
	s_nop 0
	v_pk_fma_f32 v[158:159], v[148:149], s[30:31], v[152:153] op_sel_hi:[1,0,0]
	s_nop 0
	v_pk_fma_f32 v[158:159], v[148:149], v[158:159], s[36:37] op_sel_hi:[1,1,0]
	s_nop 0
	v_pk_fma_f32 v[158:159], v[148:149], v[158:159], s[50:51] op_sel_hi:[1,1,0]
	s_nop 0
	v_pk_fma_f32 v[158:159], v[148:149], v[158:159], s[72:73] op_sel_hi:[1,1,0]
	s_nop 0
	v_pk_mul_f32 v[148:149], v[148:149], v[158:159]
	s_nop 0
	v_pk_mul_f32 v[148:149], v[156:157], v[148:149]
	s_nop 0
	v_max_f32_e32 v240, 0, v126
	v_max_f32_e32 v241, 0, v127
	v_fma_f32 v156, -|v126|, v148, v240
	v_fma_f32 v157, -|v127|, v149, v241
	s_nop 0
	s_nop 0
	v_fma_f32 v148, |v116|, s28, 1.0
	v_fma_f32 v149, |v117|, s28, 1.0
	s_nop 0
	v_rcp_f32_e32 v148, v148
	v_rcp_f32_e32 v149, v149
	s_nop 0
	v_pk_fma_f32 v[158:159], v[148:149], s[30:31], v[152:153] op_sel_hi:[1,0,0]
	s_nop 0
	v_pk_fma_f32 v[158:159], v[148:149], v[158:159], s[36:37] op_sel_hi:[1,1,0]
	s_nop 0
	v_pk_fma_f32 v[158:159], v[148:149], v[158:159], s[50:51] op_sel_hi:[1,1,0]
	s_nop 0
	v_pk_fma_f32 v[158:159], v[148:149], v[158:159], s[72:73] op_sel_hi:[1,1,0]
	s_nop 0
	v_pk_mul_f32 v[148:149], v[148:149], v[158:159]
	v_pk_mul_f32 v[158:159], v[116:117], v[116:117]
	s_nop 0
	v_pk_mul_f32 v[158:159], v[158:159], s[74:75] op_sel_hi:[1,0]
	s_nop 0
	v_exp_f32_e32 v158, v158
	v_exp_f32_e32 v159, v159
	s_nop 0
	v_pk_mul_f32 v[148:149], v[158:159], v[148:149]
	s_nop 0
	v_max_f32_e32 v240, 0, v116
	v_max_f32_e32 v241, 0, v117
	v_fma_f32 v158, -|v116|, v148, v240
	v_fma_f32 v159, -|v117|, v149, v241
	s_nop 0
	s_nop 0
	v_fma_f32 v148, |v118|, s28, 1.0
	v_fma_f32 v149, |v119|, s28, 1.0
	s_nop 0
	v_rcp_f32_e32 v148, v148
	v_rcp_f32_e32 v149, v149
	s_nop 0
	v_pk_fma_f32 v[152:153], v[148:149], s[30:31], v[152:153] op_sel_hi:[1,0,0]
	s_nop 0
	v_pk_fma_f32 v[152:153], v[148:149], v[152:153], s[36:37] op_sel_hi:[1,1,0]
	s_nop 0
	v_pk_fma_f32 v[152:153], v[148:149], v[152:153], s[50:51] op_sel_hi:[1,1,0]
	s_nop 0
	v_pk_fma_f32 v[152:153], v[148:149], v[152:153], s[72:73] op_sel_hi:[1,1,0]
	s_nop 0
	v_pk_mul_f32 v[148:149], v[148:149], v[152:153]
	v_pk_mul_f32 v[152:153], v[160:161], s[74:75] op_sel_hi:[1,0]
	s_nop 0
	v_exp_f32_e32 v152, v152
	v_exp_f32_e32 v153, v153
	s_nop 0
	v_pk_mul_f32 v[148:149], v[152:153], v[148:149]
	s_nop 0
	v_max_f32_e32 v240, 0, v118
	v_max_f32_e32 v241, 0, v119
	v_fma_f32 v160, -|v118|, v148, v240
	v_fma_f32 v161, -|v119|, v149, v241
	s_nop 0
	s_nop 1

; __device__ __forceinline__ f32x4 gelu4(f32x4 v) { f32x2 a = gelu_pk((f32x2){v[0], v[1]}), b = gelu_pk((f32x2){v[2], v[3]}); return (f32x4){a.x, a.y, b.x, b.y}; }
; __device__ __forceinline__ f32x2 gelu_pk(f32x2 v) {
;     const f32x2 av = __builtin_elementwise_abs(v), d = av * 0.2316418882f + 1.0f;
;     f32x2 t; t.x = __builtin_amdgcn_rcpf(d.x); t.y = __builtin_amdgcn_rcpf(d.y);
;     f32x2 q = t * 0.5307027145f + (-0.7265760135f); q = q * t + 0.7107068705f; q = q * t + (-0.142248368f); q = q * t + 0.127414796f; q = q * t;
;     const f32x2 s = (v * v) * (-0.72134752044f);
;     f32x2 e; e.x = __builtin_amdgcn_exp2f(s.x); e.y = __builtin_amdgcn_exp2f(s.y);
;     const f32x2 m = v * (q * e), r = v - m;
;     f32x2 o; o.x = v.x < 0.f ? m.x : r.x; o.y = v.y < 0.f ? m.y : r.y; return o;
;     __device__ __forceinline__ void operator()(const f32x4 (&acc)[2][2][4][2], const pg8::Unit& u, int wr, int wc, int fr, int fq) const {
;     ...
;                         else if (act == 1) { v0 = gelu4(v0); v1 = gelu4(v1); }
.LBB0_209:
	s_andn2_b64 vcc, exec, s[16:17]
	s_cbranch_vccnz .LBB0_211
	v_fma_f32 v154, |v120|, s28, 1.0
	v_fma_f32 v155, |v121|, s28, 1.0
	v_mov_b64_e32 v[160:161], s[34:35]
	v_rcp_f32_e32 v154, v154
	v_rcp_f32_e32 v155, v155
	v_pk_mul_f32 v[158:159], v[120:121], v[120:121]
	s_nop 0
	v_pk_mul_f32 v[158:159], v[158:159], s[74:75] op_sel_hi:[1,0]
	v_pk_fma_f32 v[156:157], v[154:155], s[30:31], v[160:161] op_sel_hi:[1,0,0]
	v_exp_f32_e32 v158, v158
	v_pk_fma_f32 v[156:157], v[154:155], v[156:157], s[36:37] op_sel_hi:[1,1,0]
	v_exp_f32_e32 v159, v159
	v_pk_fma_f32 v[156:157], v[154:155], v[156:157], s[50:51] op_sel_hi:[1,1,0]
	s_nop 0
	v_pk_fma_f32 v[156:157], v[154:155], v[156:157], s[72:73] op_sel_hi:[1,1,0]
	v_fma_f32 v168, |v122|, s28, 1.0
	v_fma_f32 v169, |v123|, s28, 1.0
	v_pk_mul_f32 v[154:155], v[154:155], v[156:157]
	v_rcp_f32_e32 v168, v168
	v_rcp_f32_e32 v169, v169
	v_pk_mul_f32 v[154:155], v[158:159], v[154:155]
	v_max_f32_e32 v240, 0, v120
	v_max_f32_e32 v241, 0, v121
	v_fma_f32 v154, -|v120|, v154, v240
	v_fma_f32 v155, -|v121|, v155, v241
	v_pk_mul_f32 v[156:157], v[122:123], v[122:123]
	s_nop 0
	v_pk_mul_f32 v[156:157], v[156:157], s[74:75] op_sel_hi:[1,0]
	v_pk_fma_f32 v[158:159], v[168:169], s[30:31], v[160:161] op_sel_hi:[1,0,0]
	v_exp_f32_e32 v156, v156
	v_pk_fma_f32 v[158:159], v[168:169], v[158:159], s[36:37] op_sel_hi:[1,1,0]
	v_exp_f32_e32 v157, v157
	v_pk_fma_f32 v[158:159], v[168:169], v[158:159], s[50:51] op_sel_hi:[1,1,0]
	s_nop 0
	v_pk_fma_f32 v[158:159], v[168:169], v[158:159], s[72:73] op_sel_hi:[1,1,0]
	s_nop 0
	v_pk_mul_f32 v[158:159], v[168:169], v[158:159]
	v_fma_f32 v168, |v112|, s28, 1.0
	v_fma_f32 v169, |v113|, s28, 1.0
	v_pk_mul_f32 v[156:157], v[156:157], v[158:159]
	v_rcp_f32_e32 v168, v168
	v_rcp_f32_e32 v169, v169
	v_max_f32_e32 v240, 0, v122
	v_max_f32_e32 v241, 0, v123
	v_fma_f32 v156, -|v122|, v156, v240
	v_fma_f32 v157, -|v123|, v157, v241
	v_fma_f32 v172, |v114|, s28, 1.0
	v_fma_f32 v173, |v115|, s28, 1.0
	s_nop 0
	v_rcp_f32_e32 v172, v172
	v_rcp_f32_e32 v173, v173
	v_pk_fma_f32 v[158:159], v[168:169], s[30:31], v[160:161] op_sel_hi:[1,0,0]
	v_pk_mul_f32 v[170:171], v[112:113], v[112:113]
	v_pk_fma_f32 v[158:159], v[168:169], v[158:159], s[36:37] op_sel_hi:[1,1,0]
	v_pk_mul_f32 v[170:171], v[170:171], s[74:75] op_sel_hi:[1,0]
	v_pk_fma_f32 v[158:159], v[168:169], v[158:159], s[50:51] op_sel_hi:[1,1,0]
	v_exp_f32_e32 v170, v170
	v_pk_fma_f32 v[158:159], v[168:169], v[158:159], s[72:73] op_sel_hi:[1,1,0]
	v_exp_f32_e32 v171, v171
	v_pk_mul_f32 v[158:159], v[168:169], v[158:159]
	v_pk_mul_f32 v[168:169], v[114:115], v[114:115]
	v_pk_fma_f32 v[160:161], v[172:173], s[30:31], v[160:161] op_sel_hi:[1,0,0]
	v_pk_mul_f32 v[168:169], v[168:169], s[74:75] op_sel_hi:[1,0]
	v_pk_fma_f32 v[160:161], v[172:173], v[160:161], s[36:37] op_sel_hi:[1,1,0]
	v_exp_f32_e32 v168, v168
	v_exp_f32_e32 v169, v169
	v_pk_fma_f32 v[160:161], v[172:173], v[160:161], s[50:51] op_sel_hi:[1,1,0]
	v_pk_mul_f32 v[158:159], v[170:171], v[158:159]
	v_pk_fma_f32 v[160:161], v[172:173], v[160:161], s[72:73] op_sel_hi:[1,1,0]
	v_max_f32_e32 v240, 0, v112
	v_max_f32_e32 v241, 0, v113
	v_fma_f32 v158, -|v112|, v158, v240
	v_fma_f32 v159, -|v113|, v159, v241
	v_pk_mul_f32 v[160:161], v[172:173], v[160:161]
	s_nop 0
	v_pk_mul_f32 v[160:161], v[168:169], v[160:161]
	s_nop 0
	v_max_f32_e32 v240, 0, v114
	v_max_f32_e32 v241, 0, v115
	v_fma_f32 v160, -|v114|, v160, v240
	v_fma_f32 v161, -|v115|, v161, v241
	s_nop 1
	s_nop 1

; __device__ __forceinline__ f32x4 gelu4(f32x4 v) { f32x2 a = gelu_pk((f32x2){v[0], v[1]}), b = gelu_pk((f32x2){v[2], v[3]}); return (f32x4){a.x, a.y, b.x, b.y}; }
; __device__ __forceinline__ f32x2 gelu_pk(f32x2 v) {
;     const f32x2 av = __builtin_elementwise_abs(v), d = av * 0.2316418882f + 1.0f;
;     f32x2 t; t.x = __builtin_amdgcn_rcpf(d.x); t.y = __builtin_amdgcn_rcpf(d.y);
;     f32x2 q = t * 0.5307027145f + (-0.7265760135f); q = q * t + 0.7107068705f; q = q * t + (-0.142248368f); q = q * t + 0.127414796f; q = q * t;
;     const f32x2 s = (v * v) * (-0.72134752044f);
;     f32x2 e; e.x = __builtin_amdgcn_exp2f(s.x); e.y = __builtin_amdgcn_exp2f(s.y);
;     const f32x2 m = v * (q * e), r = v - m;
;     f32x2 o; o.x = v.x < 0.f ? m.x : r.x; o.y = v.y < 0.f ? m.y : r.y; return o;
;     __device__ __forceinline__ void operator()(const f32x4 (&acc)[2][2][4][2], const pg8::Unit& u, int wr, int wc, int fr, int fq) const {
;     ...
;                         else if (act == 1) { v0 = gelu4(v0); v1 = gelu4(v1); }
.LBB0_223:
	s_andn2_b64 vcc, exec, s[16:17]
	s_cbranch_vccnz .LBB0_225
	v_fma_f32 v152, |v108|, s28, 1.0
	v_fma_f32 v153, |v109|, s28, 1.0
	v_mov_b64_e32 v[160:161], s[34:35]
	v_rcp_f32_e32 v152, v152
	v_rcp_f32_e32 v153, v153
	v_pk_mul_f32 v[156:157], v[108:109], v[108:109]
	s_nop 0
	v_pk_mul_f32 v[156:157], v[156:157], s[74:75] op_sel_hi:[1,0]
	v_pk_fma_f32 v[154:155], v[152:153], s[30:31], v[160:161] op_sel_hi:[1,0,0]
	v_exp_f32_e32 v156, v156
	v_pk_fma_f32 v[154:155], v[152:153], v[154:155], s[36:37] op_sel_hi:[1,1,0]
	v_exp_f32_e32 v157, v157
	v_pk_fma_f32 v[154:155], v[152:153], v[154:155], s[50:51] op_sel_hi:[1,1,0]
	v_pk_mul_f32 v[158:159], v[110:111], v[110:111]
	v_pk_fma_f32 v[154:155], v[152:153], v[154:155], s[72:73] op_sel_hi:[1,1,0]
	v_pk_mul_f32 v[158:159], v[158:159], s[74:75] op_sel_hi:[1,0]
	v_pk_mul_f32 v[152:153], v[152:153], v[154:155]
	v_exp_f32_e32 v158, v158
	v_pk_mul_f32 v[152:153], v[156:157], v[152:153]
	v_fma_f32 v156, |v110|, s28, 1.0
	v_fma_f32 v157, |v111|, s28, 1.0
	s_nop 0
	v_rcp_f32_e32 v156, v156
	v_rcp_f32_e32 v157, v157
	v_max_f32_e32 v240, 0, v108
	v_max_f32_e32 v241, 0, v109
	v_fma_f32 v154, -|v108|, v152, v240
	v_fma_f32 v155, -|v109|, v153, v241
	v_exp_f32_e32 v159, v159
	v_pk_mul_f32 v[168:169], v[100:101], v[100:101]
	v_pk_mul_f32 v[170:171], v[102:103], v[102:103]
	v_pk_fma_f32 v[152:153], v[156:157], s[30:31], v[160:161] op_sel_hi:[1,0,0]
	s_nop 0
	v_pk_fma_f32 v[152:153], v[156:157], v[152:153], s[36:37] op_sel_hi:[1,1,0]
	v_pk_mul_f32 v[168:169], v[168:169], s[74:75] op_sel_hi:[1,0]
	v_pk_fma_f32 v[152:153], v[156:157], v[152:153], s[50:51] op_sel_hi:[1,1,0]
	v_exp_f32_e32 v168, v168
	v_pk_fma_f32 v[152:153], v[156:157], v[152:153], s[72:73] op_sel_hi:[1,1,0]
	v_exp_f32_e32 v169, v169
	v_pk_mul_f32 v[152:153], v[156:157], v[152:153]
	s_nop 0
	v_pk_mul_f32 v[152:153], v[158:159], v[152:153]
	v_fma_f32 v158, |v100|, s28, 1.0
	v_fma_f32 v159, |v101|, s28, 1.0
	s_nop 0
	v_rcp_f32_e32 v158, v158
	v_rcp_f32_e32 v159, v159
	v_max_f32_e32 v240, 0, v110
	v_max_f32_e32 v241, 0, v111
	v_fma_f32 v156, -|v110|, v152, v240
	v_fma_f32 v157, -|v111|, v153, v241
	s_nop 0
	s_nop 1
	v_pk_fma_f32 v[152:153], v[158:159], s[30:31], v[160:161] op_sel_hi:[1,0,0]
	s_nop 0
	v_pk_fma_f32 v[152:153], v[158:159], v[152:153], s[36:37] op_sel_hi:[1,1,0]
	s_nop 0
	v_pk_fma_f32 v[152:153], v[158:159], v[152:153], s[50:51] op_sel_hi:[1,1,0]
	s_nop 0
	v_pk_fma_f32 v[152:153], v[158:159], v[152:153], s[72:73] op_sel_hi:[1,1,0]
	s_nop 0
	v_pk_mul_f32 v[152:153], v[158:159], v[152:153]
	s_nop 0
	v_pk_mul_f32 v[152:153], v[168:169], v[152:153]
	v_fma_f32 v168, |v102|, s28, 1.0
	v_fma_f32 v169, |v103|, s28, 1.0
	s_nop 0
	v_rcp_f32_e32 v168, v168
	v_rcp_f32_e32 v169, v169
	v_max_f32_e32 v240, 0, v100
	v_max_f32_e32 v241, 0, v101
	v_fma_f32 v158, -|v100|, v152, v240
	v_fma_f32 v159, -|v101|, v153, v241
	s_nop 0
	s_nop 1
	v_pk_fma_f32 v[152:153], v[168:169], s[30:31], v[160:161] op_sel_hi:[1,0,0]
	v_pk_mul_f32 v[160:161], v[170:171], s[74:75] op_sel_hi:[1,0]
	v_pk_fma_f32 v[152:153], v[168:169], v[152:153], s[36:37] op_sel_hi:[1,1,0]
	v_exp_f32_e32 v160, v160
	v_exp_f32_e32 v161, v161
	v_pk_fma_f32 v[152:153], v[168:169], v[152:153], s[50:51] op_sel_hi:[1,1,0]
	s_nop 0
	v_pk_fma_f32 v[152:153], v[168:169], v[152:153], s[72:73] op_sel_hi:[1,1,0]
	s_nop 0
	v_pk_mul_f32 v[152:153], v[168:169], v[152:153]
	s_nop 0
	v_pk_mul_f32 v[152:153], v[160:161], v[152:153]
	s_nop 0
	v_max_f32_e32 v240, 0, v102
	v_max_f32_e32 v241, 0, v103
	v_fma_f32 v160, -|v102|, v152, v240
	v_fma_f32 v161, -|v103|, v153, v241
	s_nop 0
	s_nop 1

; __device__ __forceinline__ f32x4 gelu4(f32x4 v) { f32x2 a = gelu_pk((f32x2){v[0], v[1]}), b = gelu_pk((f32x2){v[2], v[3]}); return (f32x4){a.x, a.y, b.x, b.y}; }
; __device__ __forceinline__ f32x2 gelu_pk(f32x2 v) {
;     const f32x2 av = __builtin_elementwise_abs(v), d = av * 0.2316418882f + 1.0f;
;     f32x2 t; t.x = __builtin_amdgcn_rcpf(d.x); t.y = __builtin_amdgcn_rcpf(d.y);
;     f32x2 q = t * 0.5307027145f + (-0.7265760135f); q = q * t + 0.7107068705f; q = q * t + (-0.142248368f); q = q * t + 0.127414796f; q = q * t;
;     const f32x2 s = (v * v) * (-0.72134752044f);
;     f32x2 e; e.x = __builtin_amdgcn_exp2f(s.x); e.y = __builtin_amdgcn_exp2f(s.y);
;     const f32x2 m = v * (q * e), r = v - m;
;     f32x2 o; o.x = v.x < 0.f ? m.x : r.x; o.y = v.y < 0.f ? m.y : r.y; return o;
;     __device__ __forceinline__ void operator()(const f32x4 (&acc)[2][2][4][2], const pg8::Unit& u, int wr, int wc, int fr, int fq) const {
;     ...
;                         else if (act == 1) { v0 = gelu4(v0); v1 = gelu4(v1); }
.LBB0_237:
	s_andn2_b64 vcc, exec, s[16:17]
	s_cbranch_vccnz .LBB0_239
	v_fma_f32 v154, |v104|, s28, 1.0
	v_fma_f32 v155, |v105|, s28, 1.0
	v_mov_b64_e32 v[160:161], s[34:35]
	v_rcp_f32_e32 v154, v154
	v_rcp_f32_e32 v155, v155
	v_pk_mul_f32 v[158:159], v[104:105], v[104:105]
	s_nop 0
	v_pk_mul_f32 v[158:159], v[158:159], s[74:75] op_sel_hi:[1,0]
	v_pk_fma_f32 v[156:157], v[154:155], s[30:31], v[160:161] op_sel_hi:[1,0,0]
	v_exp_f32_e32 v158, v158
	v_pk_fma_f32 v[156:157], v[154:155], v[156:157], s[36:37] op_sel_hi:[1,1,0]
	v_exp_f32_e32 v159, v159
	v_pk_fma_f32 v[156:157], v[154:155], v[156:157], s[50:51] op_sel_hi:[1,1,0]
	s_nop 0
	v_pk_fma_f32 v[156:157], v[154:155], v[156:157], s[72:73] op_sel_hi:[1,1,0]
	v_fma_f32 v168, |v106|, s28, 1.0
	v_fma_f32 v169, |v107|, s28, 1.0
	v_pk_mul_f32 v[154:155], v[154:155], v[156:157]
	v_rcp_f32_e32 v168, v168
	v_rcp_f32_e32 v169, v169
	v_pk_mul_f32 v[154:155], v[158:159], v[154:155]
	v_max_f32_e32 v240, 0, v104
	v_max_f32_e32 v241, 0, v105
	v_fma_f32 v154, -|v104|, v154, v240
	v_fma_f32 v155, -|v105|, v155, v241
	v_pk_mul_f32 v[156:157], v[106:107], v[106:107]
	s_nop 0
	v_pk_mul_f32 v[156:157], v[156:157], s[74:75] op_sel_hi:[1,0]
	v_pk_fma_f32 v[158:159], v[168:169], s[30:31], v[160:161] op_sel_hi:[1,0,0]
	v_exp_f32_e32 v156, v156
	v_pk_fma_f32 v[158:159], v[168:169], v[158:159], s[36:37] op_sel_hi:[1,1,0]
	v_exp_f32_e32 v157, v157
	v_pk_fma_f32 v[158:159], v[168:169], v[158:159], s[50:51] op_sel_hi:[1,1,0]
	s_nop 0
	v_pk_fma_f32 v[158:159], v[168:169], v[158:159], s[72:73] op_sel_hi:[1,1,0]
	s_nop 0
	v_pk_mul_f32 v[158:159], v[168:169], v[158:159]
	v_fma_f32 v168, |v96|, s28, 1.0
	v_fma_f32 v169, |v97|, s28, 1.0
	v_pk_mul_f32 v[156:157], v[156:157], v[158:159]
	v_rcp_f32_e32 v168, v168
	v_rcp_f32_e32 v169, v169
	v_max_f32_e32 v240, 0, v106
	v_max_f32_e32 v241, 0, v107
	v_fma_f32 v156, -|v106|, v156, v240
	v_fma_f32 v157, -|v107|, v157, v241
	v_fma_f32 v172, |v98|, s28, 1.0
	v_fma_f32 v173, |v99|, s28, 1.0
	s_nop 0
	v_rcp_f32_e32 v172, v172
	v_rcp_f32_e32 v173, v173
	v_pk_fma_f32 v[158:159], v[168:169], s[30:31], v[160:161] op_sel_hi:[1,0,0]
	v_pk_mul_f32 v[170:171], v[96:97], v[96:97]
	v_pk_fma_f32 v[158:159], v[168:169], v[158:159], s[36:37] op_sel_hi:[1,1,0]
	v_pk_mul_f32 v[170:171], v[170:171], s[74:75] op_sel_hi:[1,0]
	v_pk_fma_f32 v[158:159], v[168:169], v[158:159], s[50:51] op_sel_hi:[1,1,0]
	v_exp_f32_e32 v170, v170
	v_pk_fma_f32 v[158:159], v[168:169], v[158:159], s[72:73] op_sel_hi:[1,1,0]
	v_exp_f32_e32 v171, v171
	v_pk_mul_f32 v[158:159], v[168:169], v[158:159]
	v_pk_mul_f32 v[168:169], v[98:99], v[98:99]
	v_pk_fma_f32 v[160:161], v[172:173], s[30:31], v[160:161] op_sel_hi:[1,0,0]
	v_pk_mul_f32 v[168:169], v[168:169], s[74:75] op_sel_hi:[1,0]
	v_pk_fma_f32 v[160:161], v[172:173], v[160:161], s[36:37] op_sel_hi:[1,1,0]
	v_exp_f32_e32 v168, v168
	v_exp_f32_e32 v169, v169
	v_pk_fma_f32 v[160:161], v[172:173], v[160:161], s[50:51] op_sel_hi:[1,1,0]
	v_pk_mul_f32 v[158:159], v[170:171], v[158:159]
	v_pk_fma_f32 v[160:161], v[172:173], v[160:161], s[72:73] op_sel_hi:[1,1,0]
	v_max_f32_e32 v240, 0, v96
	v_max_f32_e32 v241, 0, v97
	v_fma_f32 v158, -|v96|, v158, v240
	v_fma_f32 v159, -|v97|, v159, v241
	v_pk_mul_f32 v[160:161], v[172:173], v[160:161]
	s_nop 0
	v_pk_mul_f32 v[160:161], v[168:169], v[160:161]
	s_nop 0
	v_max_f32_e32 v240, 0, v98
	v_max_f32_e32 v241, 0, v99
	v_fma_f32 v160, -|v98|, v160, v240
	v_fma_f32 v161, -|v99|, v161, v241
	s_nop 1
	s_nop 1

; __device__ __forceinline__ f32x4 gelu4(f32x4 v) { f32x2 a = gelu_pk((f32x2){v[0], v[1]}), b = gelu_pk((f32x2){v[2], v[3]}); return (f32x4){a.x, a.y, b.x, b.y}; }
; __device__ __forceinline__ f32x2 gelu_pk(f32x2 v) {
;     const f32x2 av = __builtin_elementwise_abs(v), d = av * 0.2316418882f + 1.0f;
;     f32x2 t; t.x = __builtin_amdgcn_rcpf(d.x); t.y = __builtin_amdgcn_rcpf(d.y);
;     f32x2 q = t * 0.5307027145f + (-0.7265760135f); q = q * t + 0.7107068705f; q = q * t + (-0.142248368f); q = q * t + 0.127414796f; q = q * t;
;     const f32x2 s = (v * v) * (-0.72134752044f);
;     f32x2 e; e.x = __builtin_amdgcn_exp2f(s.x); e.y = __builtin_amdgcn_exp2f(s.y);
;     const f32x2 m = v * (q * e), r = v - m;
;     f32x2 o; o.x = v.x < 0.f ? m.x : r.x; o.y = v.y < 0.f ? m.y : r.y; return o;
;     __device__ __forceinline__ void operator()(const f32x4 (&acc)[2][2][4][2], const pg8::Unit& u, int wr, int wc, int fr, int fq) const {
;     ...
;                         else if (act == 1) { v0 = gelu4(v0); v1 = gelu4(v1); }
.LBB0_251:
	s_andn2_b64 vcc, exec, s[16:17]
	s_cbranch_vccnz .LBB0_253
	v_fma_f32 v152, |v92|, s28, 1.0
	v_fma_f32 v153, |v93|, s28, 1.0
	v_mov_b64_e32 v[160:161], s[34:35]
	v_rcp_f32_e32 v152, v152
	v_rcp_f32_e32 v153, v153
	v_pk_mul_f32 v[156:157], v[92:93], v[92:93]
	s_nop 0
	v_pk_mul_f32 v[156:157], v[156:157], s[74:75] op_sel_hi:[1,0]
	v_pk_fma_f32 v[154:155], v[152:153], s[30:31], v[160:161] op_sel_hi:[1,0,0]
	v_exp_f32_e32 v156, v156
	v_pk_fma_f32 v[154:155], v[152:153], v[154:155], s[36:37] op_sel_hi:[1,1,0]
	v_exp_f32_e32 v157, v157
	v_pk_fma_f32 v[154:155], v[152:153], v[154:155], s[50:51] op_sel_hi:[1,1,0]
	v_pk_mul_f32 v[158:159], v[94:95], v[94:95]
	v_pk_fma_f32 v[154:155], v[152:153], v[154:155], s[72:73] op_sel_hi:[1,1,0]
	v_pk_mul_f32 v[158:159], v[158:159], s[74:75] op_sel_hi:[1,0]
	v_pk_mul_f32 v[152:153], v[152:153], v[154:155]
	v_exp_f32_e32 v158, v158
	v_pk_mul_f32 v[152:153], v[156:157], v[152:153]
	v_fma_f32 v156, |v94|, s28, 1.0
	v_fma_f32 v157, |v95|, s28, 1.0
	s_nop 0
	v_rcp_f32_e32 v156, v156
	v_rcp_f32_e32 v157, v157
	v_max_f32_e32 v240, 0, v92
	v_max_f32_e32 v241, 0, v93
	v_fma_f32 v154, -|v92|, v152, v240
	v_fma_f32 v155, -|v93|, v153, v241
	v_exp_f32_e32 v159, v159
	v_pk_mul_f32 v[168:169], v[84:85], v[84:85]
	v_pk_mul_f32 v[170:171], v[86:87], v[86:87]
	v_pk_fma_f32 v[152:153], v[156:157], s[30:31], v[160:161] op_sel_hi:[1,0,0]
	s_nop 0
	v_pk_fma_f32 v[152:153], v[156:157], v[152:153], s[36:37] op_sel_hi:[1,1,0]
	v_pk_mul_f32 v[168:169], v[168:169], s[74:75] op_sel_hi:[1,0]
	v_pk_fma_f32 v[152:153], v[156:157], v[152:153], s[50:51] op_sel_hi:[1,1,0]
	v_exp_f32_e32 v168, v168
	v_pk_fma_f32 v[152:153], v[156:157], v[152:153], s[72:73] op_sel_hi:[1,1,0]
	v_exp_f32_e32 v169, v169
	v_pk_mul_f32 v[152:153], v[156:157], v[152:153]
	s_nop 0
	v_pk_mul_f32 v[152:153], v[158:159], v[152:153]
	v_fma_f32 v158, |v84|, s28, 1.0
	v_fma_f32 v159, |v85|, s28, 1.0
	s_nop 0
	v_rcp_f32_e32 v158, v158
	v_rcp_f32_e32 v159, v159
	v_max_f32_e32 v240, 0, v94
	v_max_f32_e32 v241, 0, v95
	v_fma_f32 v156, -|v94|, v152, v240
	v_fma_f32 v157, -|v95|, v153, v241
	s_nop 0
	s_nop 1
	v_pk_fma_f32 v[152:153], v[158:159], s[30:31], v[160:161] op_sel_hi:[1,0,0]
	s_nop 0
	v_pk_fma_f32 v[152:153], v[158:159], v[152:153], s[36:37] op_sel_hi:[1,1,0]
	s_nop 0
	v_pk_fma_f32 v[152:153], v[158:159], v[152:153], s[50:51] op_sel_hi:[1,1,0]
	s_nop 0
	v_pk_fma_f32 v[152:153], v[158:159], v[152:153], s[72:73] op_sel_hi:[1,1,0]
	s_nop 0
	v_pk_mul_f32 v[152:153], v[158:159], v[152:153]
	s_nop 0
	v_pk_mul_f32 v[152:153], v[168:169], v[152:153]
	v_fma_f32 v168, |v86|, s28, 1.0
	v_fma_f32 v169, |v87|, s28, 1.0
	s_nop 0
	v_rcp_f32_e32 v168, v168
	v_rcp_f32_e32 v169, v169
	v_max_f32_e32 v240, 0, v84
	v_max_f32_e32 v241, 0, v85
	v_fma_f32 v158, -|v84|, v152, v240
	v_fma_f32 v159, -|v85|, v153, v241
	s_nop 0
	s_nop 1
	v_pk_fma_f32 v[152:153], v[168:169], s[30:31], v[160:161] op_sel_hi:[1,0,0]
	v_pk_mul_f32 v[160:161], v[170:171], s[74:75] op_sel_hi:[1,0]
	v_pk_fma_f32 v[152:153], v[168:169], v[152:153], s[36:37] op_sel_hi:[1,1,0]
	v_exp_f32_e32 v160, v160
	v_exp_f32_e32 v161, v161
	v_pk_fma_f32 v[152:153], v[168:169], v[152:153], s[50:51] op_sel_hi:[1,1,0]
	s_nop 0
	v_pk_fma_f32 v[152:153], v[168:169], v[152:153], s[72:73] op_sel_hi:[1,1,0]
	s_nop 0
	v_pk_mul_f32 v[152:153], v[168:169], v[152:153]
	s_nop 0
	v_pk_mul_f32 v[152:153], v[160:161], v[152:153]
	s_nop 0
	v_max_f32_e32 v240, 0, v86
	v_max_f32_e32 v241, 0, v87
	v_fma_f32 v160, -|v86|, v152, v240
	v_fma_f32 v161, -|v87|, v153, v241
	s_nop 0
	s_nop 1

; __device__ __forceinline__ f32x4 gelu4(f32x4 v) { f32x2 a = gelu_pk((f32x2){v[0], v[1]}), b = gelu_pk((f32x2){v[2], v[3]}); return (f32x4){a.x, a.y, b.x, b.y}; }
; __device__ __forceinline__ f32x2 gelu_pk(f32x2 v) {
;     const f32x2 av = __builtin_elementwise_abs(v), d = av * 0.2316418882f + 1.0f;
;     f32x2 t; t.x = __builtin_amdgcn_rcpf(d.x); t.y = __builtin_amdgcn_rcpf(d.y);
;     f32x2 q = t * 0.5307027145f + (-0.7265760135f); q = q * t + 0.7107068705f; q = q * t + (-0.142248368f); q = q * t + 0.127414796f; q = q * t;
;     const f32x2 s = (v * v) * (-0.72134752044f);
;     f32x2 e; e.x = __builtin_amdgcn_exp2f(s.x); e.y = __builtin_amdgcn_exp2f(s.y);
;     const f32x2 m = v * (q * e), r = v - m;
;     f32x2 o; o.x = v.x < 0.f ? m.x : r.x; o.y = v.y < 0.f ? m.y : r.y; return o;
;     __device__ __forceinline__ void operator()(const f32x4 (&acc)[2][2][4][2], const pg8::Unit& u, int wr, int wc, int fr, int fq) const {
;     ...
;                         else if (act == 1) { v0 = gelu4(v0); v1 = gelu4(v1); }
.LBB0_265:
	s_andn2_b64 vcc, exec, s[16:17]
	s_cbranch_vccnz .LBB0_267
	v_fma_f32 v154, |v88|, s28, 1.0
	v_fma_f32 v155, |v89|, s28, 1.0
	v_mov_b64_e32 v[160:161], s[34:35]
	v_rcp_f32_e32 v154, v154
	v_rcp_f32_e32 v155, v155
	v_pk_mul_f32 v[158:159], v[88:89], v[88:89]
	s_nop 0
	v_pk_mul_f32 v[158:159], v[158:159], s[74:75] op_sel_hi:[1,0]
	v_pk_fma_f32 v[156:157], v[154:155], s[30:31], v[160:161] op_sel_hi:[1,0,0]
	v_exp_f32_e32 v158, v158
	v_pk_fma_f32 v[156:157], v[154:155], v[156:157], s[36:37] op_sel_hi:[1,1,0]
	v_exp_f32_e32 v159, v159
	v_pk_fma_f32 v[156:157], v[154:155], v[156:157], s[50:51] op_sel_hi:[1,1,0]
	s_nop 0
	v_pk_fma_f32 v[156:157], v[154:155], v[156:157], s[72:73] op_sel_hi:[1,1,0]
	v_fma_f32 v168, |v90|, s28, 1.0
	v_fma_f32 v169, |v91|, s28, 1.0
	v_pk_mul_f32 v[154:155], v[154:155], v[156:157]
	v_rcp_f32_e32 v168, v168
	v_rcp_f32_e32 v169, v169
	v_pk_mul_f32 v[154:155], v[158:159], v[154:155]
	v_max_f32_e32 v240, 0, v88
	v_max_f32_e32 v241, 0, v89
	v_fma_f32 v154, -|v88|, v154, v240
	v_fma_f32 v155, -|v89|, v155, v241
	v_pk_mul_f32 v[156:157], v[90:91], v[90:91]
	s_nop 0
	v_pk_mul_f32 v[156:157], v[156:157], s[74:75] op_sel_hi:[1,0]
	v_pk_fma_f32 v[158:159], v[168:169], s[30:31], v[160:161] op_sel_hi:[1,0,0]
	v_exp_f32_e32 v156, v156
	v_pk_fma_f32 v[158:159], v[168:169], v[158:159], s[36:37] op_sel_hi:[1,1,0]
	v_exp_f32_e32 v157, v157
	v_pk_fma_f32 v[158:159], v[168:169], v[158:159], s[50:51] op_sel_hi:[1,1,0]
	s_nop 0
	v_pk_fma_f32 v[158:159], v[168:169], v[158:159], s[72:73] op_sel_hi:[1,1,0]
	s_nop 0
	v_pk_mul_f32 v[158:159], v[168:169], v[158:159]
	v_fma_f32 v168, |v80|, s28, 1.0
	v_fma_f32 v169, |v81|, s28, 1.0
	v_pk_mul_f32 v[156:157], v[156:157], v[158:159]
	v_rcp_f32_e32 v168, v168
	v_rcp_f32_e32 v169, v169
	v_max_f32_e32 v240, 0, v90
	v_max_f32_e32 v241, 0, v91
	v_fma_f32 v156, -|v90|, v156, v240
	v_fma_f32 v157, -|v91|, v157, v241
	v_fma_f32 v172, |v82|, s28, 1.0
	v_fma_f32 v173, |v83|, s28, 1.0
	s_nop 0
	v_rcp_f32_e32 v172, v172
	v_rcp_f32_e32 v173, v173
	v_pk_fma_f32 v[158:159], v[168:169], s[30:31], v[160:161] op_sel_hi:[1,0,0]
	v_pk_mul_f32 v[170:171], v[80:81], v[80:81]
	v_pk_fma_f32 v[158:159], v[168:169], v[158:159], s[36:37] op_sel_hi:[1,1,0]
	v_pk_mul_f32 v[170:171], v[170:171], s[74:75] op_sel_hi:[1,0]
	v_pk_fma_f32 v[158:159], v[168:169], v[158:159], s[50:51] op_sel_hi:[1,1,0]
	v_exp_f32_e32 v170, v170
	v_pk_fma_f32 v[158:159], v[168:169], v[158:159], s[72:73] op_sel_hi:[1,1,0]
	v_exp_f32_e32 v171, v171
	v_pk_mul_f32 v[158:159], v[168:169], v[158:159]
	v_pk_mul_f32 v[168:169], v[82:83], v[82:83]
	v_pk_fma_f32 v[160:161], v[172:173], s[30:31], v[160:161] op_sel_hi:[1,0,0]
	v_pk_mul_f32 v[168:169], v[168:169], s[74:75] op_sel_hi:[1,0]
	v_pk_fma_f32 v[160:161], v[172:173], v[160:161], s[36:37] op_sel_hi:[1,1,0]
	v_exp_f32_e32 v168, v168
	v_exp_f32_e32 v169, v169
	v_pk_fma_f32 v[160:161], v[172:173], v[160:161], s[50:51] op_sel_hi:[1,1,0]
	v_pk_mul_f32 v[158:159], v[170:171], v[158:159]
	v_pk_fma_f32 v[160:161], v[172:173], v[160:161], s[72:73] op_sel_hi:[1,1,0]
	v_max_f32_e32 v240, 0, v80
	v_max_f32_e32 v241, 0, v81
	v_fma_f32 v158, -|v80|, v158, v240
	v_fma_f32 v159, -|v81|, v159, v241
	v_pk_mul_f32 v[160:161], v[172:173], v[160:161]
	s_nop 0
	v_pk_mul_f32 v[160:161], v[168:169], v[160:161]
	s_nop 0
	v_max_f32_e32 v240, 0, v82
	v_max_f32_e32 v241, 0, v83
	v_fma_f32 v160, -|v82|, v160, v240
	v_fma_f32 v161, -|v83|, v161, v241
	s_nop 1
	s_nop 1

; __device__ __forceinline__ f32x4 gelu4(f32x4 v) { f32x2 a = gelu_pk((f32x2){v[0], v[1]}), b = gelu_pk((f32x2){v[2], v[3]}); return (f32x4){a.x, a.y, b.x, b.y}; }
; __device__ __forceinline__ f32x2 gelu_pk(f32x2 v) {
;     const f32x2 av = __builtin_elementwise_abs(v), d = av * 0.2316418882f + 1.0f;
;     f32x2 t; t.x = __builtin_amdgcn_rcpf(d.x); t.y = __builtin_amdgcn_rcpf(d.y);
;     f32x2 q = t * 0.5307027145f + (-0.7265760135f); q = q * t + 0.7107068705f; q = q * t + (-0.142248368f); q = q * t + 0.127414796f; q = q * t;
;     const f32x2 s = (v * v) * (-0.72134752044f);
;     f32x2 e; e.x = __builtin_amdgcn_exp2f(s.x); e.y = __builtin_amdgcn_exp2f(s.y);
;     const f32x2 m = v * (q * e), r = v - m;
;     f32x2 o; o.x = v.x < 0.f ? m.x : r.x; o.y = v.y < 0.f ? m.y : r.y; return o;
;     __device__ __forceinline__ void operator()(const f32x4 (&acc)[2][2][4][2], const pg8::Unit& u, int wr, int wc, int fr, int fq) const {
;     ...
;                         else if (act == 1) { v0 = gelu4(v0); v1 = gelu4(v1); }
.LBB0_279:
	s_andn2_b64 vcc, exec, s[16:17]
	s_cbranch_vccnz .LBB0_281
	v_fma_f32 v152, |v76|, s28, 1.0
	v_fma_f32 v153, |v77|, s28, 1.0
	v_mov_b64_e32 v[160:161], s[34:35]
	v_rcp_f32_e32 v152, v152
	v_rcp_f32_e32 v153, v153
	v_pk_mul_f32 v[156:157], v[76:77], v[76:77]
	s_nop 0
	v_pk_mul_f32 v[156:157], v[156:157], s[74:75] op_sel_hi:[1,0]
	v_pk_fma_f32 v[154:155], v[152:153], s[30:31], v[160:161] op_sel_hi:[1,0,0]
	v_exp_f32_e32 v156, v156
	v_pk_fma_f32 v[154:155], v[152:153], v[154:155], s[36:37] op_sel_hi:[1,1,0]
	v_exp_f32_e32 v157, v157
	v_pk_fma_f32 v[154:155], v[152:153], v[154:155], s[50:51] op_sel_hi:[1,1,0]
	v_pk_mul_f32 v[158:159], v[78:79], v[78:79]
	v_pk_fma_f32 v[154:155], v[152:153], v[154:155], s[72:73] op_sel_hi:[1,1,0]
	v_pk_mul_f32 v[158:159], v[158:159], s[74:75] op_sel_hi:[1,0]
	v_pk_mul_f32 v[152:153], v[152:153], v[154:155]
	v_exp_f32_e32 v158, v158
	v_pk_mul_f32 v[152:153], v[156:157], v[152:153]
	v_fma_f32 v156, |v78|, s28, 1.0
	v_fma_f32 v157, |v79|, s28, 1.0
	s_nop 0
	v_rcp_f32_e32 v156, v156
	v_rcp_f32_e32 v157, v157
	v_max_f32_e32 v240, 0, v76
	v_max_f32_e32 v241, 0, v77
	v_fma_f32 v154, -|v76|, v152, v240
	v_fma_f32 v155, -|v77|, v153, v241
	v_exp_f32_e32 v159, v159
	v_pk_mul_f32 v[168:169], v[68:69], v[68:69]
	v_pk_mul_f32 v[170:171], v[70:71], v[70:71]
	v_pk_fma_f32 v[152:153], v[156:157], s[30:31], v[160:161] op_sel_hi:[1,0,0]
	s_nop 0
	v_pk_fma_f32 v[152:153], v[156:157], v[152:153], s[36:37] op_sel_hi:[1,1,0]
	v_pk_mul_f32 v[168:169], v[168:169], s[74:75] op_sel_hi:[1,0]
	v_pk_fma_f32 v[152:153], v[156:157], v[152:153], s[50:51] op_sel_hi:[1,1,0]
	v_exp_f32_e32 v168, v168
	v_pk_fma_f32 v[152:153], v[156:157], v[152:153], s[72:73] op_sel_hi:[1,1,0]
	v_exp_f32_e32 v169, v169
	v_pk_mul_f32 v[152:153], v[156:157], v[152:153]
	s_nop 0
	v_pk_mul_f32 v[152:153], v[158:159], v[152:153]
	v_fma_f32 v158, |v68|, s28, 1.0
	v_fma_f32 v159, |v69|, s28, 1.0
	s_nop 0
	v_rcp_f32_e32 v158, v158
	v_rcp_f32_e32 v159, v159
	v_max_f32_e32 v240, 0, v78
	v_max_f32_e32 v241, 0, v79
	v_fma_f32 v156, -|v78|, v152, v240
	v_fma_f32 v157, -|v79|, v153, v241
	s_nop 0
	s_nop 1
	v_pk_fma_f32 v[152:153], v[158:159], s[30:31], v[160:161] op_sel_hi:[1,0,0]
	s_nop 0
	v_pk_fma_f32 v[152:153], v[158:159], v[152:153], s[36:37] op_sel_hi:[1,1,0]
	s_nop 0
	v_pk_fma_f32 v[152:153], v[158:159], v[152:153], s[50:51] op_sel_hi:[1,1,0]
	s_nop 0
	v_pk_fma_f32 v[152:153], v[158:159], v[152:153], s[72:73] op_sel_hi:[1,1,0]
	s_nop 0
	v_pk_mul_f32 v[152:153], v[158:159], v[152:153]
	s_nop 0
	v_pk_mul_f32 v[152:153], v[168:169], v[152:153]
	v_fma_f32 v168, |v70|, s28, 1.0
	v_fma_f32 v169, |v71|, s28, 1.0
	s_nop 0
	v_rcp_f32_e32 v168, v168
	v_rcp_f32_e32 v169, v169
	v_max_f32_e32 v240, 0, v68
	v_max_f32_e32 v241, 0, v69
	v_fma_f32 v158, -|v68|, v152, v240
	v_fma_f32 v159, -|v69|, v153, v241
	s_nop 0
	s_nop 1
	v_pk_fma_f32 v[152:153], v[168:169], s[30:31], v[160:161] op_sel_hi:[1,0,0]
	v_pk_mul_f32 v[160:161], v[170:171], s[74:75] op_sel_hi:[1,0]
	v_pk_fma_f32 v[152:153], v[168:169], v[152:153], s[36:37] op_sel_hi:[1,1,0]
	v_exp_f32_e32 v160, v160
	v_exp_f32_e32 v161, v161
	v_pk_fma_f32 v[152:153], v[168:169], v[152:153], s[50:51] op_sel_hi:[1,1,0]
	s_nop 0
	v_pk_fma_f32 v[152:153], v[168:169], v[152:153], s[72:73] op_sel_hi:[1,1,0]
	s_nop 0
	v_pk_mul_f32 v[152:153], v[168:169], v[152:153]
	s_nop 0
	v_pk_mul_f32 v[152:153], v[160:161], v[152:153]
	s_nop 0
	v_max_f32_e32 v240, 0, v70
	v_max_f32_e32 v241, 0, v71
	v_fma_f32 v160, -|v70|, v152, v240
	v_fma_f32 v161, -|v71|, v153, v241
	s_nop 0
	s_nop 1

; __device__ __forceinline__ f32x4 gelu4(f32x4 v) { f32x2 a = gelu_pk((f32x2){v[0], v[1]}), b = gelu_pk((f32x2){v[2], v[3]}); return (f32x4){a.x, a.y, b.x, b.y}; }
; __device__ __forceinline__ f32x4 sigm4(f32x4 v) { return (f32x4){sigmoid_f(v[0]), sigmoid_f(v[1]), sigmoid_f(v[2]), sigmoid_f(v[3])}; }
; __device__ __forceinline__ f32x2 gelu_pk(f32x2 v) {
;     const f32x2 av = __builtin_elementwise_abs(v), d = av * 0.2316418882f + 1.0f;
;     f32x2 t; t.x = __builtin_amdgcn_rcpf(d.x); t.y = __builtin_amdgcn_rcpf(d.y);
;     f32x2 q = t * 0.5307027145f + (-0.7265760135f); q = q * t + 0.7107068705f; q = q * t + (-0.142248368f); q = q * t + 0.127414796f; q = q * t;
;     const f32x2 s = (v * v) * (-0.72134752044f);
;     f32x2 e; e.x = __builtin_amdgcn_exp2f(s.x); e.y = __builtin_amdgcn_exp2f(s.y);
;     const f32x2 m = v * (q * e), r = v - m;
;     f32x2 o; o.x = v.x < 0.f ? m.x : r.x; o.y = v.y < 0.f ? m.y : r.y; return o;
; }
;     __device__ __forceinline__ void operator()(const f32x4 (&acc)[2][2][4][2], const pg8::Unit& u, int wr, int wc, int fr, int fq) const {
;     ...
;                         f32x4 v0 = acc[ai][bj][m][0], v1 = acc[ai][bj][m][1];
;                         if (act == 5) { v0 = sigm4(v0); v1 = sigm4(v1);
;                             if (bj == 0) { const f32x4 b0 = sigm4(acc[ai][1][m][0]), b1 = sigm4(acc[ai][1][m][1]);
; #pragma unroll
;                                 for (int e = 0; e < 4; ++e) { v0[e] *= __builtin_amdgcn_rcpf(fmaxf(b0[e], 1e-20f)); v1[e] *= __builtin_amdgcn_rcpf(fmaxf(b1[e], 1e-20f)); } } }
;                         else if (act == 1) { v0 = gelu4(v0); v1 = gelu4(v1); }
.LBB0_293:
	s_andn2_b64 vcc, exec, s[16:17]
	s_cbranch_vccnz .LBB0_295
	v_fma_f32 v154, |v72|, s28, 1.0
	v_fma_f32 v155, |v73|, s28, 1.0
	v_mov_b64_e32 v[160:161], s[34:35]
	v_rcp_f32_e32 v154, v154
	v_rcp_f32_e32 v155, v155
	v_pk_mul_f32 v[158:159], v[72:73], v[72:73]
	s_nop 0
	v_pk_mul_f32 v[158:159], v[158:159], s[74:75] op_sel_hi:[1,0]
	v_pk_fma_f32 v[156:157], v[154:155], s[30:31], v[160:161] op_sel_hi:[1,0,0]
	v_exp_f32_e32 v158, v158
	v_pk_fma_f32 v[156:157], v[154:155], v[156:157], s[36:37] op_sel_hi:[1,1,0]
	v_exp_f32_e32 v159, v159
	v_pk_fma_f32 v[156:157], v[154:155], v[156:157], s[50:51] op_sel_hi:[1,1,0]
	s_nop 0
	v_pk_fma_f32 v[156:157], v[154:155], v[156:157], s[72:73] op_sel_hi:[1,1,0]
	v_fma_f32 v168, |v74|, s28, 1.0
	v_fma_f32 v169, |v75|, s28, 1.0
	v_pk_mul_f32 v[154:155], v[154:155], v[156:157]
	v_rcp_f32_e32 v168, v168
	v_rcp_f32_e32 v169, v169
	v_pk_mul_f32 v[154:155], v[158:159], v[154:155]
	v_max_f32_e32 v240, 0, v72
	v_max_f32_e32 v241, 0, v73
	v_fma_f32 v154, -|v72|, v154, v240
	v_fma_f32 v155, -|v73|, v155, v241
	v_pk_mul_f32 v[156:157], v[74:75], v[74:75]
	s_nop 0
	v_pk_mul_f32 v[156:157], v[156:157], s[74:75] op_sel_hi:[1,0]
	v_pk_fma_f32 v[158:159], v[168:169], s[30:31], v[160:161] op_sel_hi:[1,0,0]
	v_exp_f32_e32 v156, v156
	v_pk_fma_f32 v[158:159], v[168:169], v[158:159], s[36:37] op_sel_hi:[1,1,0]
	v_exp_f32_e32 v157, v157
	v_pk_fma_f32 v[158:159], v[168:169], v[158:159], s[50:51] op_sel_hi:[1,1,0]
	s_nop 0
	v_pk_fma_f32 v[158:159], v[168:169], v[158:159], s[72:73] op_sel_hi:[1,1,0]
	s_nop 0
	v_pk_mul_f32 v[158:159], v[168:169], v[158:159]
	v_fma_f32 v168, |v64|, s28, 1.0
	v_fma_f32 v169, |v65|, s28, 1.0
	v_pk_mul_f32 v[156:157], v[156:157], v[158:159]
	v_rcp_f32_e32 v168, v168
	v_rcp_f32_e32 v169, v169
	v_max_f32_e32 v240, 0, v74
	v_max_f32_e32 v241, 0, v75
	v_fma_f32 v156, -|v74|, v156, v240
	v_fma_f32 v157, -|v75|, v157, v241
	v_fma_f32 v172, |v66|, s28, 1.0
	v_fma_f32 v173, |v67|, s28, 1.0
	s_nop 0
	v_rcp_f32_e32 v172, v172
	v_rcp_f32_e32 v173, v173
	v_pk_fma_f32 v[158:159], v[168:169], s[30:31], v[160:161] op_sel_hi:[1,0,0]
	v_pk_mul_f32 v[170:171], v[64:65], v[64:65]
	v_pk_fma_f32 v[158:159], v[168:169], v[158:159], s[36:37] op_sel_hi:[1,1,0]
	v_pk_mul_f32 v[170:171], v[170:171], s[74:75] op_sel_hi:[1,0]
	v_pk_fma_f32 v[158:159], v[168:169], v[158:159], s[50:51] op_sel_hi:[1,1,0]
	v_exp_f32_e32 v170, v170
	v_pk_fma_f32 v[158:159], v[168:169], v[158:159], s[72:73] op_sel_hi:[1,1,0]
	v_exp_f32_e32 v171, v171
	v_pk_mul_f32 v[158:159], v[168:169], v[158:159]
	v_pk_mul_f32 v[168:169], v[66:67], v[66:67]
	v_pk_fma_f32 v[160:161], v[172:173], s[30:31], v[160:161] op_sel_hi:[1,0,0]
	v_pk_mul_f32 v[168:169], v[168:169], s[74:75] op_sel_hi:[1,0]
	v_pk_fma_f32 v[160:161], v[172:173], v[160:161], s[36:37] op_sel_hi:[1,1,0]
	v_exp_f32_e32 v168, v168
	v_exp_f32_e32 v169, v169
	v_pk_fma_f32 v[160:161], v[172:173], v[160:161], s[50:51] op_sel_hi:[1,1,0]
	v_pk_mul_f32 v[158:159], v[170:171], v[158:159]
	v_pk_fma_f32 v[160:161], v[172:173], v[160:161], s[72:73] op_sel_hi:[1,1,0]
	v_max_f32_e32 v240, 0, v64
	v_max_f32_e32 v241, 0, v65
	v_fma_f32 v158, -|v64|, v158, v240
	v_fma_f32 v159, -|v65|, v159, v241
	v_pk_mul_f32 v[160:161], v[172:173], v[160:161]
	s_nop 0
	v_pk_mul_f32 v[160:161], v[168:169], v[160:161]
	s_nop 0
	v_max_f32_e32 v240, 0, v66
	v_max_f32_e32 v241, 0, v67
	v_fma_f32 v160, -|v66|, v160, v240
	v_fma_f32 v161, -|v67|, v161, v241
	s_nop 1
	s_nop 1

; __device__ __forceinline__ f32x4 gelu4(f32x4 v) { f32x2 a = gelu_pk((f32x2){v[0], v[1]}), b = gelu_pk((f32x2){v[2], v[3]}); return (f32x4){a.x, a.y, b.x, b.y}; }
; __device__ __forceinline__ f32x4 sigm4(f32x4 v) { return (f32x4){sigmoid_f(v[0]), sigmoid_f(v[1]), sigmoid_f(v[2]), sigmoid_f(v[3])}; }
; __device__ __forceinline__ f32x2 gelu_pk(f32x2 v) {
;     const f32x2 av = __builtin_elementwise_abs(v), d = av * 0.2316418882f + 1.0f;
;     f32x2 t; t.x = __builtin_amdgcn_rcpf(d.x); t.y = __builtin_amdgcn_rcpf(d.y);
;     f32x2 q = t * 0.5307027145f + (-0.7265760135f); q = q * t + 0.7107068705f; q = q * t + (-0.142248368f); q = q * t + 0.127414796f; q = q * t;
;     const f32x2 s = (v * v) * (-0.72134752044f);
;     f32x2 e; e.x = __builtin_amdgcn_exp2f(s.x); e.y = __builtin_amdgcn_exp2f(s.y);
;     const f32x2 m = v * (q * e), r = v - m;
;     f32x2 o; o.x = v.x < 0.f ? m.x : r.x; o.y = v.y < 0.f ? m.y : r.y; return o;
; }
;     __device__ __forceinline__ void operator()(const f32x4 (&acc)[2][2][4][2], const pg8::Unit& u, int wr, int wc, int fr, int fq) const {
;     ...
;                         f32x4 v0 = acc[ai][bj][m][0], v1 = acc[ai][bj][m][1];
;                         if (act == 5) { v0 = sigm4(v0); v1 = sigm4(v1);
;                             if (bj == 0) { const f32x4 b0 = sigm4(acc[ai][1][m][0]), b1 = sigm4(acc[ai][1][m][1]);
; #pragma unroll
;                                 for (int e = 0; e < 4; ++e) { v0[e] *= __builtin_amdgcn_rcpf(fmaxf(b0[e], 1e-20f)); v1[e] *= __builtin_amdgcn_rcpf(fmaxf(b1[e], 1e-20f)); } } }
;                         else if (act == 1) { v0 = gelu4(v0); v1 = gelu4(v1); }
.LBB0_307:
	s_andn2_b64 vcc, exec, s[16:17]
	s_cbranch_vccnz .LBB0_309
	v_fma_f32 v152, |v60|, s28, 1.0
	v_fma_f32 v153, |v61|, s28, 1.0
	v_mov_b64_e32 v[160:161], s[34:35]
	v_rcp_f32_e32 v152, v152
	v_rcp_f32_e32 v153, v153
	v_pk_mul_f32 v[156:157], v[60:61], v[60:61]
	s_nop 0
	v_pk_mul_f32 v[156:157], v[156:157], s[74:75] op_sel_hi:[1,0]
	v_pk_fma_f32 v[154:155], v[152:153], s[30:31], v[160:161] op_sel_hi:[1,0,0]
	v_exp_f32_e32 v156, v156
	v_pk_fma_f32 v[154:155], v[152:153], v[154:155], s[36:37] op_sel_hi:[1,1,0]
	v_exp_f32_e32 v157, v157
	v_pk_fma_f32 v[154:155], v[152:153], v[154:155], s[50:51] op_sel_hi:[1,1,0]
	v_pk_mul_f32 v[158:159], v[62:63], v[62:63]
	v_pk_fma_f32 v[154:155], v[152:153], v[154:155], s[72:73] op_sel_hi:[1,1,0]
	v_pk_mul_f32 v[158:159], v[158:159], s[74:75] op_sel_hi:[1,0]
	v_pk_mul_f32 v[152:153], v[152:153], v[154:155]
	v_exp_f32_e32 v158, v158
	v_pk_mul_f32 v[152:153], v[156:157], v[152:153]
	v_fma_f32 v156, |v62|, s28, 1.0
	v_fma_f32 v157, |v63|, s28, 1.0
	s_nop 0
	v_rcp_f32_e32 v156, v156
	v_rcp_f32_e32 v157, v157
	v_max_f32_e32 v240, 0, v60
	v_max_f32_e32 v241, 0, v61
	v_fma_f32 v154, -|v60|, v152, v240
	v_fma_f32 v155, -|v61|, v153, v241
	v_exp_f32_e32 v159, v159
	v_pk_mul_f32 v[168:169], v[52:53], v[52:53]
	v_pk_mul_f32 v[170:171], v[54:55], v[54:55]
	v_pk_fma_f32 v[152:153], v[156:157], s[30:31], v[160:161] op_sel_hi:[1,0,0]
	s_nop 0
	v_pk_fma_f32 v[152:153], v[156:157], v[152:153], s[36:37] op_sel_hi:[1,1,0]
	v_pk_mul_f32 v[168:169], v[168:169], s[74:75] op_sel_hi:[1,0]
	v_pk_fma_f32 v[152:153], v[156:157], v[152:153], s[50:51] op_sel_hi:[1,1,0]
	v_exp_f32_e32 v168, v168
	v_pk_fma_f32 v[152:153], v[156:157], v[152:153], s[72:73] op_sel_hi:[1,1,0]
	v_exp_f32_e32 v169, v169
	v_pk_mul_f32 v[152:153], v[156:157], v[152:153]
	s_nop 0
	v_pk_mul_f32 v[152:153], v[158:159], v[152:153]
	v_fma_f32 v158, |v52|, s28, 1.0
	v_fma_f32 v159, |v53|, s28, 1.0
	s_nop 0
	v_rcp_f32_e32 v158, v158
	v_rcp_f32_e32 v159, v159
	v_max_f32_e32 v240, 0, v62
	v_max_f32_e32 v241, 0, v63
	v_fma_f32 v156, -|v62|, v152, v240
	v_fma_f32 v157, -|v63|, v153, v241
	s_nop 0
	s_nop 1
	v_pk_fma_f32 v[152:153], v[158:159], s[30:31], v[160:161] op_sel_hi:[1,0,0]
	s_nop 0
	v_pk_fma_f32 v[152:153], v[158:159], v[152:153], s[36:37] op_sel_hi:[1,1,0]
	s_nop 0
	v_pk_fma_f32 v[152:153], v[158:159], v[152:153], s[50:51] op_sel_hi:[1,1,0]
	s_nop 0
	v_pk_fma_f32 v[152:153], v[158:159], v[152:153], s[72:73] op_sel_hi:[1,1,0]
	s_nop 0
	v_pk_mul_f32 v[152:153], v[158:159], v[152:153]
	s_nop 0
	v_pk_mul_f32 v[152:153], v[168:169], v[152:153]
	v_fma_f32 v168, |v54|, s28, 1.0
	v_fma_f32 v169, |v55|, s28, 1.0
	s_nop 0
	v_rcp_f32_e32 v168, v168
	v_rcp_f32_e32 v169, v169
	v_max_f32_e32 v240, 0, v52
	v_max_f32_e32 v241, 0, v53
	v_fma_f32 v158, -|v52|, v152, v240
	v_fma_f32 v159, -|v53|, v153, v241
	s_nop 0
	s_nop 1
	v_pk_fma_f32 v[152:153], v[168:169], s[30:31], v[160:161] op_sel_hi:[1,0,0]
	v_pk_mul_f32 v[160:161], v[170:171], s[74:75] op_sel_hi:[1,0]
	v_pk_fma_f32 v[152:153], v[168:169], v[152:153], s[36:37] op_sel_hi:[1,1,0]
	v_exp_f32_e32 v160, v160
	v_exp_f32_e32 v161, v161
	v_pk_fma_f32 v[152:153], v[168:169], v[152:153], s[50:51] op_sel_hi:[1,1,0]
	s_nop 0
	v_pk_fma_f32 v[152:153], v[168:169], v[152:153], s[72:73] op_sel_hi:[1,1,0]
	s_nop 0
	v_pk_mul_f32 v[152:153], v[168:169], v[152:153]
	s_nop 0
	v_pk_mul_f32 v[152:153], v[160:161], v[152:153]
	s_nop 0
	v_max_f32_e32 v240, 0, v54
	v_max_f32_e32 v241, 0, v55
	v_fma_f32 v160, -|v54|, v152, v240
	v_fma_f32 v161, -|v55|, v153, v241
	s_nop 0
	s_nop 1

; __device__ __forceinline__ f32x4 gelu4(f32x4 v) { f32x2 a = gelu_pk((f32x2){v[0], v[1]}), b = gelu_pk((f32x2){v[2], v[3]}); return (f32x4){a.x, a.y, b.x, b.y}; }
; __device__ __forceinline__ f32x4 sigm4(f32x4 v) { return (f32x4){sigmoid_f(v[0]), sigmoid_f(v[1]), sigmoid_f(v[2]), sigmoid_f(v[3])}; }
; __device__ __forceinline__ f32x2 gelu_pk(f32x2 v) {
;     const f32x2 av = __builtin_elementwise_abs(v), d = av * 0.2316418882f + 1.0f;
;     f32x2 t; t.x = __builtin_amdgcn_rcpf(d.x); t.y = __builtin_amdgcn_rcpf(d.y);
;     f32x2 q = t * 0.5307027145f + (-0.7265760135f); q = q * t + 0.7107068705f; q = q * t + (-0.142248368f); q = q * t + 0.127414796f; q = q * t;
;     const f32x2 s = (v * v) * (-0.72134752044f);
;     f32x2 e; e.x = __builtin_amdgcn_exp2f(s.x); e.y = __builtin_amdgcn_exp2f(s.y);
;     const f32x2 m = v * (q * e), r = v - m;
;     f32x2 o; o.x = v.x < 0.f ? m.x : r.x; o.y = v.y < 0.f ? m.y : r.y; return o;
; }
;     __device__ __forceinline__ void operator()(const f32x4 (&acc)[2][2][4][2], const pg8::Unit& u, int wr, int wc, int fr, int fq) const {
;     ...
;                         f32x4 v0 = acc[ai][bj][m][0], v1 = acc[ai][bj][m][1];
;                         if (act == 5) { v0 = sigm4(v0); v1 = sigm4(v1);
;                             if (bj == 0) { const f32x4 b0 = sigm4(acc[ai][1][m][0]), b1 = sigm4(acc[ai][1][m][1]);
; #pragma unroll
;                                 for (int e = 0; e < 4; ++e) { v0[e] *= __builtin_amdgcn_rcpf(fmaxf(b0[e], 1e-20f)); v1[e] *= __builtin_amdgcn_rcpf(fmaxf(b1[e], 1e-20f)); } } }
;                         else if (act == 1) { v0 = gelu4(v0); v1 = gelu4(v1); }
.LBB0_321:
	s_andn2_b64 vcc, exec, s[16:17]
	s_cbranch_vccnz .LBB0_323
	v_fma_f32 v154, |v56|, s28, 1.0
	v_fma_f32 v155, |v57|, s28, 1.0
	v_mov_b64_e32 v[160:161], s[34:35]
	v_rcp_f32_e32 v154, v154
	v_rcp_f32_e32 v155, v155
	v_pk_mul_f32 v[158:159], v[56:57], v[56:57]
	s_nop 0
	v_pk_mul_f32 v[158:159], v[158:159], s[74:75] op_sel_hi:[1,0]
	v_pk_fma_f32 v[156:157], v[154:155], s[30:31], v[160:161] op_sel_hi:[1,0,0]
	v_exp_f32_e32 v158, v158
	v_pk_fma_f32 v[156:157], v[154:155], v[156:157], s[36:37] op_sel_hi:[1,1,0]
	v_exp_f32_e32 v159, v159
	v_pk_fma_f32 v[156:157], v[154:155], v[156:157], s[50:51] op_sel_hi:[1,1,0]
	s_nop 0
	v_pk_fma_f32 v[156:157], v[154:155], v[156:157], s[72:73] op_sel_hi:[1,1,0]
	v_fma_f32 v168, |v58|, s28, 1.0
	v_fma_f32 v169, |v59|, s28, 1.0
	v_pk_mul_f32 v[154:155], v[154:155], v[156:157]
	v_rcp_f32_e32 v168, v168
	v_rcp_f32_e32 v169, v169
	v_pk_mul_f32 v[154:155], v[158:159], v[154:155]
	v_max_f32_e32 v240, 0, v56
	v_max_f32_e32 v241, 0, v57
	v_fma_f32 v154, -|v56|, v154, v240
	v_fma_f32 v155, -|v57|, v155, v241
	v_pk_mul_f32 v[156:157], v[58:59], v[58:59]
	s_nop 0
	v_pk_mul_f32 v[156:157], v[156:157], s[74:75] op_sel_hi:[1,0]
	v_pk_fma_f32 v[158:159], v[168:169], s[30:31], v[160:161] op_sel_hi:[1,0,0]
	v_exp_f32_e32 v156, v156
	v_pk_fma_f32 v[158:159], v[168:169], v[158:159], s[36:37] op_sel_hi:[1,1,0]
	v_exp_f32_e32 v157, v157
	v_pk_fma_f32 v[158:159], v[168:169], v[158:159], s[50:51] op_sel_hi:[1,1,0]
	s_nop 0
	v_pk_fma_f32 v[158:159], v[168:169], v[158:159], s[72:73] op_sel_hi:[1,1,0]
	s_nop 0
	v_pk_mul_f32 v[158:159], v[168:169], v[158:159]
	v_fma_f32 v168, |v48|, s28, 1.0
	v_fma_f32 v169, |v49|, s28, 1.0
	v_pk_mul_f32 v[156:157], v[156:157], v[158:159]
	v_rcp_f32_e32 v168, v168
	v_rcp_f32_e32 v169, v169
	v_max_f32_e32 v240, 0, v58
	v_max_f32_e32 v241, 0, v59
	v_fma_f32 v156, -|v58|, v156, v240
	v_fma_f32 v157, -|v59|, v157, v241
	v_fma_f32 v172, |v50|, s28, 1.0
	v_fma_f32 v173, |v51|, s28, 1.0
	s_nop 0
	v_rcp_f32_e32 v172, v172
	v_rcp_f32_e32 v173, v173
	v_pk_fma_f32 v[158:159], v[168:169], s[30:31], v[160:161] op_sel_hi:[1,0,0]
	v_pk_mul_f32 v[170:171], v[48:49], v[48:49]
	v_pk_fma_f32 v[158:159], v[168:169], v[158:159], s[36:37] op_sel_hi:[1,1,0]
	v_pk_mul_f32 v[170:171], v[170:171], s[74:75] op_sel_hi:[1,0]
	v_pk_fma_f32 v[158:159], v[168:169], v[158:159], s[50:51] op_sel_hi:[1,1,0]
	v_exp_f32_e32 v170, v170
	v_pk_fma_f32 v[158:159], v[168:169], v[158:159], s[72:73] op_sel_hi:[1,1,0]
	v_exp_f32_e32 v171, v171
	v_pk_mul_f32 v[158:159], v[168:169], v[158:159]
	v_pk_mul_f32 v[168:169], v[50:51], v[50:51]
	v_pk_fma_f32 v[160:161], v[172:173], s[30:31], v[160:161] op_sel_hi:[1,0,0]
	v_pk_mul_f32 v[168:169], v[168:169], s[74:75] op_sel_hi:[1,0]
	v_pk_fma_f32 v[160:161], v[172:173], v[160:161], s[36:37] op_sel_hi:[1,1,0]
	v_exp_f32_e32 v168, v168
	v_exp_f32_e32 v169, v169
	v_pk_fma_f32 v[160:161], v[172:173], v[160:161], s[50:51] op_sel_hi:[1,1,0]
	v_pk_mul_f32 v[158:159], v[170:171], v[158:159]
	v_pk_fma_f32 v[160:161], v[172:173], v[160:161], s[72:73] op_sel_hi:[1,1,0]
	v_max_f32_e32 v240, 0, v48
	v_max_f32_e32 v241, 0, v49
	v_fma_f32 v158, -|v48|, v158, v240
	v_fma_f32 v159, -|v49|, v159, v241
	v_pk_mul_f32 v[160:161], v[172:173], v[160:161]
	s_nop 0
	v_pk_mul_f32 v[160:161], v[168:169], v[160:161]
	s_nop 0
	v_max_f32_e32 v240, 0, v50
	v_max_f32_e32 v241, 0, v51
	v_fma_f32 v160, -|v50|, v160, v240
	v_fma_f32 v161, -|v51|, v161, v241
	s_nop 1
	s_nop 1

; __device__ __forceinline__ f32x4 gelu4(f32x4 v) { f32x2 a = gelu_pk((f32x2){v[0], v[1]}), b = gelu_pk((f32x2){v[2], v[3]}); return (f32x4){a.x, a.y, b.x, b.y}; }
; __device__ __forceinline__ f32x4 sigm4(f32x4 v) { return (f32x4){sigmoid_f(v[0]), sigmoid_f(v[1]), sigmoid_f(v[2]), sigmoid_f(v[3])}; }
; __device__ __forceinline__ f32x2 gelu_pk(f32x2 v) {
;     const f32x2 av = __builtin_elementwise_abs(v), d = av * 0.2316418882f + 1.0f;
;     f32x2 t; t.x = __builtin_amdgcn_rcpf(d.x); t.y = __builtin_amdgcn_rcpf(d.y);
;     f32x2 q = t * 0.5307027145f + (-0.7265760135f); q = q * t + 0.7107068705f; q = q * t + (-0.142248368f); q = q * t + 0.127414796f; q = q * t;
;     const f32x2 s = (v * v) * (-0.72134752044f);
;     f32x2 e; e.x = __builtin_amdgcn_exp2f(s.x); e.y = __builtin_amdgcn_exp2f(s.y);
;     const f32x2 m = v * (q * e), r = v - m;
;     f32x2 o; o.x = v.x < 0.f ? m.x : r.x; o.y = v.y < 0.f ? m.y : r.y; return o;
; }
;     __device__ __forceinline__ void operator()(const f32x4 (&acc)[2][2][4][2], const pg8::Unit& u, int wr, int wc, int fr, int fq) const {
;     ...
;                         f32x4 v0 = acc[ai][bj][m][0], v1 = acc[ai][bj][m][1];
;                         if (act == 5) { v0 = sigm4(v0); v1 = sigm4(v1);
;                             if (bj == 0) { const f32x4 b0 = sigm4(acc[ai][1][m][0]), b1 = sigm4(acc[ai][1][m][1]);
; #pragma unroll
;                                 for (int e = 0; e < 4; ++e) { v0[e] *= __builtin_amdgcn_rcpf(fmaxf(b0[e], 1e-20f)); v1[e] *= __builtin_amdgcn_rcpf(fmaxf(b1[e], 1e-20f)); } } }
;                         else if (act == 1) { v0 = gelu4(v0); v1 = gelu4(v1); }
.LBB0_335:
	s_andn2_b64 vcc, exec, s[16:17]
	s_cbranch_vccnz .LBB0_337
	v_fma_f32 v152, |v44|, s28, 1.0
	v_fma_f32 v153, |v45|, s28, 1.0
	v_mov_b64_e32 v[160:161], s[34:35]
	v_rcp_f32_e32 v152, v152
	v_rcp_f32_e32 v153, v153
	v_pk_mul_f32 v[156:157], v[44:45], v[44:45]
	s_nop 0
	v_pk_mul_f32 v[156:157], v[156:157], s[74:75] op_sel_hi:[1,0]
	v_pk_fma_f32 v[154:155], v[152:153], s[30:31], v[160:161] op_sel_hi:[1,0,0]
	v_exp_f32_e32 v156, v156
	v_pk_fma_f32 v[154:155], v[152:153], v[154:155], s[36:37] op_sel_hi:[1,1,0]
	v_exp_f32_e32 v157, v157
	v_pk_fma_f32 v[154:155], v[152:153], v[154:155], s[50:51] op_sel_hi:[1,1,0]
	v_pk_mul_f32 v[158:159], v[46:47], v[46:47]
	v_pk_fma_f32 v[154:155], v[152:153], v[154:155], s[72:73] op_sel_hi:[1,1,0]
	v_pk_mul_f32 v[158:159], v[158:159], s[74:75] op_sel_hi:[1,0]
	v_pk_mul_f32 v[152:153], v[152:153], v[154:155]
	v_exp_f32_e32 v158, v158
	v_pk_mul_f32 v[152:153], v[156:157], v[152:153]
	v_fma_f32 v156, |v46|, s28, 1.0
	v_fma_f32 v157, |v47|, s28, 1.0
	s_nop 0
	v_rcp_f32_e32 v156, v156
	v_rcp_f32_e32 v157, v157
	v_max_f32_e32 v240, 0, v44
	v_max_f32_e32 v241, 0, v45
	v_fma_f32 v154, -|v44|, v152, v240
	v_fma_f32 v155, -|v45|, v153, v241
	v_exp_f32_e32 v159, v159
	v_pk_mul_f32 v[168:169], v[36:37], v[36:37]
	v_pk_mul_f32 v[170:171], v[38:39], v[38:39]
	v_pk_fma_f32 v[152:153], v[156:157], s[30:31], v[160:161] op_sel_hi:[1,0,0]
	s_nop 0
	v_pk_fma_f32 v[152:153], v[156:157], v[152:153], s[36:37] op_sel_hi:[1,1,0]
	v_pk_mul_f32 v[168:169], v[168:169], s[74:75] op_sel_hi:[1,0]
	v_pk_fma_f32 v[152:153], v[156:157], v[152:153], s[50:51] op_sel_hi:[1,1,0]
	v_exp_f32_e32 v168, v168
	v_pk_fma_f32 v[152:153], v[156:157], v[152:153], s[72:73] op_sel_hi:[1,1,0]
	v_exp_f32_e32 v169, v169
	v_pk_mul_f32 v[152:153], v[156:157], v[152:153]
	s_nop 0
	v_pk_mul_f32 v[152:153], v[158:159], v[152:153]
	v_fma_f32 v158, |v36|, s28, 1.0
	v_fma_f32 v159, |v37|, s28, 1.0
	s_nop 0
	v_rcp_f32_e32 v158, v158
	v_rcp_f32_e32 v159, v159
	v_max_f32_e32 v240, 0, v46
	v_max_f32_e32 v241, 0, v47
	v_fma_f32 v156, -|v46|, v152, v240
	v_fma_f32 v157, -|v47|, v153, v241
	s_nop 0
	s_nop 1
	v_pk_fma_f32 v[152:153], v[158:159], s[30:31], v[160:161] op_sel_hi:[1,0,0]
	s_nop 0
	v_pk_fma_f32 v[152:153], v[158:159], v[152:153], s[36:37] op_sel_hi:[1,1,0]
	s_nop 0
	v_pk_fma_f32 v[152:153], v[158:159], v[152:153], s[50:51] op_sel_hi:[1,1,0]
	s_nop 0
	v_pk_fma_f32 v[152:153], v[158:159], v[152:153], s[72:73] op_sel_hi:[1,1,0]
	s_nop 0
	v_pk_mul_f32 v[152:153], v[158:159], v[152:153]
	s_nop 0
	v_pk_mul_f32 v[152:153], v[168:169], v[152:153]
	v_fma_f32 v168, |v38|, s28, 1.0
	v_fma_f32 v169, |v39|, s28, 1.0
	s_nop 0
	v_rcp_f32_e32 v168, v168
	v_rcp_f32_e32 v169, v169
	v_max_f32_e32 v240, 0, v36
	v_max_f32_e32 v241, 0, v37
	v_fma_f32 v158, -|v36|, v152, v240
	v_fma_f32 v159, -|v37|, v153, v241
	s_nop 0
	s_nop 1
	v_pk_fma_f32 v[152:153], v[168:169], s[30:31], v[160:161] op_sel_hi:[1,0,0]
	v_pk_mul_f32 v[160:161], v[170:171], s[74:75] op_sel_hi:[1,0]
	v_pk_fma_f32 v[152:153], v[168:169], v[152:153], s[36:37] op_sel_hi:[1,1,0]
	v_exp_f32_e32 v160, v160
	v_exp_f32_e32 v161, v161
	v_pk_fma_f32 v[152:153], v[168:169], v[152:153], s[50:51] op_sel_hi:[1,1,0]
	s_nop 0
	v_pk_fma_f32 v[152:153], v[168:169], v[152:153], s[72:73] op_sel_hi:[1,1,0]
	s_nop 0
	v_pk_mul_f32 v[152:153], v[168:169], v[152:153]
	s_nop 0
	v_pk_mul_f32 v[152:153], v[160:161], v[152:153]
	s_nop 0
	v_max_f32_e32 v240, 0, v38
	v_max_f32_e32 v241, 0, v39
	v_fma_f32 v160, -|v38|, v152, v240
	v_fma_f32 v161, -|v39|, v153, v241
	s_nop 0
	s_nop 1

; __device__ __forceinline__ f32x4 gelu4(f32x4 v) { f32x2 a = gelu_pk((f32x2){v[0], v[1]}), b = gelu_pk((f32x2){v[2], v[3]}); return (f32x4){a.x, a.y, b.x, b.y}; }
; __device__ __forceinline__ f32x4 sigm4(f32x4 v) { return (f32x4){sigmoid_f(v[0]), sigmoid_f(v[1]), sigmoid_f(v[2]), sigmoid_f(v[3])}; }
; __device__ __forceinline__ f32x2 gelu_pk(f32x2 v) {
;     const f32x2 av = __builtin_elementwise_abs(v), d = av * 0.2316418882f + 1.0f;
;     f32x2 t; t.x = __builtin_amdgcn_rcpf(d.x); t.y = __builtin_amdgcn_rcpf(d.y);
;     f32x2 q = t * 0.5307027145f + (-0.7265760135f); q = q * t + 0.7107068705f; q = q * t + (-0.142248368f); q = q * t + 0.127414796f; q = q * t;
;     const f32x2 s = (v * v) * (-0.72134752044f);
;     f32x2 e; e.x = __builtin_amdgcn_exp2f(s.x); e.y = __builtin_amdgcn_exp2f(s.y);
;     const f32x2 m = v * (q * e), r = v - m;
;     f32x2 o; o.x = v.x < 0.f ? m.x : r.x; o.y = v.y < 0.f ? m.y : r.y; return o;
; }
;     __device__ __forceinline__ void operator()(const f32x4 (&acc)[2][2][4][2], const pg8::Unit& u, int wr, int wc, int fr, int fq) const {
;     ...
;                         f32x4 v0 = acc[ai][bj][m][0], v1 = acc[ai][bj][m][1];
;                         if (act == 5) { v0 = sigm4(v0); v1 = sigm4(v1);
;                             if (bj == 0) { const f32x4 b0 = sigm4(acc[ai][1][m][0]), b1 = sigm4(acc[ai][1][m][1]);
; #pragma unroll
;                                 for (int e = 0; e < 4; ++e) { v0[e] *= __builtin_amdgcn_rcpf(fmaxf(b0[e], 1e-20f)); v1[e] *= __builtin_amdgcn_rcpf(fmaxf(b1[e], 1e-20f)); } } }
;                         else if (act == 1) { v0 = gelu4(v0); v1 = gelu4(v1); }
.LBB0_349:
	s_andn2_b64 vcc, exec, s[16:17]
	s_cbranch_vccnz .LBB0_351
	v_fma_f32 v154, |v40|, s28, 1.0
	v_fma_f32 v155, |v41|, s28, 1.0
	v_mov_b64_e32 v[160:161], s[34:35]
	v_rcp_f32_e32 v154, v154
	v_rcp_f32_e32 v155, v155
	v_pk_mul_f32 v[158:159], v[40:41], v[40:41]
	s_nop 0
	v_pk_mul_f32 v[158:159], v[158:159], s[74:75] op_sel_hi:[1,0]
	v_pk_fma_f32 v[156:157], v[154:155], s[30:31], v[160:161] op_sel_hi:[1,0,0]
	v_exp_f32_e32 v158, v158
	v_pk_fma_f32 v[156:157], v[154:155], v[156:157], s[36:37] op_sel_hi:[1,1,0]
	v_exp_f32_e32 v159, v159
	v_pk_fma_f32 v[156:157], v[154:155], v[156:157], s[50:51] op_sel_hi:[1,1,0]
	s_nop 0
	v_pk_fma_f32 v[156:157], v[154:155], v[156:157], s[72:73] op_sel_hi:[1,1,0]
	v_fma_f32 v168, |v42|, s28, 1.0
	v_fma_f32 v169, |v43|, s28, 1.0
	v_pk_mul_f32 v[154:155], v[154:155], v[156:157]
	v_rcp_f32_e32 v168, v168
	v_rcp_f32_e32 v169, v169
	v_pk_mul_f32 v[154:155], v[158:159], v[154:155]
	v_max_f32_e32 v240, 0, v40
	v_max_f32_e32 v241, 0, v41
	v_fma_f32 v154, -|v40|, v154, v240
	v_fma_f32 v155, -|v41|, v155, v241
	v_pk_mul_f32 v[156:157], v[42:43], v[42:43]
	s_nop 0
	v_pk_mul_f32 v[156:157], v[156:157], s[74:75] op_sel_hi:[1,0]
	v_pk_fma_f32 v[158:159], v[168:169], s[30:31], v[160:161] op_sel_hi:[1,0,0]
	v_exp_f32_e32 v156, v156
	v_pk_fma_f32 v[158:159], v[168:169], v[158:159], s[36:37] op_sel_hi:[1,1,0]
	v_exp_f32_e32 v157, v157
	v_pk_fma_f32 v[158:159], v[168:169], v[158:159], s[50:51] op_sel_hi:[1,1,0]
	s_nop 0
	v_pk_fma_f32 v[158:159], v[168:169], v[158:159], s[72:73] op_sel_hi:[1,1,0]
	s_nop 0
	v_pk_mul_f32 v[158:159], v[168:169], v[158:159]
	v_fma_f32 v168, |v32|, s28, 1.0
	v_fma_f32 v169, |v33|, s28, 1.0
	v_pk_mul_f32 v[156:157], v[156:157], v[158:159]
	v_rcp_f32_e32 v168, v168
	v_rcp_f32_e32 v169, v169
	v_max_f32_e32 v240, 0, v42
	v_max_f32_e32 v241, 0, v43
	v_fma_f32 v156, -|v42|, v156, v240
	v_fma_f32 v157, -|v43|, v157, v241
	v_fma_f32 v172, |v34|, s28, 1.0
	v_fma_f32 v173, |v35|, s28, 1.0
	s_nop 0
	v_rcp_f32_e32 v172, v172
	v_rcp_f32_e32 v173, v173
	v_pk_fma_f32 v[158:159], v[168:169], s[30:31], v[160:161] op_sel_hi:[1,0,0]
	v_pk_mul_f32 v[170:171], v[32:33], v[32:33]
	v_pk_fma_f32 v[158:159], v[168:169], v[158:159], s[36:37] op_sel_hi:[1,1,0]
	v_pk_mul_f32 v[170:171], v[170:171], s[74:75] op_sel_hi:[1,0]
	v_pk_fma_f32 v[158:159], v[168:169], v[158:159], s[50:51] op_sel_hi:[1,1,0]
	v_exp_f32_e32 v170, v170
	v_pk_fma_f32 v[158:159], v[168:169], v[158:159], s[72:73] op_sel_hi:[1,1,0]
	v_exp_f32_e32 v171, v171
	v_pk_mul_f32 v[158:159], v[168:169], v[158:159]
	v_pk_mul_f32 v[168:169], v[34:35], v[34:35]
	v_pk_fma_f32 v[160:161], v[172:173], s[30:31], v[160:161] op_sel_hi:[1,0,0]
	v_pk_mul_f32 v[168:169], v[168:169], s[74:75] op_sel_hi:[1,0]
	v_pk_fma_f32 v[160:161], v[172:173], v[160:161], s[36:37] op_sel_hi:[1,1,0]
	v_exp_f32_e32 v168, v168
	v_exp_f32_e32 v169, v169
	v_pk_fma_f32 v[160:161], v[172:173], v[160:161], s[50:51] op_sel_hi:[1,1,0]
	v_pk_mul_f32 v[158:159], v[170:171], v[158:159]
	v_pk_fma_f32 v[160:161], v[172:173], v[160:161], s[72:73] op_sel_hi:[1,1,0]
	v_max_f32_e32 v240, 0, v32
	v_max_f32_e32 v241, 0, v33
	v_fma_f32 v158, -|v32|, v158, v240
	v_fma_f32 v159, -|v33|, v159, v241
	v_pk_mul_f32 v[160:161], v[172:173], v[160:161]
	s_nop 0
	v_pk_mul_f32 v[160:161], v[168:169], v[160:161]
	s_nop 0
	v_max_f32_e32 v240, 0, v34
	v_max_f32_e32 v241, 0, v35
	v_fma_f32 v160, -|v34|, v160, v240
	v_fma_f32 v161, -|v35|, v161, v241
	s_nop 1
	s_nop 1

; __device__ __forceinline__ f32x4 gelu4(f32x4 v) { f32x2 a = gelu_pk((f32x2){v[0], v[1]}), b = gelu_pk((f32x2){v[2], v[3]}); return (f32x4){a.x, a.y, b.x, b.y}; }
; __device__ __forceinline__ f32x4 sigm4(f32x4 v) { return (f32x4){sigmoid_f(v[0]), sigmoid_f(v[1]), sigmoid_f(v[2]), sigmoid_f(v[3])}; }
; __device__ __forceinline__ f32x2 gelu_pk(f32x2 v) {
;     const f32x2 av = __builtin_elementwise_abs(v), d = av * 0.2316418882f + 1.0f;
;     f32x2 t; t.x = __builtin_amdgcn_rcpf(d.x); t.y = __builtin_amdgcn_rcpf(d.y);
;     f32x2 q = t * 0.5307027145f + (-0.7265760135f); q = q * t + 0.7107068705f; q = q * t + (-0.142248368f); q = q * t + 0.127414796f; q = q * t;
;     const f32x2 s = (v * v) * (-0.72134752044f);
;     f32x2 e; e.x = __builtin_amdgcn_exp2f(s.x); e.y = __builtin_amdgcn_exp2f(s.y);
;     const f32x2 m = v * (q * e), r = v - m;
;     f32x2 o; o.x = v.x < 0.f ? m.x : r.x; o.y = v.y < 0.f ? m.y : r.y; return o;
; }
;     __device__ __forceinline__ void operator()(const f32x4 (&acc)[2][2][4][2], const pg8::Unit& u, int wr, int wc, int fr, int fq) const {
;     ...
;                         f32x4 v0 = acc[ai][bj][m][0], v1 = acc[ai][bj][m][1];
;                         if (act == 5) { v0 = sigm4(v0); v1 = sigm4(v1);
;                             if (bj == 0) { const f32x4 b0 = sigm4(acc[ai][1][m][0]), b1 = sigm4(acc[ai][1][m][1]);
; #pragma unroll
;                                 for (int e = 0; e < 4; ++e) { v0[e] *= __builtin_amdgcn_rcpf(fmaxf(b0[e], 1e-20f)); v1[e] *= __builtin_amdgcn_rcpf(fmaxf(b1[e], 1e-20f)); } } }
;                         else if (act == 1) { v0 = gelu4(v0); v1 = gelu4(v1); }
.LBB0_363:
	s_andn2_b64 vcc, exec, s[16:17]
	s_cbranch_vccnz .LBB0_365
	v_fma_f32 v152, |v28|, s28, 1.0
	v_fma_f32 v153, |v29|, s28, 1.0
	v_mov_b64_e32 v[160:161], s[34:35]
	v_rcp_f32_e32 v152, v152
	v_rcp_f32_e32 v153, v153
	v_pk_mul_f32 v[156:157], v[28:29], v[28:29]
	s_nop 0
	v_pk_mul_f32 v[156:157], v[156:157], s[74:75] op_sel_hi:[1,0]
	v_pk_fma_f32 v[154:155], v[152:153], s[30:31], v[160:161] op_sel_hi:[1,0,0]
	v_exp_f32_e32 v156, v156
	v_pk_fma_f32 v[154:155], v[152:153], v[154:155], s[36:37] op_sel_hi:[1,1,0]
	v_exp_f32_e32 v157, v157
	v_pk_fma_f32 v[154:155], v[152:153], v[154:155], s[50:51] op_sel_hi:[1,1,0]
	v_pk_mul_f32 v[158:159], v[30:31], v[30:31]
	v_pk_fma_f32 v[154:155], v[152:153], v[154:155], s[72:73] op_sel_hi:[1,1,0]
	v_pk_mul_f32 v[158:159], v[158:159], s[74:75] op_sel_hi:[1,0]
	v_pk_mul_f32 v[152:153], v[152:153], v[154:155]
	v_exp_f32_e32 v158, v158
	v_pk_mul_f32 v[152:153], v[156:157], v[152:153]
	v_fma_f32 v156, |v30|, s28, 1.0
	v_fma_f32 v157, |v31|, s28, 1.0
	s_nop 0
	v_rcp_f32_e32 v156, v156
	v_rcp_f32_e32 v157, v157
	v_max_f32_e32 v240, 0, v28
	v_max_f32_e32 v241, 0, v29
	v_fma_f32 v154, -|v28|, v152, v240
	v_fma_f32 v155, -|v29|, v153, v241
	v_exp_f32_e32 v159, v159
	v_pk_mul_f32 v[168:169], v[20:21], v[20:21]
	v_pk_mul_f32 v[170:171], v[22:23], v[22:23]
	v_pk_fma_f32 v[152:153], v[156:157], s[30:31], v[160:161] op_sel_hi:[1,0,0]
	s_nop 0
	v_pk_fma_f32 v[152:153], v[156:157], v[152:153], s[36:37] op_sel_hi:[1,1,0]
	v_pk_mul_f32 v[168:169], v[168:169], s[74:75] op_sel_hi:[1,0]
	v_pk_fma_f32 v[152:153], v[156:157], v[152:153], s[50:51] op_sel_hi:[1,1,0]
	v_exp_f32_e32 v168, v168
	v_pk_fma_f32 v[152:153], v[156:157], v[152:153], s[72:73] op_sel_hi:[1,1,0]
	v_exp_f32_e32 v169, v169
	v_pk_mul_f32 v[152:153], v[156:157], v[152:153]
	s_nop 0
	v_pk_mul_f32 v[152:153], v[158:159], v[152:153]
	v_fma_f32 v158, |v20|, s28, 1.0
	v_fma_f32 v159, |v21|, s28, 1.0
	s_nop 0
	v_rcp_f32_e32 v158, v158
	v_rcp_f32_e32 v159, v159
	v_max_f32_e32 v240, 0, v30
	v_max_f32_e32 v241, 0, v31
	v_fma_f32 v156, -|v30|, v152, v240
	v_fma_f32 v157, -|v31|, v153, v241
	s_nop 0
	s_nop 1
	v_pk_fma_f32 v[152:153], v[158:159], s[30:31], v[160:161] op_sel_hi:[1,0,0]
	s_nop 0
	v_pk_fma_f32 v[152:153], v[158:159], v[152:153], s[36:37] op_sel_hi:[1,1,0]
	s_nop 0
	v_pk_fma_f32 v[152:153], v[158:159], v[152:153], s[50:51] op_sel_hi:[1,1,0]
	s_nop 0
	v_pk_fma_f32 v[152:153], v[158:159], v[152:153], s[72:73] op_sel_hi:[1,1,0]
	s_nop 0
	v_pk_mul_f32 v[152:153], v[158:159], v[152:153]
	s_nop 0
	v_pk_mul_f32 v[152:153], v[168:169], v[152:153]
	v_fma_f32 v168, |v22|, s28, 1.0
	v_fma_f32 v169, |v23|, s28, 1.0
	s_nop 0
	v_rcp_f32_e32 v168, v168
	v_rcp_f32_e32 v169, v169
	v_max_f32_e32 v240, 0, v20
	v_max_f32_e32 v241, 0, v21
	v_fma_f32 v158, -|v20|, v152, v240
	v_fma_f32 v159, -|v21|, v153, v241
	s_nop 0
	s_nop 1
	v_pk_fma_f32 v[152:153], v[168:169], s[30:31], v[160:161] op_sel_hi:[1,0,0]
	v_pk_mul_f32 v[160:161], v[170:171], s[74:75] op_sel_hi:[1,0]
	v_pk_fma_f32 v[152:153], v[168:169], v[152:153], s[36:37] op_sel_hi:[1,1,0]
	v_exp_f32_e32 v160, v160
	v_exp_f32_e32 v161, v161
	v_pk_fma_f32 v[152:153], v[168:169], v[152:153], s[50:51] op_sel_hi:[1,1,0]
	s_nop 0
	v_pk_fma_f32 v[152:153], v[168:169], v[152:153], s[72:73] op_sel_hi:[1,1,0]
	s_nop 0
	v_pk_mul_f32 v[152:153], v[168:169], v[152:153]
	s_nop 0
	v_pk_mul_f32 v[152:153], v[160:161], v[152:153]
	s_nop 0
	v_max_f32_e32 v240, 0, v22
	v_max_f32_e32 v241, 0, v23
	v_fma_f32 v160, -|v22|, v152, v240
	v_fma_f32 v161, -|v23|, v153, v241
	s_nop 0
	s_nop 1

; __device__ __forceinline__ f32x4 gelu4(f32x4 v) { f32x2 a = gelu_pk((f32x2){v[0], v[1]}), b = gelu_pk((f32x2){v[2], v[3]}); return (f32x4){a.x, a.y, b.x, b.y}; }
; __device__ __forceinline__ f32x4 sigm4(f32x4 v) { return (f32x4){sigmoid_f(v[0]), sigmoid_f(v[1]), sigmoid_f(v[2]), sigmoid_f(v[3])}; }
; __device__ __forceinline__ f32x2 gelu_pk(f32x2 v) {
;     const f32x2 av = __builtin_elementwise_abs(v), d = av * 0.2316418882f + 1.0f;
;     f32x2 t; t.x = __builtin_amdgcn_rcpf(d.x); t.y = __builtin_amdgcn_rcpf(d.y);
;     f32x2 q = t * 0.5307027145f + (-0.7265760135f); q = q * t + 0.7107068705f; q = q * t + (-0.142248368f); q = q * t + 0.127414796f; q = q * t;
;     const f32x2 s = (v * v) * (-0.72134752044f);
;     f32x2 e; e.x = __builtin_amdgcn_exp2f(s.x); e.y = __builtin_amdgcn_exp2f(s.y);
;     const f32x2 m = v * (q * e), r = v - m;
;     f32x2 o; o.x = v.x < 0.f ? m.x : r.x; o.y = v.y < 0.f ? m.y : r.y; return o;
; }
;     __device__ __forceinline__ void operator()(const f32x4 (&acc)[2][2][4][2], const pg8::Unit& u, int wr, int wc, int fr, int fq) const {
;     ...
;                         f32x4 v0 = acc[ai][bj][m][0], v1 = acc[ai][bj][m][1];
;                         if (act == 5) { v0 = sigm4(v0); v1 = sigm4(v1);
;                             if (bj == 0) { const f32x4 b0 = sigm4(acc[ai][1][m][0]), b1 = sigm4(acc[ai][1][m][1]);
; #pragma unroll
;                                 for (int e = 0; e < 4; ++e) { v0[e] *= __builtin_amdgcn_rcpf(fmaxf(b0[e], 1e-20f)); v1[e] *= __builtin_amdgcn_rcpf(fmaxf(b1[e], 1e-20f)); } } }
;                         else if (act == 1) { v0 = gelu4(v0); v1 = gelu4(v1); }
.LBB0_377:
	s_andn2_b64 vcc, exec, s[16:17]
	s_cbranch_vccnz .LBB0_379
	v_fma_f32 v154, |v24|, s28, 1.0
	v_fma_f32 v155, |v25|, s28, 1.0
	v_mov_b64_e32 v[160:161], s[34:35]
	v_rcp_f32_e32 v154, v154
	v_rcp_f32_e32 v155, v155
	v_pk_mul_f32 v[158:159], v[24:25], v[24:25]
	s_nop 0
	v_pk_mul_f32 v[158:159], v[158:159], s[74:75] op_sel_hi:[1,0]
	v_pk_fma_f32 v[156:157], v[154:155], s[30:31], v[160:161] op_sel_hi:[1,0,0]
	v_exp_f32_e32 v158, v158
	v_pk_fma_f32 v[156:157], v[154:155], v[156:157], s[36:37] op_sel_hi:[1,1,0]
	v_exp_f32_e32 v159, v159
	v_pk_fma_f32 v[156:157], v[154:155], v[156:157], s[50:51] op_sel_hi:[1,1,0]
	s_nop 0
	v_pk_fma_f32 v[156:157], v[154:155], v[156:157], s[72:73] op_sel_hi:[1,1,0]
	v_fma_f32 v168, |v26|, s28, 1.0
	v_fma_f32 v169, |v27|, s28, 1.0
	v_pk_mul_f32 v[154:155], v[154:155], v[156:157]
	v_rcp_f32_e32 v168, v168
	v_rcp_f32_e32 v169, v169
	v_pk_mul_f32 v[154:155], v[158:159], v[154:155]
	v_max_f32_e32 v240, 0, v24
	v_max_f32_e32 v241, 0, v25
	v_fma_f32 v154, -|v24|, v154, v240
	v_fma_f32 v155, -|v25|, v155, v241
	v_pk_mul_f32 v[156:157], v[26:27], v[26:27]
	s_nop 0
	v_pk_mul_f32 v[156:157], v[156:157], s[74:75] op_sel_hi:[1,0]
	v_pk_fma_f32 v[158:159], v[168:169], s[30:31], v[160:161] op_sel_hi:[1,0,0]
	v_exp_f32_e32 v156, v156
	v_pk_fma_f32 v[158:159], v[168:169], v[158:159], s[36:37] op_sel_hi:[1,1,0]
	v_exp_f32_e32 v157, v157
	v_pk_fma_f32 v[158:159], v[168:169], v[158:159], s[50:51] op_sel_hi:[1,1,0]
	s_nop 0
	v_pk_fma_f32 v[158:159], v[168:169], v[158:159], s[72:73] op_sel_hi:[1,1,0]
	s_nop 0
	v_pk_mul_f32 v[158:159], v[168:169], v[158:159]
	v_fma_f32 v168, |v16|, s28, 1.0
	v_fma_f32 v169, |v17|, s28, 1.0
	v_pk_mul_f32 v[156:157], v[156:157], v[158:159]
	v_rcp_f32_e32 v168, v168
	v_rcp_f32_e32 v169, v169
	v_max_f32_e32 v240, 0, v26
	v_max_f32_e32 v241, 0, v27
	v_fma_f32 v156, -|v26|, v156, v240
	v_fma_f32 v157, -|v27|, v157, v241
	v_fma_f32 v172, |v18|, s28, 1.0
	v_fma_f32 v173, |v19|, s28, 1.0
	s_nop 0
	v_rcp_f32_e32 v172, v172
	v_rcp_f32_e32 v173, v173
	v_pk_fma_f32 v[158:159], v[168:169], s[30:31], v[160:161] op_sel_hi:[1,0,0]
	v_pk_mul_f32 v[170:171], v[16:17], v[16:17]
	v_pk_fma_f32 v[158:159], v[168:169], v[158:159], s[36:37] op_sel_hi:[1,1,0]
	v_pk_mul_f32 v[170:171], v[170:171], s[74:75] op_sel_hi:[1,0]
	v_pk_fma_f32 v[158:159], v[168:169], v[158:159], s[50:51] op_sel_hi:[1,1,0]
	v_exp_f32_e32 v170, v170
	v_pk_fma_f32 v[158:159], v[168:169], v[158:159], s[72:73] op_sel_hi:[1,1,0]
	v_exp_f32_e32 v171, v171
	v_pk_mul_f32 v[158:159], v[168:169], v[158:159]
	v_pk_mul_f32 v[168:169], v[18:19], v[18:19]
	v_pk_fma_f32 v[160:161], v[172:173], s[30:31], v[160:161] op_sel_hi:[1,0,0]
	v_pk_mul_f32 v[168:169], v[168:169], s[74:75] op_sel_hi:[1,0]
	v_pk_fma_f32 v[160:161], v[172:173], v[160:161], s[36:37] op_sel_hi:[1,1,0]
	v_exp_f32_e32 v168, v168
	v_exp_f32_e32 v169, v169
	v_pk_fma_f32 v[160:161], v[172:173], v[160:161], s[50:51] op_sel_hi:[1,1,0]
	v_pk_mul_f32 v[158:159], v[170:171], v[158:159]
	v_pk_fma_f32 v[160:161], v[172:173], v[160:161], s[72:73] op_sel_hi:[1,1,0]
	v_max_f32_e32 v240, 0, v16
	v_max_f32_e32 v241, 0, v17
	v_fma_f32 v158, -|v16|, v158, v240
	v_fma_f32 v159, -|v17|, v159, v241
	v_pk_mul_f32 v[160:161], v[172:173], v[160:161]
	s_nop 0
	v_pk_mul_f32 v[160:161], v[168:169], v[160:161]
	s_nop 0
	v_max_f32_e32 v240, 0, v18
	v_max_f32_e32 v241, 0, v19
	v_fma_f32 v160, -|v18|, v160, v240
	v_fma_f32 v161, -|v19|, v161, v241
	s_nop 1
	s_nop 1

; __device__ __forceinline__ f32x4 gelu4(f32x4 v) { f32x2 a = gelu_pk((f32x2){v[0], v[1]}), b = gelu_pk((f32x2){v[2], v[3]}); return (f32x4){a.x, a.y, b.x, b.y}; }
; __device__ __forceinline__ f32x4 sigm4(f32x4 v) { return (f32x4){sigmoid_f(v[0]), sigmoid_f(v[1]), sigmoid_f(v[2]), sigmoid_f(v[3])}; }
; __device__ __forceinline__ f32x2 gelu_pk(f32x2 v) {
;     const f32x2 av = __builtin_elementwise_abs(v), d = av * 0.2316418882f + 1.0f;
;     f32x2 t; t.x = __builtin_amdgcn_rcpf(d.x); t.y = __builtin_amdgcn_rcpf(d.y);
;     f32x2 q = t * 0.5307027145f + (-0.7265760135f); q = q * t + 0.7107068705f; q = q * t + (-0.142248368f); q = q * t + 0.127414796f; q = q * t;
;     const f32x2 s = (v * v) * (-0.72134752044f);
;     f32x2 e; e.x = __builtin_amdgcn_exp2f(s.x); e.y = __builtin_amdgcn_exp2f(s.y);
;     const f32x2 m = v * (q * e), r = v - m;
;     f32x2 o; o.x = v.x < 0.f ? m.x : r.x; o.y = v.y < 0.f ? m.y : r.y; return o;
; }
;     __device__ __forceinline__ void operator()(const f32x4 (&acc)[2][2][4][2], const pg8::Unit& u, int wr, int wc, int fr, int fq) const {
;     ...
;                         f32x4 v0 = acc[ai][bj][m][0], v1 = acc[ai][bj][m][1];
;                         if (act == 5) { v0 = sigm4(v0); v1 = sigm4(v1);
;                             if (bj == 0) { const f32x4 b0 = sigm4(acc[ai][1][m][0]), b1 = sigm4(acc[ai][1][m][1]);
; #pragma unroll
;                                 for (int e = 0; e < 4; ++e) { v0[e] *= __builtin_amdgcn_rcpf(fmaxf(b0[e], 1e-20f)); v1[e] *= __builtin_amdgcn_rcpf(fmaxf(b1[e], 1e-20f)); } } }
;                         else if (act == 1) { v0 = gelu4(v0); v1 = gelu4(v1); }
.LBB0_391:
	s_andn2_b64 vcc, exec, s[16:17]
	s_cbranch_vccnz .LBB0_393
	v_fma_f32 v152, |v12|, s28, 1.0
	v_fma_f32 v153, |v13|, s28, 1.0
	v_mov_b64_e32 v[158:159], s[34:35]
	v_rcp_f32_e32 v152, v152
	v_rcp_f32_e32 v153, v153
	v_pk_mul_f32 v[156:157], v[12:13], v[12:13]
	s_nop 0
	v_pk_mul_f32 v[156:157], v[156:157], s[74:75] op_sel_hi:[1,0]
	v_pk_fma_f32 v[154:155], v[152:153], s[30:31], v[158:159] op_sel_hi:[1,0,0]
	v_exp_f32_e32 v156, v156
	v_pk_fma_f32 v[154:155], v[152:153], v[154:155], s[36:37] op_sel_hi:[1,1,0]
	v_exp_f32_e32 v157, v157
	v_pk_fma_f32 v[154:155], v[152:153], v[154:155], s[50:51] op_sel_hi:[1,1,0]
	s_nop 0
	v_pk_fma_f32 v[154:155], v[152:153], v[154:155], s[72:73] op_sel_hi:[1,1,0]
	v_fma_f32 v160, |v14|, s28, 1.0
	v_fma_f32 v161, |v15|, s28, 1.0
	v_pk_mul_f32 v[152:153], v[152:153], v[154:155]
	v_rcp_f32_e32 v160, v160
	v_rcp_f32_e32 v161, v161
	v_pk_mul_f32 v[152:153], v[156:157], v[152:153]
	v_max_f32_e32 v240, 0, v12
	v_max_f32_e32 v241, 0, v13
	v_fma_f32 v152, -|v12|, v152, v240
	v_fma_f32 v153, -|v13|, v153, v241
	v_pk_mul_f32 v[154:155], v[14:15], v[14:15]
	s_nop 0
	v_pk_mul_f32 v[154:155], v[154:155], s[74:75] op_sel_hi:[1,0]
	v_pk_fma_f32 v[156:157], v[160:161], s[30:31], v[158:159] op_sel_hi:[1,0,0]
	v_exp_f32_e32 v154, v154
	v_pk_fma_f32 v[156:157], v[160:161], v[156:157], s[36:37] op_sel_hi:[1,1,0]
	v_exp_f32_e32 v155, v155
	v_pk_fma_f32 v[156:157], v[160:161], v[156:157], s[50:51] op_sel_hi:[1,1,0]
	s_nop 0
	v_pk_fma_f32 v[156:157], v[160:161], v[156:157], s[72:73] op_sel_hi:[1,1,0]
	s_nop 0
	v_pk_mul_f32 v[156:157], v[160:161], v[156:157]
	v_fma_f32 v160, |v4|, s28, 1.0
	v_fma_f32 v161, |v5|, s28, 1.0
	v_pk_mul_f32 v[154:155], v[154:155], v[156:157]
	v_rcp_f32_e32 v160, v160
	v_rcp_f32_e32 v161, v161
	v_max_f32_e32 v240, 0, v14
	v_max_f32_e32 v241, 0, v15
	v_fma_f32 v154, -|v14|, v154, v240
	v_fma_f32 v155, -|v15|, v155, v241
	v_fma_f32 v170, |v6|, s28, 1.0
	v_fma_f32 v171, |v7|, s28, 1.0
	s_nop 0
	v_rcp_f32_e32 v170, v170
	v_rcp_f32_e32 v171, v171
	v_pk_fma_f32 v[156:157], v[160:161], s[30:31], v[158:159] op_sel_hi:[1,0,0]
	v_pk_mul_f32 v[168:169], v[4:5], v[4:5]
	v_pk_fma_f32 v[156:157], v[160:161], v[156:157], s[36:37] op_sel_hi:[1,1,0]
	v_pk_mul_f32 v[168:169], v[168:169], s[74:75] op_sel_hi:[1,0]
	v_pk_fma_f32 v[156:157], v[160:161], v[156:157], s[50:51] op_sel_hi:[1,1,0]
	v_exp_f32_e32 v168, v168
	v_pk_fma_f32 v[156:157], v[160:161], v[156:157], s[72:73] op_sel_hi:[1,1,0]
	v_exp_f32_e32 v169, v169
	v_pk_mul_f32 v[156:157], v[160:161], v[156:157]
	v_pk_mul_f32 v[160:161], v[6:7], v[6:7]
	v_pk_fma_f32 v[158:159], v[170:171], s[30:31], v[158:159] op_sel_hi:[1,0,0]
	v_pk_mul_f32 v[160:161], v[160:161], s[74:75] op_sel_hi:[1,0]
	v_pk_fma_f32 v[158:159], v[170:171], v[158:159], s[36:37] op_sel_hi:[1,1,0]
	v_exp_f32_e32 v160, v160
	v_exp_f32_e32 v161, v161
	v_pk_fma_f32 v[158:159], v[170:171], v[158:159], s[50:51] op_sel_hi:[1,1,0]
	v_pk_mul_f32 v[156:157], v[168:169], v[156:157]
	v_pk_fma_f32 v[158:159], v[170:171], v[158:159], s[72:73] op_sel_hi:[1,1,0]
	v_max_f32_e32 v240, 0, v4
	v_max_f32_e32 v241, 0, v5
	v_fma_f32 v156, -|v4|, v156, v240
	v_fma_f32 v157, -|v5|, v157, v241
	v_pk_mul_f32 v[158:159], v[170:171], v[158:159]
	s_nop 0
	v_pk_mul_f32 v[158:159], v[160:161], v[158:159]
	s_nop 0
	v_max_f32_e32 v240, 0, v6
	v_max_f32_e32 v241, 0, v7
	v_fma_f32 v158, -|v6|, v158, v240
	v_fma_f32 v159, -|v7|, v159, v241
	s_nop 1
	s_nop 1

; __device__ __forceinline__ f32x4 gelu4(f32x4 v) { f32x2 a = gelu_pk((f32x2){v[0], v[1]}), b = gelu_pk((f32x2){v[2], v[3]}); return (f32x4){a.x, a.y, b.x, b.y}; }
; __device__ __forceinline__ f32x4 sigm4(f32x4 v) { return (f32x4){sigmoid_f(v[0]), sigmoid_f(v[1]), sigmoid_f(v[2]), sigmoid_f(v[3])}; }
; __device__ __forceinline__ f32x2 gelu_pk(f32x2 v) {
;     const f32x2 av = __builtin_elementwise_abs(v), d = av * 0.2316418882f + 1.0f;
;     f32x2 t; t.x = __builtin_amdgcn_rcpf(d.x); t.y = __builtin_amdgcn_rcpf(d.y);
;     f32x2 q = t * 0.5307027145f + (-0.7265760135f); q = q * t + 0.7107068705f; q = q * t + (-0.142248368f); q = q * t + 0.127414796f; q = q * t;
;     const f32x2 s = (v * v) * (-0.72134752044f);
;     f32x2 e; e.x = __builtin_amdgcn_exp2f(s.x); e.y = __builtin_amdgcn_exp2f(s.y);
;     const f32x2 m = v * (q * e), r = v - m;
;     f32x2 o; o.x = v.x < 0.f ? m.x : r.x; o.y = v.y < 0.f ? m.y : r.y; return o;
; }
;     __device__ __forceinline__ void operator()(const f32x4 (&acc)[2][2][4][2], const pg8::Unit& u, int wr, int wc, int fr, int fq) const {
;     ...
;                         f32x4 v0 = acc[ai][bj][m][0], v1 = acc[ai][bj][m][1];
;                         if (act == 5) { v0 = sigm4(v0); v1 = sigm4(v1);
;                             if (bj == 0) { const f32x4 b0 = sigm4(acc[ai][1][m][0]), b1 = sigm4(acc[ai][1][m][1]);
; #pragma unroll
;                                 for (int e = 0; e < 4; ++e) { v0[e] *= __builtin_amdgcn_rcpf(fmaxf(b0[e], 1e-20f)); v1[e] *= __builtin_amdgcn_rcpf(fmaxf(b1[e], 1e-20f)); } } }
;                         else if (act == 1) { v0 = gelu4(v0); v1 = gelu4(v1); }
.LBB0_405:
	s_andn2_b64 vcc, exec, s[6:7]
	s_cbranch_vccnz .LBB0_407
	v_fma_f32 v150, |v8|, s28, 1.0
	v_fma_f32 v151, |v9|, s28, 1.0
	v_mov_b64_e32 v[156:157], s[34:35]
	v_rcp_f32_e32 v150, v150
	v_rcp_f32_e32 v151, v151
	v_pk_mul_f32 v[154:155], v[8:9], v[8:9]
	s_nop 0
	v_pk_mul_f32 v[154:155], v[154:155], s[74:75] op_sel_hi:[1,0]
	v_pk_fma_f32 v[152:153], v[150:151], s[30:31], v[156:157] op_sel_hi:[1,0,0]
	v_exp_f32_e32 v154, v154
	v_pk_fma_f32 v[152:153], v[150:151], v[152:153], s[36:37] op_sel_hi:[1,1,0]
	v_exp_f32_e32 v155, v155
	v_pk_fma_f32 v[152:153], v[150:151], v[152:153], s[50:51] op_sel_hi:[1,1,0]
	s_nop 0
	v_pk_fma_f32 v[152:153], v[150:151], v[152:153], s[72:73] op_sel_hi:[1,1,0]
	v_fma_f32 v158, |v10|, s28, 1.0
	v_fma_f32 v159, |v11|, s28, 1.0
	v_pk_mul_f32 v[150:151], v[150:151], v[152:153]
	v_rcp_f32_e32 v158, v158
	v_rcp_f32_e32 v159, v159
	v_pk_mul_f32 v[150:151], v[154:155], v[150:151]
	v_max_f32_e32 v240, 0, v8
	v_max_f32_e32 v241, 0, v9
	v_fma_f32 v150, -|v8|, v150, v240
	v_fma_f32 v151, -|v9|, v151, v241
	v_pk_mul_f32 v[152:153], v[10:11], v[10:11]
	s_nop 0
	v_pk_mul_f32 v[152:153], v[152:153], s[74:75] op_sel_hi:[1,0]
	v_pk_fma_f32 v[154:155], v[158:159], s[30:31], v[156:157] op_sel_hi:[1,0,0]
	v_exp_f32_e32 v152, v152
	v_pk_fma_f32 v[154:155], v[158:159], v[154:155], s[36:37] op_sel_hi:[1,1,0]
	v_exp_f32_e32 v153, v153
	v_pk_fma_f32 v[154:155], v[158:159], v[154:155], s[50:51] op_sel_hi:[1,1,0]
	s_nop 0
	v_pk_fma_f32 v[154:155], v[158:159], v[154:155], s[72:73] op_sel_hi:[1,1,0]
	s_nop 0
	v_pk_mul_f32 v[154:155], v[158:159], v[154:155]
	v_fma_f32 v158, |v0|, s28, 1.0
	v_fma_f32 v159, |v1|, s28, 1.0
	v_pk_mul_f32 v[152:153], v[152:153], v[154:155]
	v_rcp_f32_e32 v158, v158
	v_rcp_f32_e32 v159, v159
	v_max_f32_e32 v240, 0, v10
	v_max_f32_e32 v241, 0, v11
	v_fma_f32 v152, -|v10|, v152, v240
	v_fma_f32 v153, -|v11|, v153, v241
	v_fma_f32 v168, |v2|, s28, 1.0
	v_fma_f32 v169, |v3|, s28, 1.0
	s_nop 0
	v_rcp_f32_e32 v168, v168
	v_rcp_f32_e32 v169, v169
	v_pk_fma_f32 v[154:155], v[158:159], s[30:31], v[156:157] op_sel_hi:[1,0,0]
	v_pk_mul_f32 v[160:161], v[0:1], v[0:1]
	v_pk_fma_f32 v[154:155], v[158:159], v[154:155], s[36:37] op_sel_hi:[1,1,0]
	v_pk_mul_f32 v[160:161], v[160:161], s[74:75] op_sel_hi:[1,0]
	v_pk_fma_f32 v[154:155], v[158:159], v[154:155], s[50:51] op_sel_hi:[1,1,0]
	v_exp_f32_e32 v160, v160
	v_pk_fma_f32 v[154:155], v[158:159], v[154:155], s[72:73] op_sel_hi:[1,1,0]
	v_exp_f32_e32 v161, v161
	v_pk_mul_f32 v[154:155], v[158:159], v[154:155]
	v_pk_mul_f32 v[158:159], v[2:3], v[2:3]
	v_pk_fma_f32 v[156:157], v[168:169], s[30:31], v[156:157] op_sel_hi:[1,0,0]
	v_pk_mul_f32 v[158:159], v[158:159], s[74:75] op_sel_hi:[1,0]
	v_pk_fma_f32 v[156:157], v[168:169], v[156:157], s[36:37] op_sel_hi:[1,1,0]
	v_exp_f32_e32 v158, v158
	v_exp_f32_e32 v159, v159
	v_pk_fma_f32 v[156:157], v[168:169], v[156:157], s[50:51] op_sel_hi:[1,1,0]
	v_pk_mul_f32 v[154:155], v[160:161], v[154:155]
	v_pk_fma_f32 v[156:157], v[168:169], v[156:157], s[72:73] op_sel_hi:[1,1,0]
	v_max_f32_e32 v240, 0, v0
	v_max_f32_e32 v241, 0, v1
	v_fma_f32 v154, -|v0|, v154, v240
	v_fma_f32 v155, -|v1|, v155, v241
	v_pk_mul_f32 v[156:157], v[168:169], v[156:157]
	s_nop 0
	v_pk_mul_f32 v[156:157], v[158:159], v[156:157]
	s_nop 0
	v_max_f32_e32 v240, 0, v2
	v_max_f32_e32 v241, 0, v3
	v_fma_f32 v156, -|v2|, v156, v240
	v_fma_f32 v157, -|v3|, v157, v241
	s_nop 1
	s_nop 1

; __device__ __forceinline__ unsigned cvt_pk_bf16(float lo, float hi) { unsigned r; asm volatile("v_cvt_pk_bf16_f32 %0, %1, %2" : "=v"(r) : "v"(lo), "v"(hi)); return r; }
; __device__ __forceinline__ float sigmoid_f(float x) { return __builtin_amdgcn_rcpf(1.0f + __builtin_amdgcn_exp2f(-1.44269504f * x)); }
; __device__ __forceinline__ f32x2 gelu_pk(f32x2 v) {
;     const f32x2 av = __builtin_elementwise_abs(v), d = av * 0.2316418882f + 1.0f;
;     f32x2 t; t.x = __builtin_amdgcn_rcpf(d.x); t.y = __builtin_amdgcn_rcpf(d.y);
;     f32x2 q = t * 0.5307027145f + (-0.7265760135f); q = q * t + 0.7107068705f; q = q * t + (-0.142248368f); q = q * t + 0.127414796f; q = q * t;
;     const f32x2 s = (v * v) * (-0.72134752044f);
;     f32x2 e; e.x = __builtin_amdgcn_exp2f(s.x); e.y = __builtin_amdgcn_exp2f(s.y);
;     const f32x2 m = v * (q * e), r = v - m;
;     f32x2 o; o.x = v.x < 0.f ? m.x : r.x; o.y = v.y < 0.f ? m.y : r.y; return o;
; }
; __device__ __forceinline__ f32x4 gelu4(f32x4 v) { f32x2 a = gelu_pk((f32x2){v[0], v[1]}), b = gelu_pk((f32x2){v[2], v[3]}); return (f32x4){a.x, a.y, b.x, b.y}; }
; __device__ __forceinline__ f32x4 sigm4(f32x4 v) { return (f32x4){sigmoid_f(v[0]), sigmoid_f(v[1]), sigmoid_f(v[2]), sigmoid_f(v[3])}; }
; __device__ __forceinline__ f32x4 silu4(f32x4 v) { return v * sigm4(v); }
;     __device__ __forceinline__ void operator()(const f32x4 (&acc)[2][2][4][2], const pg8::Unit& u, int wr, int wc, int fr, int fq) const {
;     ...
;             bf16_t* base = PJ + T_P + 128 * pn + wc * 32 + 8 * fq;
; #pragma unroll
;             for (int ai = 0; ai < 2; ++ai)
; #pragma unroll
;                 for (int m = 0; m < 4; ++m) {
;                     bf16_t* rowp = base + (size_t)(row0 + ai * 128 + m * 16) * 1024;
;                     const f32x4 v0 = gelu4(acc[ai][0][m][0]) * silu4(acc[ai][1][m][0]), v1 = gelu4(acc[ai][0][m][1]) * silu4(acc[ai][1][m][1]);
;                     u32x4 w; w.x = cvt_pk_bf16(v0[0], v0[1]); w.y = cvt_pk_bf16(v0[2], v0[3]); w.z = cvt_pk_bf16(v1[0], v1[1]); w.w = cvt_pk_bf16(v1[2], v1[3]);
;                     __builtin_nontemporal_store(w, (u32x4*)rowp);
.LBB0_411:
	v_fma_f32 v148, |v124|, s28, 1.0
	v_fma_f32 v149, |v125|, s28, 1.0
	v_mov_b64_e32 v[150:151], s[34:35]
	v_rcp_f32_e32 v154, v148
	v_rcp_f32_e32 v155, v149
	v_pk_mul_f32 v[158:159], v[124:125], v[124:125]
	s_nop 0
	v_pk_mul_f32 v[158:159], v[158:159], s[74:75] op_sel_hi:[1,0]
	v_pk_fma_f32 v[156:157], v[154:155], s[30:31], v[150:151] op_sel_hi:[1,0,0]
	v_exp_f32_e32 v158, v158
	v_pk_fma_f32 v[156:157], v[154:155], v[156:157], s[36:37] op_sel_hi:[1,1,0]
	v_exp_f32_e32 v159, v159
	v_pk_fma_f32 v[156:157], v[154:155], v[156:157], s[50:51] op_sel_hi:[1,1,0]
	s_nop 0
	v_pk_fma_f32 v[156:157], v[154:155], v[156:157], s[72:73] op_sel_hi:[1,1,0]
	v_fma_f32 v160, |v126|, s28, 1.0
	v_fma_f32 v161, |v127|, s28, 1.0
	v_pk_mul_f32 v[154:155], v[154:155], v[156:157]
	v_rcp_f32_e32 v160, v160
	v_rcp_f32_e32 v161, v161
	v_pk_mul_f32 v[154:155], v[158:159], v[154:155]
	v_max_f32_e32 v240, 0, v124
	v_max_f32_e32 v241, 0, v125
	v_fma_f32 v124, -|v124|, v154, v240
	v_fma_f32 v125, -|v125|, v155, v241
	v_pk_mul_f32 v[156:157], v[126:127], v[126:127]
	s_nop 0
	v_pk_mul_f32 v[156:157], v[156:157], s[74:75] op_sel_hi:[1,0]
	v_ashrrev_i32_e32 v147, 31, v146
	v_pk_fma_f32 v[154:155], v[160:161], s[30:31], v[150:151] op_sel_hi:[1,0,0]
	v_exp_f32_e32 v156, v156
	v_pk_fma_f32 v[154:155], v[160:161], v[154:155], s[36:37] op_sel_hi:[1,1,0]
	v_exp_f32_e32 v157, v157
	v_pk_fma_f32 v[154:155], v[160:161], v[154:155], s[50:51] op_sel_hi:[1,1,0]
	v_lshlrev_b64 v[148:149], 11, v[146:147]
	v_pk_fma_f32 v[154:155], v[160:161], v[154:155], s[72:73] op_sel_hi:[1,1,0]
	s_nop 0
	v_pk_mul_f32 v[154:155], v[160:161], v[154:155]
	v_mul_f32_e32 v147, 0xbfb8aa3b, v120
	v_pk_mul_f32 v[154:155], v[156:157], v[154:155]
	v_exp_f32_e32 v147, v147
	v_max_f32_e32 v240, 0, v126
	v_max_f32_e32 v241, 0, v127
	v_fma_f32 v126, -|v126|, v154, v240
	v_fma_f32 v127, -|v127|, v155, v241
	s_lshl_b32 s6, s84, 7
	v_mul_f32_e32 v154, 0xbfb8aa3b, v121
	v_exp_f32_e32 v156, v154
	v_add_f32_e32 v147, 1.0, v147
	v_rcp_f32_e32 v154, v147
	v_mul_f32_e32 v155, 0xbfb8aa3b, v122
	v_add_f32_e32 v147, 1.0, v156
	v_exp_f32_e32 v156, v155
	v_mul_f32_e32 v155, 0xbfb8aa3b, v123
	v_exp_f32_e32 v157, v155
	v_rcp_f32_e32 v155, v147
	v_add_f32_e32 v147, 1.0, v156
	v_rcp_f32_e32 v156, v147
	v_add_f32_e32 v147, 1.0, v157
	v_rcp_f32_e32 v157, v147
	v_pk_mul_f32 v[120:121], v[120:121], v[154:155]
	v_fma_f32 v154, |v116|, s28, 1.0
	v_fma_f32 v155, |v117|, s28, 1.0
	v_pk_mul_f32 v[122:123], v[122:123], v[156:157]
	v_rcp_f32_e32 v154, v154
	v_rcp_f32_e32 v155, v155
	v_pk_mul_f32 v[122:123], v[126:127], v[122:123]
	v_pk_mul_f32 v[126:127], v[116:117], v[116:117]
	v_pk_mul_f32 v[120:121], v[124:125], v[120:121]
	v_pk_fma_f32 v[124:125], v[154:155], s[30:31], v[150:151] op_sel_hi:[1,0,0]
	v_pk_mul_f32 v[126:127], v[126:127], s[74:75] op_sel_hi:[1,0]
	v_pk_fma_f32 v[124:125], v[154:155], v[124:125], s[36:37] op_sel_hi:[1,1,0]
	v_exp_f32_e32 v126, v126
	v_exp_f32_e32 v127, v127
	v_pk_fma_f32 v[124:125], v[154:155], v[124:125], s[50:51] op_sel_hi:[1,1,0]
	s_nop 0
	v_pk_fma_f32 v[124:125], v[154:155], v[124:125], s[72:73] op_sel_hi:[1,1,0]
	v_fma_f32 v156, |v118|, s28, 1.0
	v_fma_f32 v157, |v119|, s28, 1.0
	v_pk_mul_f32 v[124:125], v[154:155], v[124:125]
	v_rcp_f32_e32 v156, v156
	v_rcp_f32_e32 v157, v157
	v_pk_mul_f32 v[124:125], v[126:127], v[124:125]
	v_max_f32_e32 v240, 0, v116
	v_max_f32_e32 v241, 0, v117
	v_fma_f32 v116, -|v116|, v124, v240
	v_fma_f32 v117, -|v117|, v125, v241
	v_pk_mul_f32 v[154:155], v[118:119], v[118:119]
	v_mul_f32_e32 v147, 0xbfb8aa3b, v112
	v_exp_f32_e32 v147, v147
	v_pk_fma_f32 v[124:125], v[156:157], s[30:31], v[150:151] op_sel_hi:[1,0,0]
	v_pk_mul_f32 v[126:127], v[154:155], s[74:75] op_sel_hi:[1,0]
	v_pk_fma_f32 v[124:125], v[156:157], v[124:125], s[36:37] op_sel_hi:[1,1,0]
	v_exp_f32_e32 v126, v126
	v_exp_f32_e32 v127, v127
	v_pk_fma_f32 v[124:125], v[156:157], v[124:125], s[50:51] op_sel_hi:[1,1,0]
	v_mul_f32_e32 v154, 0xbfb8aa3b, v113
	v_pk_fma_f32 v[124:125], v[156:157], v[124:125], s[72:73] op_sel_hi:[1,1,0]
	s_nop 0
	v_pk_mul_f32 v[124:125], v[156:157], v[124:125]
	v_exp_f32_e32 v155, v154
	v_pk_mul_f32 v[124:125], v[126:127], v[124:125]
	s_ashr_i32 s7, s6, 31
	v_max_f32_e32 v240, 0, v118
	v_max_f32_e32 v241, 0, v119
	v_fma_f32 v118, -|v118|, v124, v240
	v_fma_f32 v119, -|v119|, v125, v241
	v_lshl_add_u64 v[152:153], s[6:7], 1, v[136:137]
	v_mul_f32_e32 v126, 0xbfb8aa3b, v114
	v_add_f32_e32 v124, 1.0, v147
	v_exp_f32_e32 v126, v126
	v_mul_f32_e32 v147, 0xbfb8aa3b, v115
	v_exp_f32_e32 v147, v147
	v_rcp_f32_e32 v154, v124
	v_add_f32_e32 v124, 1.0, v155
	v_rcp_f32_e32 v155, v124
	v_add_f32_e32 v124, 1.0, v126
	v_rcp_f32_e32 v156, v124
	v_add_f32_e32 v124, 1.0, v147
	v_rcp_f32_e32 v157, v124
	v_pk_mul_f32 v[112:113], v[112:113], v[154:155]
	v_lshl_add_u64 v[148:149], v[152:153], 0, v[148:149]
	v_pk_mul_f32 v[114:115], v[114:115], v[156:157]
	s_nop 0
	v_pk_mul_f32 v[118:119], v[118:119], v[114:115]
	v_pk_mul_f32 v[114:115], v[116:117], v[112:113]
	v_cvt_pk_bf16_f32 v112, v120, v121
	v_cvt_pk_bf16_f32 v113, v122, v123
	v_cvt_pk_bf16_f32 v114, v114, v115
	v_cvt_pk_bf16_f32 v115, v118, v119
	global_store_dwordx4 v[148:149], v[112:115], off nt
	s_cmp_lg_u64 s[24:25], 0
	s_cbranch_scc0 .Lepi_nb_b
	s_barrier
; __device__ __forceinline__ unsigned cvt_pk_bf16(float lo, float hi) { unsigned r; asm volatile("v_cvt_pk_bf16_f32 %0, %1, %2" : "=v"(r) : "v"(lo), "v"(hi)); return r; }
; __device__ __forceinline__ float sigmoid_f(float x) { return __builtin_amdgcn_rcpf(1.0f + __builtin_amdgcn_exp2f(-1.44269504f * x)); }
; __device__ __forceinline__ f32x2 gelu_pk(f32x2 v) {
;     const f32x2 av = __builtin_elementwise_abs(v), d = av * 0.2316418882f + 1.0f;
;     f32x2 t; t.x = __builtin_amdgcn_rcpf(d.x); t.y = __builtin_amdgcn_rcpf(d.y);
;     f32x2 q = t * 0.5307027145f + (-0.7265760135f); q = q * t + 0.7107068705f; q = q * t + (-0.142248368f); q = q * t + 0.127414796f; q = q * t;
;     const f32x2 s = (v * v) * (-0.72134752044f);
;     f32x2 e; e.x = __builtin_amdgcn_exp2f(s.x); e.y = __builtin_amdgcn_exp2f(s.y);
;     const f32x2 m = v * (q * e), r = v - m;
;     f32x2 o; o.x = v.x < 0.f ? m.x : r.x; o.y = v.y < 0.f ? m.y : r.y; return o;
; }
; __device__ __forceinline__ f32x4 gelu4(f32x4 v) { f32x2 a = gelu_pk((f32x2){v[0], v[1]}), b = gelu_pk((f32x2){v[2], v[3]}); return (f32x4){a.x, a.y, b.x, b.y}; }
; __device__ __forceinline__ f32x4 sigm4(f32x4 v) { return (f32x4){sigmoid_f(v[0]), sigmoid_f(v[1]), sigmoid_f(v[2]), sigmoid_f(v[3])}; }
; __device__ __forceinline__ f32x4 silu4(f32x4 v) { return v * sigm4(v); }
;     __device__ __forceinline__ void operator()(const f32x4 (&acc)[2][2][4][2], const pg8::Unit& u, int wr, int wc, int fr, int fq) const {
;     ...
;             bf16_t* base = PJ + T_P + 128 * pn + wc * 32 + 8 * fq;
; #pragma unroll
;             for (int ai = 0; ai < 2; ++ai)
; #pragma unroll
;                 for (int m = 0; m < 4; ++m) {
;                     bf16_t* rowp = base + (size_t)(row0 + ai * 128 + m * 16) * 1024;
;                     const f32x4 v0 = gelu4(acc[ai][0][m][0]) * silu4(acc[ai][1][m][0]), v1 = gelu4(acc[ai][0][m][1]) * silu4(acc[ai][1][m][1]);
;                     u32x4 w; w.x = cvt_pk_bf16(v0[0], v0[1]); w.y = cvt_pk_bf16(v0[2], v0[3]); w.z = cvt_pk_bf16(v1[0], v1[1]); w.w = cvt_pk_bf16(v1[2], v1[3]);
;                     __builtin_nontemporal_store(w, (u32x4*)rowp);
.Lepi_nb_b:
	v_pk_mul_f32 v[118:119], v[108:109], v[108:109]
	v_fma_f32 v114, |v108|, s28, 1.0
	v_fma_f32 v115, |v109|, s28, 1.0
	v_pk_mul_f32 v[118:119], v[118:119], s[74:75] op_sel_hi:[1,0]
	v_rcp_f32_e32 v114, v114
	v_rcp_f32_e32 v115, v115
	v_exp_f32_e32 v118, v118
	v_exp_f32_e32 v119, v119
	v_fma_f32 v120, |v110|, s28, 1.0
	v_fma_f32 v121, |v111|, s28, 1.0
	v_pk_fma_f32 v[116:117], v[114:115], s[30:31], v[150:151] op_sel_hi:[1,0,0]
	v_rcp_f32_e32 v120, v120
	v_pk_fma_f32 v[116:117], v[114:115], v[116:117], s[36:37] op_sel_hi:[1,1,0]
	v_rcp_f32_e32 v121, v121
	v_pk_fma_f32 v[116:117], v[114:115], v[116:117], s[50:51] op_sel_hi:[1,1,0]
	v_or_b32_e32 v112, 16, v146
	v_pk_fma_f32 v[116:117], v[114:115], v[116:117], s[72:73] op_sel_hi:[1,1,0]
	v_ashrrev_i32_e32 v113, 31, v112
	v_pk_mul_f32 v[114:115], v[114:115], v[116:117]
	v_pk_mul_f32 v[116:117], v[110:111], v[110:111]
	v_pk_mul_f32 v[114:115], v[118:119], v[114:115]
	v_pk_mul_f32 v[116:117], v[116:117], s[74:75] op_sel_hi:[1,0]
	v_max_f32_e32 v240, 0, v108
	v_max_f32_e32 v241, 0, v109
	v_fma_f32 v108, -|v108|, v114, v240
	v_fma_f32 v109, -|v109|, v115, v241
	v_exp_f32_e32 v116, v116
	v_exp_f32_e32 v117, v117
	v_lshlrev_b64 v[112:113], 11, v[112:113]
	v_pk_fma_f32 v[114:115], v[120:121], s[30:31], v[150:151] op_sel_hi:[1,0,0]
	s_nop 0
	v_pk_fma_f32 v[114:115], v[120:121], v[114:115], s[36:37] op_sel_hi:[1,1,0]
	v_lshl_add_u64 v[112:113], v[152:153], 0, v[112:113]
	v_pk_fma_f32 v[114:115], v[120:121], v[114:115], s[50:51] op_sel_hi:[1,1,0]
	s_mov_b32 s6, 0x40000
	v_pk_fma_f32 v[114:115], v[120:121], v[114:115], s[72:73] op_sel_hi:[1,1,0]
	s_nop 0
	v_pk_mul_f32 v[114:115], v[120:121], v[114:115]
	s_nop 0
	v_pk_mul_f32 v[114:115], v[116:117], v[114:115]
	s_nop 0
	v_max_f32_e32 v240, 0, v110
	v_max_f32_e32 v241, 0, v111
	v_fma_f32 v110, -|v110|, v114, v240
	v_fma_f32 v111, -|v111|, v115, v241
	s_nop 0
	v_mul_f32_e32 v116, 0xbfb8aa3b, v105
	v_mul_f32_e32 v114, 0xbfb8aa3b, v104
	v_exp_f32_e32 v116, v116
	v_exp_f32_e32 v114, v114
	s_nop 0
	v_add_f32_e32 v114, 1.0, v114
	s_nop 0
	v_add_f32_e32 v115, 1.0, v116
	v_mul_f32_e32 v116, 0xbfb8aa3b, v106
	v_mul_f32_e32 v117, 0xbfb8aa3b, v107
	v_exp_f32_e32 v116, v116
	v_exp_f32_e32 v117, v117
	v_rcp_f32_e32 v114, v114
	v_rcp_f32_e32 v115, v115
	v_add_f32_e32 v116, 1.0, v116
	v_add_f32_e32 v117, 1.0, v117
	v_rcp_f32_e32 v116, v116
	v_rcp_f32_e32 v117, v117
	v_pk_mul_f32 v[104:105], v[104:105], v[114:115]
	v_fma_f32 v114, |v100|, s28, 1.0
	v_fma_f32 v115, |v101|, s28, 1.0
	v_pk_mul_f32 v[106:107], v[106:107], v[116:117]
	v_rcp_f32_e32 v114, v114
	v_rcp_f32_e32 v115, v115
	v_pk_mul_f32 v[106:107], v[110:111], v[106:107]
	v_pk_mul_f32 v[110:111], v[100:101], v[100:101]
	v_pk_mul_f32 v[104:105], v[108:109], v[104:105]
	v_pk_fma_f32 v[108:109], v[114:115], s[30:31], v[150:151] op_sel_hi:[1,0,0]
	v_pk_mul_f32 v[110:111], v[110:111], s[74:75] op_sel_hi:[1,0]
	v_pk_fma_f32 v[108:109], v[114:115], v[108:109], s[36:37] op_sel_hi:[1,1,0]
	v_exp_f32_e32 v110, v110
	v_exp_f32_e32 v111, v111
	v_pk_fma_f32 v[108:109], v[114:115], v[108:109], s[50:51] op_sel_hi:[1,1,0]
	s_nop 0
	v_pk_fma_f32 v[108:109], v[114:115], v[108:109], s[72:73] op_sel_hi:[1,1,0]
	v_fma_f32 v116, |v102|, s28, 1.0
	v_fma_f32 v117, |v103|, s28, 1.0
	v_pk_mul_f32 v[108:109], v[114:115], v[108:109]
	v_rcp_f32_e32 v116, v116
	v_rcp_f32_e32 v117, v117
	v_pk_mul_f32 v[108:109], v[110:111], v[108:109]
	v_max_f32_e32 v240, 0, v100
	v_max_f32_e32 v241, 0, v101
	v_fma_f32 v100, -|v100|, v108, v240
	v_fma_f32 v101, -|v101|, v109, v241
	v_pk_mul_f32 v[114:115], v[102:103], v[102:103]
	s_nop 1
	v_pk_fma_f32 v[108:109], v[116:117], s[30:31], v[150:151] op_sel_hi:[1,0,0]
	v_pk_mul_f32 v[110:111], v[114:115], s[74:75] op_sel_hi:[1,0]
	v_pk_fma_f32 v[108:109], v[116:117], v[108:109], s[36:37] op_sel_hi:[1,1,0]
	v_exp_f32_e32 v110, v110
	v_exp_f32_e32 v111, v111
	v_pk_fma_f32 v[108:109], v[116:117], v[108:109], s[50:51] op_sel_hi:[1,1,0]
	v_mul_f32_e32 v114, 0xbfb8aa3b, v96
	v_pk_fma_f32 v[108:109], v[116:117], v[108:109], s[72:73] op_sel_hi:[1,1,0]
	v_exp_f32_e32 v114, v114
	v_mul_f32_e32 v115, 0xbfb8aa3b, v97
	v_pk_mul_f32 v[108:109], v[116:117], v[108:109]
	v_exp_f32_e32 v115, v115
	v_pk_mul_f32 v[108:109], v[110:111], v[108:109]
	v_max_f32_e32 v240, 0, v102
	v_max_f32_e32 v241, 0, v103
	v_fma_f32 v102, -|v102|, v108, v240
	v_fma_f32 v103, -|v103|, v109, v241
	s_nop 0
	v_add_f32_e32 v108, 1.0, v114
	v_mul_f32_e32 v110, 0xbfb8aa3b, v98
	v_rcp_f32_e32 v114, v108
	v_add_f32_e32 v108, 1.0, v115
	v_exp_f32_e32 v110, v110
	v_mul_f32_e32 v115, 0xbfb8aa3b, v99
	v_exp_f32_e32 v117, v115
	v_rcp_f32_e32 v115, v108
	v_add_f32_e32 v108, 1.0, v110
	v_rcp_f32_e32 v116, v108
	v_add_f32_e32 v108, 1.0, v117
	v_rcp_f32_e32 v117, v108
	v_pk_mul_f32 v[96:97], v[96:97], v[114:115]
	v_pk_mul_f32 v[98:99], v[98:99], v[116:117]
	s_nop 0
	v_pk_mul_f32 v[102:103], v[102:103], v[98:99]
	v_pk_mul_f32 v[98:99], v[100:101], v[96:97]
	v_cvt_pk_bf16_f32 v96, v104, v105
	v_cvt_pk_bf16_f32 v97, v106, v107
	v_cvt_pk_bf16_f32 v98, v98, v99
	v_cvt_pk_bf16_f32 v99, v102, v103
	global_store_dwordx4 v[112:113], v[96:99], off nt
	v_pk_mul_f32 v[102:103], v[92:93], v[92:93]
	s_nop 0
	v_fma_f32 v98, |v92|, s28, 1.0
	v_fma_f32 v99, |v93|, s28, 1.0
	v_pk_mul_f32 v[102:103], v[102:103], s[74:75] op_sel_hi:[1,0]
	v_rcp_f32_e32 v98, v98
	v_rcp_f32_e32 v99, v99
	v_exp_f32_e32 v102, v102
	v_exp_f32_e32 v103, v103
	v_fma_f32 v104, |v94|, s28, 1.0
	v_fma_f32 v105, |v95|, s28, 1.0
	v_pk_fma_f32 v[100:101], v[98:99], s[30:31], v[150:151] op_sel_hi:[1,0,0]
	v_rcp_f32_e32 v104, v104
	v_pk_fma_f32 v[100:101], v[98:99], v[100:101], s[36:37] op_sel_hi:[1,1,0]
; __device__ __forceinline__ unsigned cvt_pk_bf16(float lo, float hi) { unsigned r; asm volatile("v_cvt_pk_bf16_f32 %0, %1, %2" : "=v"(r) : "v"(lo), "v"(hi)); return r; }
; __device__ __forceinline__ float sigmoid_f(float x) { return __builtin_amdgcn_rcpf(1.0f + __builtin_amdgcn_exp2f(-1.44269504f * x)); }
; __device__ __forceinline__ f32x2 gelu_pk(f32x2 v) {
;     const f32x2 av = __builtin_elementwise_abs(v), d = av * 0.2316418882f + 1.0f;
;     f32x2 t; t.x = __builtin_amdgcn_rcpf(d.x); t.y = __builtin_amdgcn_rcpf(d.y);
;     f32x2 q = t * 0.5307027145f + (-0.7265760135f); q = q * t + 0.7107068705f; q = q * t + (-0.142248368f); q = q * t + 0.127414796f; q = q * t;
;     const f32x2 s = (v * v) * (-0.72134752044f);
;     f32x2 e; e.x = __builtin_amdgcn_exp2f(s.x); e.y = __builtin_amdgcn_exp2f(s.y);
;     const f32x2 m = v * (q * e), r = v - m;
;     f32x2 o; o.x = v.x < 0.f ? m.x : r.x; o.y = v.y < 0.f ? m.y : r.y; return o;
; }
; __device__ __forceinline__ f32x4 gelu4(f32x4 v) { f32x2 a = gelu_pk((f32x2){v[0], v[1]}), b = gelu_pk((f32x2){v[2], v[3]}); return (f32x4){a.x, a.y, b.x, b.y}; }
; __device__ __forceinline__ f32x4 sigm4(f32x4 v) { return (f32x4){sigmoid_f(v[0]), sigmoid_f(v[1]), sigmoid_f(v[2]), sigmoid_f(v[3])}; }
; __device__ __forceinline__ f32x4 silu4(f32x4 v) { return v * sigm4(v); }
;     __device__ __forceinline__ void operator()(const f32x4 (&acc)[2][2][4][2], const pg8::Unit& u, int wr, int wc, int fr, int fq) const {
;     ...
;             bf16_t* base = PJ + T_P + 128 * pn + wc * 32 + 8 * fq;
; #pragma unroll
;             for (int ai = 0; ai < 2; ++ai)
; #pragma unroll
;                 for (int m = 0; m < 4; ++m) {
;                     bf16_t* rowp = base + (size_t)(row0 + ai * 128 + m * 16) * 1024;
;                     const f32x4 v0 = gelu4(acc[ai][0][m][0]) * silu4(acc[ai][1][m][0]), v1 = gelu4(acc[ai][0][m][1]) * silu4(acc[ai][1][m][1]);
;                     u32x4 w; w.x = cvt_pk_bf16(v0[0], v0[1]); w.y = cvt_pk_bf16(v0[2], v0[3]); w.z = cvt_pk_bf16(v1[0], v1[1]); w.w = cvt_pk_bf16(v1[2], v1[3]);
;                     __builtin_nontemporal_store(w, (u32x4*)rowp);
	v_rcp_f32_e32 v105, v105
	v_pk_fma_f32 v[100:101], v[98:99], v[100:101], s[50:51] op_sel_hi:[1,1,0]
	s_nop 0
	v_pk_fma_f32 v[100:101], v[98:99], v[100:101], s[72:73] op_sel_hi:[1,1,0]
	v_or_b32_e32 v96, 32, v146
	v_pk_mul_f32 v[98:99], v[98:99], v[100:101]
	v_pk_mul_f32 v[100:101], v[94:95], v[94:95]
	v_pk_mul_f32 v[98:99], v[102:103], v[98:99]
	v_pk_mul_f32 v[100:101], v[100:101], s[74:75] op_sel_hi:[1,0]
	v_max_f32_e32 v240, 0, v92
	v_max_f32_e32 v241, 0, v93
	v_fma_f32 v92, -|v92|, v98, v240
	v_fma_f32 v93, -|v93|, v99, v241
	v_exp_f32_e32 v100, v100
	v_exp_f32_e32 v101, v101
	v_ashrrev_i32_e32 v97, 31, v96
	v_pk_fma_f32 v[98:99], v[104:105], s[30:31], v[150:151] op_sel_hi:[1,0,0]
	s_nop 0
	v_pk_fma_f32 v[98:99], v[104:105], v[98:99], s[36:37] op_sel_hi:[1,1,0]
	v_lshlrev_b64 v[96:97], 11, v[96:97]
	v_pk_fma_f32 v[98:99], v[104:105], v[98:99], s[50:51] op_sel_hi:[1,1,0]
	v_lshl_add_u64 v[96:97], v[152:153], 0, v[96:97]
	v_pk_fma_f32 v[98:99], v[104:105], v[98:99], s[72:73] op_sel_hi:[1,1,0]
	s_nop 0
	v_pk_mul_f32 v[98:99], v[104:105], v[98:99]
	s_nop 0
	v_pk_mul_f32 v[98:99], v[100:101], v[98:99]
	s_nop 0
	v_max_f32_e32 v240, 0, v94
	v_max_f32_e32 v241, 0, v95
	v_fma_f32 v94, -|v94|, v98, v240
	v_fma_f32 v95, -|v95|, v99, v241
	s_nop 0
	v_mul_f32_e32 v100, 0xbfb8aa3b, v89
	v_mul_f32_e32 v98, 0xbfb8aa3b, v88
	v_exp_f32_e32 v100, v100
	v_exp_f32_e32 v98, v98
	s_nop 0
	v_add_f32_e32 v98, 1.0, v98
	s_nop 0
	v_add_f32_e32 v99, 1.0, v100
	v_mul_f32_e32 v100, 0xbfb8aa3b, v90
	v_mul_f32_e32 v101, 0xbfb8aa3b, v91
	v_exp_f32_e32 v100, v100
	v_exp_f32_e32 v101, v101
	v_rcp_f32_e32 v98, v98
	v_rcp_f32_e32 v99, v99
	v_add_f32_e32 v100, 1.0, v100
	v_add_f32_e32 v101, 1.0, v101
	v_rcp_f32_e32 v100, v100
	v_rcp_f32_e32 v101, v101
	v_pk_mul_f32 v[88:89], v[88:89], v[98:99]
	v_fma_f32 v98, |v84|, s28, 1.0
	v_fma_f32 v99, |v85|, s28, 1.0
	v_pk_mul_f32 v[90:91], v[90:91], v[100:101]
	v_rcp_f32_e32 v98, v98
	v_rcp_f32_e32 v99, v99
	v_pk_mul_f32 v[90:91], v[94:95], v[90:91]
	v_pk_mul_f32 v[94:95], v[84:85], v[84:85]
	v_pk_mul_f32 v[88:89], v[92:93], v[88:89]
	v_pk_fma_f32 v[92:93], v[98:99], s[30:31], v[150:151] op_sel_hi:[1,0,0]
	v_pk_mul_f32 v[94:95], v[94:95], s[74:75] op_sel_hi:[1,0]
	v_pk_fma_f32 v[92:93], v[98:99], v[92:93], s[36:37] op_sel_hi:[1,1,0]
	v_exp_f32_e32 v94, v94
	v_exp_f32_e32 v95, v95
	v_pk_fma_f32 v[92:93], v[98:99], v[92:93], s[50:51] op_sel_hi:[1,1,0]
	s_nop 0
	v_pk_fma_f32 v[92:93], v[98:99], v[92:93], s[72:73] op_sel_hi:[1,1,0]
	v_fma_f32 v100, |v86|, s28, 1.0
	v_fma_f32 v101, |v87|, s28, 1.0
	v_pk_mul_f32 v[92:93], v[98:99], v[92:93]
	v_rcp_f32_e32 v100, v100
	v_rcp_f32_e32 v101, v101
	v_pk_mul_f32 v[92:93], v[94:95], v[92:93]
	v_max_f32_e32 v240, 0, v84
	v_max_f32_e32 v241, 0, v85
	v_fma_f32 v84, -|v84|, v92, v240
	v_fma_f32 v85, -|v85|, v93, v241
	v_pk_mul_f32 v[98:99], v[86:87], v[86:87]
	s_nop 1
	v_pk_fma_f32 v[92:93], v[100:101], s[30:31], v[150:151] op_sel_hi:[1,0,0]
	v_pk_mul_f32 v[94:95], v[98:99], s[74:75] op_sel_hi:[1,0]
	v_pk_fma_f32 v[92:93], v[100:101], v[92:93], s[36:37] op_sel_hi:[1,1,0]
	v_exp_f32_e32 v94, v94
	v_exp_f32_e32 v95, v95
	v_pk_fma_f32 v[92:93], v[100:101], v[92:93], s[50:51] op_sel_hi:[1,1,0]
	v_mul_f32_e32 v98, 0xbfb8aa3b, v80
	v_pk_fma_f32 v[92:93], v[100:101], v[92:93], s[72:73] op_sel_hi:[1,1,0]
	v_exp_f32_e32 v98, v98
	v_mul_f32_e32 v99, 0xbfb8aa3b, v81
	v_pk_mul_f32 v[92:93], v[100:101], v[92:93]
	v_exp_f32_e32 v99, v99
	v_pk_mul_f32 v[92:93], v[94:95], v[92:93]
	v_max_f32_e32 v240, 0, v86
	v_max_f32_e32 v241, 0, v87
	v_fma_f32 v86, -|v86|, v92, v240
	v_fma_f32 v87, -|v87|, v93, v241
	s_nop 0
	v_add_f32_e32 v92, 1.0, v98
	v_mul_f32_e32 v94, 0xbfb8aa3b, v82
	v_rcp_f32_e32 v98, v92
	v_add_f32_e32 v92, 1.0, v99
	v_exp_f32_e32 v94, v94
	v_mul_f32_e32 v99, 0xbfb8aa3b, v83
	v_exp_f32_e32 v101, v99
	v_rcp_f32_e32 v99, v92
	v_add_f32_e32 v92, 1.0, v94
	v_rcp_f32_e32 v100, v92
	v_add_f32_e32 v92, 1.0, v101
	v_rcp_f32_e32 v101, v92
	v_pk_mul_f32 v[80:81], v[80:81], v[98:99]
	v_pk_mul_f32 v[82:83], v[82:83], v[100:101]
	s_nop 0
	v_pk_mul_f32 v[86:87], v[86:87], v[82:83]
	v_pk_mul_f32 v[82:83], v[84:85], v[80:81]
	v_cvt_pk_bf16_f32 v80, v88, v89
	v_cvt_pk_bf16_f32 v81, v90, v91
	v_cvt_pk_bf16_f32 v82, v82, v83
	v_cvt_pk_bf16_f32 v83, v86, v87
	global_store_dwordx4 v[96:97], v[80:83], off nt
	v_pk_mul_f32 v[86:87], v[76:77], v[76:77]
	s_nop 0
	v_fma_f32 v82, |v76|, s28, 1.0
	v_fma_f32 v83, |v77|, s28, 1.0
	v_pk_mul_f32 v[86:87], v[86:87], s[74:75] op_sel_hi:[1,0]
	v_rcp_f32_e32 v82, v82
	v_rcp_f32_e32 v83, v83
	v_exp_f32_e32 v86, v86
	v_exp_f32_e32 v87, v87
	v_fma_f32 v88, |v78|, s28, 1.0
	v_fma_f32 v89, |v79|, s28, 1.0
	v_pk_fma_f32 v[84:85], v[82:83], s[30:31], v[150:151] op_sel_hi:[1,0,0]
	v_rcp_f32_e32 v88, v88
	v_pk_fma_f32 v[84:85], v[82:83], v[84:85], s[36:37] op_sel_hi:[1,1,0]
	v_rcp_f32_e32 v89, v89
	v_pk_fma_f32 v[84:85], v[82:83], v[84:85], s[50:51] op_sel_hi:[1,1,0]
	s_nop 0
	v_pk_fma_f32 v[84:85], v[82:83], v[84:85], s[72:73] op_sel_hi:[1,1,0]
	v_or_b32_e32 v80, 48, v146
	v_pk_mul_f32 v[82:83], v[82:83], v[84:85]
	v_pk_mul_f32 v[84:85], v[78:79], v[78:79]
	v_pk_mul_f32 v[82:83], v[86:87], v[82:83]
	v_pk_mul_f32 v[84:85], v[84:85], s[74:75] op_sel_hi:[1,0]
	v_max_f32_e32 v240, 0, v76
	v_max_f32_e32 v241, 0, v77
	v_fma_f32 v76, -|v76|, v82, v240
	v_fma_f32 v77, -|v77|, v83, v241
	v_exp_f32_e32 v84, v84
	v_exp_f32_e32 v85, v85
	v_ashrrev_i32_e32 v81, 31, v80
	v_pk_fma_f32 v[82:83], v[88:89], s[30:31], v[150:151] op_sel_hi:[1,0,0]
	s_nop 0
	v_pk_fma_f32 v[82:83], v[88:89], v[82:83], s[36:37] op_sel_hi:[1,1,0]
	v_lshlrev_b64 v[80:81], 11, v[80:81]
	v_pk_fma_f32 v[82:83], v[88:89], v[82:83], s[50:51] op_sel_hi:[1,1,0]
; __device__ __forceinline__ unsigned cvt_pk_bf16(float lo, float hi) { unsigned r; asm volatile("v_cvt_pk_bf16_f32 %0, %1, %2" : "=v"(r) : "v"(lo), "v"(hi)); return r; }
; __device__ __forceinline__ float sigmoid_f(float x) { return __builtin_amdgcn_rcpf(1.0f + __builtin_amdgcn_exp2f(-1.44269504f * x)); }
; __device__ __forceinline__ f32x2 gelu_pk(f32x2 v) {
;     const f32x2 av = __builtin_elementwise_abs(v), d = av * 0.2316418882f + 1.0f;
;     f32x2 t; t.x = __builtin_amdgcn_rcpf(d.x); t.y = __builtin_amdgcn_rcpf(d.y);
;     f32x2 q = t * 0.5307027145f + (-0.7265760135f); q = q * t + 0.7107068705f; q = q * t + (-0.142248368f); q = q * t + 0.127414796f; q = q * t;
;     const f32x2 s = (v * v) * (-0.72134752044f);
;     f32x2 e; e.x = __builtin_amdgcn_exp2f(s.x); e.y = __builtin_amdgcn_exp2f(s.y);
;     const f32x2 m = v * (q * e), r = v - m;
;     f32x2 o; o.x = v.x < 0.f ? m.x : r.x; o.y = v.y < 0.f ? m.y : r.y; return o;
; }
; __device__ __forceinline__ f32x4 gelu4(f32x4 v) { f32x2 a = gelu_pk((f32x2){v[0], v[1]}), b = gelu_pk((f32x2){v[2], v[3]}); return (f32x4){a.x, a.y, b.x, b.y}; }
; __device__ __forceinline__ f32x4 sigm4(f32x4 v) { return (f32x4){sigmoid_f(v[0]), sigmoid_f(v[1]), sigmoid_f(v[2]), sigmoid_f(v[3])}; }
; __device__ __forceinline__ f32x4 silu4(f32x4 v) { return v * sigm4(v); }
;     __device__ __forceinline__ void operator()(const f32x4 (&acc)[2][2][4][2], const pg8::Unit& u, int wr, int wc, int fr, int fq) const {
;     ...
;             bf16_t* base = PJ + T_P + 128 * pn + wc * 32 + 8 * fq;
; #pragma unroll
;             for (int ai = 0; ai < 2; ++ai)
; #pragma unroll
;                 for (int m = 0; m < 4; ++m) {
;                     bf16_t* rowp = base + (size_t)(row0 + ai * 128 + m * 16) * 1024;
;                     const f32x4 v0 = gelu4(acc[ai][0][m][0]) * silu4(acc[ai][1][m][0]), v1 = gelu4(acc[ai][0][m][1]) * silu4(acc[ai][1][m][1]);
;                     u32x4 w; w.x = cvt_pk_bf16(v0[0], v0[1]); w.y = cvt_pk_bf16(v0[2], v0[3]); w.z = cvt_pk_bf16(v1[0], v1[1]); w.w = cvt_pk_bf16(v1[2], v1[3]);
;                     __builtin_nontemporal_store(w, (u32x4*)rowp);
	v_lshl_add_u64 v[80:81], v[152:153], 0, v[80:81]
	v_pk_fma_f32 v[82:83], v[88:89], v[82:83], s[72:73] op_sel_hi:[1,1,0]
	s_nop 0
	v_pk_mul_f32 v[82:83], v[88:89], v[82:83]
	s_nop 0
	v_pk_mul_f32 v[82:83], v[84:85], v[82:83]
	s_nop 0
	v_max_f32_e32 v240, 0, v78
	v_max_f32_e32 v241, 0, v79
	v_fma_f32 v78, -|v78|, v82, v240
	v_fma_f32 v79, -|v79|, v83, v241
	s_nop 0
	v_mul_f32_e32 v84, 0xbfb8aa3b, v73
	v_mul_f32_e32 v82, 0xbfb8aa3b, v72
	v_exp_f32_e32 v84, v84
	v_exp_f32_e32 v82, v82
	s_nop 0
	v_add_f32_e32 v82, 1.0, v82
	s_nop 0
	v_add_f32_e32 v83, 1.0, v84
	v_mul_f32_e32 v84, 0xbfb8aa3b, v74
	v_mul_f32_e32 v85, 0xbfb8aa3b, v75
	v_exp_f32_e32 v84, v84
	v_exp_f32_e32 v85, v85
	v_rcp_f32_e32 v82, v82
	v_rcp_f32_e32 v83, v83
	v_add_f32_e32 v84, 1.0, v84
	v_add_f32_e32 v85, 1.0, v85
	v_rcp_f32_e32 v84, v84
	v_rcp_f32_e32 v85, v85
	v_pk_mul_f32 v[72:73], v[72:73], v[82:83]
	v_fma_f32 v82, |v68|, s28, 1.0
	v_fma_f32 v83, |v69|, s28, 1.0
	v_pk_mul_f32 v[74:75], v[74:75], v[84:85]
	v_rcp_f32_e32 v82, v82
	v_rcp_f32_e32 v83, v83
	v_pk_mul_f32 v[74:75], v[78:79], v[74:75]
	v_pk_mul_f32 v[78:79], v[68:69], v[68:69]
	v_pk_mul_f32 v[72:73], v[76:77], v[72:73]
	v_pk_fma_f32 v[76:77], v[82:83], s[30:31], v[150:151] op_sel_hi:[1,0,0]
	v_pk_mul_f32 v[78:79], v[78:79], s[74:75] op_sel_hi:[1,0]
	v_pk_fma_f32 v[76:77], v[82:83], v[76:77], s[36:37] op_sel_hi:[1,1,0]
	v_exp_f32_e32 v78, v78
	v_exp_f32_e32 v79, v79
	v_pk_fma_f32 v[76:77], v[82:83], v[76:77], s[50:51] op_sel_hi:[1,1,0]
	s_nop 0
	v_pk_fma_f32 v[76:77], v[82:83], v[76:77], s[72:73] op_sel_hi:[1,1,0]
	v_fma_f32 v84, |v70|, s28, 1.0
	v_fma_f32 v85, |v71|, s28, 1.0
	v_pk_mul_f32 v[76:77], v[82:83], v[76:77]
	v_rcp_f32_e32 v84, v84
	v_rcp_f32_e32 v85, v85
	v_pk_mul_f32 v[76:77], v[78:79], v[76:77]
	v_max_f32_e32 v240, 0, v68
	v_max_f32_e32 v241, 0, v69
	v_fma_f32 v68, -|v68|, v76, v240
	v_fma_f32 v69, -|v69|, v77, v241
	v_pk_mul_f32 v[82:83], v[70:71], v[70:71]
	s_nop 1
	v_pk_fma_f32 v[76:77], v[84:85], s[30:31], v[150:151] op_sel_hi:[1,0,0]
	v_pk_mul_f32 v[78:79], v[82:83], s[74:75] op_sel_hi:[1,0]
	v_pk_fma_f32 v[76:77], v[84:85], v[76:77], s[36:37] op_sel_hi:[1,1,0]
	v_exp_f32_e32 v78, v78
	v_exp_f32_e32 v79, v79
	v_pk_fma_f32 v[76:77], v[84:85], v[76:77], s[50:51] op_sel_hi:[1,1,0]
	v_mul_f32_e32 v82, 0xbfb8aa3b, v64
	v_pk_fma_f32 v[76:77], v[84:85], v[76:77], s[72:73] op_sel_hi:[1,1,0]
	v_exp_f32_e32 v82, v82
	v_mul_f32_e32 v83, 0xbfb8aa3b, v65
	v_pk_mul_f32 v[76:77], v[84:85], v[76:77]
	v_exp_f32_e32 v83, v83
	v_pk_mul_f32 v[76:77], v[78:79], v[76:77]
	v_max_f32_e32 v240, 0, v70
	v_max_f32_e32 v241, 0, v71
	v_fma_f32 v70, -|v70|, v76, v240
	v_fma_f32 v71, -|v71|, v77, v241
	s_nop 0
	v_add_f32_e32 v76, 1.0, v82
	v_mul_f32_e32 v78, 0xbfb8aa3b, v66
	v_rcp_f32_e32 v82, v76
	v_add_f32_e32 v76, 1.0, v83
	v_exp_f32_e32 v78, v78
	v_mul_f32_e32 v83, 0xbfb8aa3b, v67
	v_exp_f32_e32 v85, v83
	v_rcp_f32_e32 v83, v76
	v_add_f32_e32 v76, 1.0, v78
	v_rcp_f32_e32 v84, v76
	v_add_f32_e32 v76, 1.0, v85
	v_rcp_f32_e32 v85, v76
	v_pk_mul_f32 v[64:65], v[64:65], v[82:83]
	v_pk_mul_f32 v[66:67], v[66:67], v[84:85]
	s_nop 0
	v_pk_mul_f32 v[70:71], v[70:71], v[66:67]
	v_pk_mul_f32 v[66:67], v[68:69], v[64:65]
	v_fma_f32 v68, |v60|, s28, 1.0
	v_fma_f32 v69, |v61|, s28, 1.0
	v_cvt_pk_bf16_f32 v64, v72, v73
	v_cvt_pk_bf16_f32 v65, v74, v75
	v_cvt_pk_bf16_f32 v66, v66, v67
	v_cvt_pk_bf16_f32 v67, v70, v71
	global_store_dwordx4 v[80:81], v[64:67], off nt
	v_rcp_f32_e32 v68, v68
	v_rcp_f32_e32 v69, v69
	v_pk_mul_f32 v[66:67], v[60:61], v[60:61]
	s_nop 0
	v_pk_mul_f32 v[66:67], v[66:67], s[74:75] op_sel_hi:[1,0]
	v_pk_fma_f32 v[64:65], v[68:69], s[30:31], v[150:151] op_sel_hi:[1,0,0]
	v_exp_f32_e32 v66, v66
	v_pk_fma_f32 v[64:65], v[68:69], v[64:65], s[36:37] op_sel_hi:[1,1,0]
	v_exp_f32_e32 v67, v67
	v_pk_fma_f32 v[64:65], v[68:69], v[64:65], s[50:51] op_sel_hi:[1,1,0]
	s_nop 0
	v_pk_fma_f32 v[64:65], v[68:69], v[64:65], s[72:73] op_sel_hi:[1,1,0]
	v_fma_f32 v70, |v62|, s28, 1.0
	v_fma_f32 v71, |v63|, s28, 1.0
	v_pk_mul_f32 v[64:65], v[68:69], v[64:65]
	v_rcp_f32_e32 v70, v70
	v_rcp_f32_e32 v71, v71
	v_pk_mul_f32 v[64:65], v[66:67], v[64:65]
	v_max_f32_e32 v240, 0, v60
	v_max_f32_e32 v241, 0, v61
	v_fma_f32 v60, -|v60|, v64, v240
	v_fma_f32 v61, -|v61|, v65, v241
	v_pk_mul_f32 v[68:69], v[62:63], v[62:63]
	s_nop 1
	v_pk_fma_f32 v[64:65], v[70:71], s[30:31], v[150:151] op_sel_hi:[1,0,0]
	v_pk_mul_f32 v[66:67], v[68:69], s[74:75] op_sel_hi:[1,0]
	v_pk_fma_f32 v[64:65], v[70:71], v[64:65], s[36:37] op_sel_hi:[1,1,0]
	v_exp_f32_e32 v66, v66
	v_exp_f32_e32 v67, v67
	v_pk_fma_f32 v[64:65], v[70:71], v[64:65], s[50:51] op_sel_hi:[1,1,0]
	s_nop 0
	v_pk_fma_f32 v[64:65], v[70:71], v[64:65], s[72:73] op_sel_hi:[1,1,0]
	s_nop 0
	v_pk_mul_f32 v[64:65], v[70:71], v[64:65]
	s_nop 0
	v_pk_mul_f32 v[64:65], v[66:67], v[64:65]
	s_nop 0
	v_max_f32_e32 v240, 0, v62
	v_max_f32_e32 v241, 0, v63
	v_fma_f32 v62, -|v62|, v64, v240
	v_fma_f32 v63, -|v63|, v65, v241
	s_nop 0
	v_mul_f32_e32 v66, 0xbfb8aa3b, v57
	v_mul_f32_e32 v64, 0xbfb8aa3b, v56
	v_exp_f32_e32 v66, v66
	v_exp_f32_e32 v64, v64
	s_nop 0
	v_add_f32_e32 v64, 1.0, v64
	s_nop 0
	v_add_f32_e32 v65, 1.0, v66
	v_mul_f32_e32 v66, 0xbfb8aa3b, v58
	v_mul_f32_e32 v67, 0xbfb8aa3b, v59
	v_exp_f32_e32 v66, v66
	v_exp_f32_e32 v67, v67
	v_rcp_f32_e32 v64, v64
	v_rcp_f32_e32 v65, v65
	v_add_f32_e32 v66, 1.0, v66
	v_add_f32_e32 v67, 1.0, v67
	v_rcp_f32_e32 v66, v66
	v_rcp_f32_e32 v67, v67
	v_pk_mul_f32 v[56:57], v[56:57], v[64:65]
	v_fma_f32 v64, |v52|, s28, 1.0
	v_fma_f32 v65, |v53|, s28, 1.0
	v_pk_mul_f32 v[58:59], v[58:59], v[66:67]
	v_rcp_f32_e32 v64, v64
	v_rcp_f32_e32 v65, v65
; __device__ __forceinline__ unsigned cvt_pk_bf16(float lo, float hi) { unsigned r; asm volatile("v_cvt_pk_bf16_f32 %0, %1, %2" : "=v"(r) : "v"(lo), "v"(hi)); return r; }
; __device__ __forceinline__ float sigmoid_f(float x) { return __builtin_amdgcn_rcpf(1.0f + __builtin_amdgcn_exp2f(-1.44269504f * x)); }
; __device__ __forceinline__ f32x2 gelu_pk(f32x2 v) {
;     const f32x2 av = __builtin_elementwise_abs(v), d = av * 0.2316418882f + 1.0f;
;     f32x2 t; t.x = __builtin_amdgcn_rcpf(d.x); t.y = __builtin_amdgcn_rcpf(d.y);
;     f32x2 q = t * 0.5307027145f + (-0.7265760135f); q = q * t + 0.7107068705f; q = q * t + (-0.142248368f); q = q * t + 0.127414796f; q = q * t;
;     const f32x2 s = (v * v) * (-0.72134752044f);
;     f32x2 e; e.x = __builtin_amdgcn_exp2f(s.x); e.y = __builtin_amdgcn_exp2f(s.y);
;     const f32x2 m = v * (q * e), r = v - m;
;     f32x2 o; o.x = v.x < 0.f ? m.x : r.x; o.y = v.y < 0.f ? m.y : r.y; return o;
; }
; __device__ __forceinline__ f32x4 gelu4(f32x4 v) { f32x2 a = gelu_pk((f32x2){v[0], v[1]}), b = gelu_pk((f32x2){v[2], v[3]}); return (f32x4){a.x, a.y, b.x, b.y}; }
; __device__ __forceinline__ f32x4 sigm4(f32x4 v) { return (f32x4){sigmoid_f(v[0]), sigmoid_f(v[1]), sigmoid_f(v[2]), sigmoid_f(v[3])}; }
; __device__ __forceinline__ f32x4 silu4(f32x4 v) { return v * sigm4(v); }
;     __device__ __forceinline__ void operator()(const f32x4 (&acc)[2][2][4][2], const pg8::Unit& u, int wr, int wc, int fr, int fq) const {
;     ...
;             bf16_t* base = PJ + T_P + 128 * pn + wc * 32 + 8 * fq;
; #pragma unroll
;             for (int ai = 0; ai < 2; ++ai)
; #pragma unroll
;                 for (int m = 0; m < 4; ++m) {
;                     bf16_t* rowp = base + (size_t)(row0 + ai * 128 + m * 16) * 1024;
;                     const f32x4 v0 = gelu4(acc[ai][0][m][0]) * silu4(acc[ai][1][m][0]), v1 = gelu4(acc[ai][0][m][1]) * silu4(acc[ai][1][m][1]);
;                     u32x4 w; w.x = cvt_pk_bf16(v0[0], v0[1]); w.y = cvt_pk_bf16(v0[2], v0[3]); w.z = cvt_pk_bf16(v1[0], v1[1]); w.w = cvt_pk_bf16(v1[2], v1[3]);
;                     __builtin_nontemporal_store(w, (u32x4*)rowp);
	v_pk_mul_f32 v[58:59], v[62:63], v[58:59]
	v_pk_mul_f32 v[62:63], v[52:53], v[52:53]
	v_pk_mul_f32 v[56:57], v[60:61], v[56:57]
	v_pk_fma_f32 v[60:61], v[64:65], s[30:31], v[150:151] op_sel_hi:[1,0,0]
	v_pk_mul_f32 v[62:63], v[62:63], s[74:75] op_sel_hi:[1,0]
	v_pk_fma_f32 v[60:61], v[64:65], v[60:61], s[36:37] op_sel_hi:[1,1,0]
	v_exp_f32_e32 v62, v62
	v_exp_f32_e32 v63, v63
	v_pk_fma_f32 v[60:61], v[64:65], v[60:61], s[50:51] op_sel_hi:[1,1,0]
	s_nop 0
	v_pk_fma_f32 v[60:61], v[64:65], v[60:61], s[72:73] op_sel_hi:[1,1,0]
	v_fma_f32 v66, |v54|, s28, 1.0
	v_fma_f32 v67, |v55|, s28, 1.0
	v_pk_mul_f32 v[60:61], v[64:65], v[60:61]
	v_rcp_f32_e32 v66, v66
	v_rcp_f32_e32 v67, v67
	v_pk_mul_f32 v[60:61], v[62:63], v[60:61]
	v_max_f32_e32 v240, 0, v52
	v_max_f32_e32 v241, 0, v53
	v_fma_f32 v52, -|v52|, v60, v240
	v_fma_f32 v53, -|v53|, v61, v241
	v_pk_mul_f32 v[64:65], v[54:55], v[54:55]
	s_nop 1
	v_pk_fma_f32 v[60:61], v[66:67], s[30:31], v[150:151] op_sel_hi:[1,0,0]
	v_pk_mul_f32 v[62:63], v[64:65], s[74:75] op_sel_hi:[1,0]
	v_pk_fma_f32 v[60:61], v[66:67], v[60:61], s[36:37] op_sel_hi:[1,1,0]
	v_exp_f32_e32 v62, v62
	v_exp_f32_e32 v63, v63
	v_pk_fma_f32 v[60:61], v[66:67], v[60:61], s[50:51] op_sel_hi:[1,1,0]
	v_mul_f32_e32 v64, 0xbfb8aa3b, v48
	v_pk_fma_f32 v[60:61], v[66:67], v[60:61], s[72:73] op_sel_hi:[1,1,0]
	v_exp_f32_e32 v64, v64
	v_mul_f32_e32 v65, 0xbfb8aa3b, v49
	v_pk_mul_f32 v[60:61], v[66:67], v[60:61]
	v_exp_f32_e32 v65, v65
	v_pk_mul_f32 v[60:61], v[62:63], v[60:61]
	v_max_f32_e32 v240, 0, v54
	v_max_f32_e32 v241, 0, v55
	v_fma_f32 v54, -|v54|, v60, v240
	v_fma_f32 v55, -|v55|, v61, v241
	s_nop 0
	v_add_f32_e32 v60, 1.0, v64
	v_mul_f32_e32 v62, 0xbfb8aa3b, v50
	v_rcp_f32_e32 v64, v60
	v_add_f32_e32 v60, 1.0, v65
	v_exp_f32_e32 v62, v62
	v_mul_f32_e32 v65, 0xbfb8aa3b, v51
	v_exp_f32_e32 v67, v65
	v_rcp_f32_e32 v65, v60
	v_add_f32_e32 v60, 1.0, v62
	v_rcp_f32_e32 v66, v60
	v_add_f32_e32 v60, 1.0, v67
	v_rcp_f32_e32 v67, v60
	v_pk_mul_f32 v[48:49], v[48:49], v[64:65]
	v_pk_mul_f32 v[50:51], v[50:51], v[66:67]
	s_nop 0
	v_pk_mul_f32 v[54:55], v[54:55], v[50:51]
	v_pk_mul_f32 v[50:51], v[52:53], v[48:49]
	v_fma_f32 v52, |v44|, s28, 1.0
	v_fma_f32 v53, |v45|, s28, 1.0
	v_cvt_pk_bf16_f32 v48, v56, v57
	v_cvt_pk_bf16_f32 v49, v58, v59
	v_cvt_pk_bf16_f32 v50, v50, v51
	v_cvt_pk_bf16_f32 v51, v54, v55
	v_add_co_u32_e32 v54, vcc, s6, v148
	v_rcp_f32_e32 v52, v52
	v_rcp_f32_e32 v53, v53
	v_addc_co_u32_e32 v55, vcc, 0, v149, vcc
	global_store_dwordx4 v[54:55], v[48:51], off nt
	s_nop 1
	v_pk_mul_f32 v[50:51], v[44:45], v[44:45]
	s_nop 0
	v_pk_fma_f32 v[48:49], v[52:53], s[30:31], v[150:151] op_sel_hi:[1,0,0]
	v_pk_mul_f32 v[50:51], v[50:51], s[74:75] op_sel_hi:[1,0]
	v_pk_fma_f32 v[48:49], v[52:53], v[48:49], s[36:37] op_sel_hi:[1,1,0]
	v_exp_f32_e32 v50, v50
	v_exp_f32_e32 v51, v51
	v_pk_fma_f32 v[48:49], v[52:53], v[48:49], s[50:51] op_sel_hi:[1,1,0]
	v_fma_f32 v54, |v46|, s28, 1.0
	v_fma_f32 v55, |v47|, s28, 1.0
	v_pk_fma_f32 v[48:49], v[52:53], v[48:49], s[72:73] op_sel_hi:[1,1,0]
	v_rcp_f32_e32 v54, v54
	v_pk_mul_f32 v[48:49], v[52:53], v[48:49]
	v_rcp_f32_e32 v55, v55
	v_pk_mul_f32 v[48:49], v[50:51], v[48:49]
	v_max_f32_e32 v240, 0, v44
	v_max_f32_e32 v241, 0, v45
	v_fma_f32 v44, -|v44|, v48, v240
	v_fma_f32 v45, -|v45|, v49, v241
	v_pk_mul_f32 v[52:53], v[46:47], v[46:47]
	s_mov_b32 s6, 0x48000
	s_nop 0
	v_pk_fma_f32 v[48:49], v[54:55], s[30:31], v[150:151] op_sel_hi:[1,0,0]
	v_pk_mul_f32 v[50:51], v[52:53], s[74:75] op_sel_hi:[1,0]
	v_pk_fma_f32 v[48:49], v[54:55], v[48:49], s[36:37] op_sel_hi:[1,1,0]
	v_exp_f32_e32 v50, v50
	v_exp_f32_e32 v51, v51
	v_pk_fma_f32 v[48:49], v[54:55], v[48:49], s[50:51] op_sel_hi:[1,1,0]
	s_nop 0
	v_pk_fma_f32 v[48:49], v[54:55], v[48:49], s[72:73] op_sel_hi:[1,1,0]
	s_nop 0
	v_pk_mul_f32 v[48:49], v[54:55], v[48:49]
	s_nop 0
	v_pk_mul_f32 v[48:49], v[50:51], v[48:49]
	s_nop 0
	v_max_f32_e32 v240, 0, v46
	v_max_f32_e32 v241, 0, v47
	v_fma_f32 v46, -|v46|, v48, v240
	v_fma_f32 v47, -|v47|, v49, v241
	s_nop 0
	v_mul_f32_e32 v50, 0xbfb8aa3b, v41
	v_mul_f32_e32 v48, 0xbfb8aa3b, v40
	v_exp_f32_e32 v50, v50
	v_exp_f32_e32 v48, v48
	s_nop 0
	v_add_f32_e32 v48, 1.0, v48
	s_nop 0
	v_add_f32_e32 v49, 1.0, v50
	v_mul_f32_e32 v50, 0xbfb8aa3b, v42
	v_mul_f32_e32 v51, 0xbfb8aa3b, v43
	v_exp_f32_e32 v50, v50
	v_exp_f32_e32 v51, v51
	v_rcp_f32_e32 v48, v48
	v_rcp_f32_e32 v49, v49
	v_add_f32_e32 v50, 1.0, v50
	v_add_f32_e32 v51, 1.0, v51
	v_rcp_f32_e32 v50, v50
	v_rcp_f32_e32 v51, v51
	v_pk_mul_f32 v[40:41], v[40:41], v[48:49]
	v_fma_f32 v48, |v36|, s28, 1.0
	v_fma_f32 v49, |v37|, s28, 1.0
	v_pk_mul_f32 v[42:43], v[42:43], v[50:51]
	v_rcp_f32_e32 v48, v48
	v_rcp_f32_e32 v49, v49
	v_pk_mul_f32 v[42:43], v[46:47], v[42:43]
	v_pk_mul_f32 v[46:47], v[36:37], v[36:37]
	v_pk_mul_f32 v[40:41], v[44:45], v[40:41]
	v_pk_fma_f32 v[44:45], v[48:49], s[30:31], v[150:151] op_sel_hi:[1,0,0]
	v_pk_mul_f32 v[46:47], v[46:47], s[74:75] op_sel_hi:[1,0]
	v_pk_fma_f32 v[44:45], v[48:49], v[44:45], s[36:37] op_sel_hi:[1,1,0]
	v_exp_f32_e32 v46, v46
	v_exp_f32_e32 v47, v47
	v_pk_fma_f32 v[44:45], v[48:49], v[44:45], s[50:51] op_sel_hi:[1,1,0]
	s_nop 0
	v_pk_fma_f32 v[44:45], v[48:49], v[44:45], s[72:73] op_sel_hi:[1,1,0]
	v_fma_f32 v50, |v38|, s28, 1.0
	v_fma_f32 v51, |v39|, s28, 1.0
	v_pk_mul_f32 v[44:45], v[48:49], v[44:45]
	v_rcp_f32_e32 v50, v50
	v_rcp_f32_e32 v51, v51
	v_pk_mul_f32 v[44:45], v[46:47], v[44:45]
	v_max_f32_e32 v240, 0, v36
	v_max_f32_e32 v241, 0, v37
	v_fma_f32 v36, -|v36|, v44, v240
	v_fma_f32 v37, -|v37|, v45, v241
	v_pk_mul_f32 v[48:49], v[38:39], v[38:39]
	s_nop 1
	v_pk_fma_f32 v[44:45], v[50:51], s[30:31], v[150:151] op_sel_hi:[1,0,0]
; __device__ __forceinline__ unsigned cvt_pk_bf16(float lo, float hi) { unsigned r; asm volatile("v_cvt_pk_bf16_f32 %0, %1, %2" : "=v"(r) : "v"(lo), "v"(hi)); return r; }
; __device__ __forceinline__ float sigmoid_f(float x) { return __builtin_amdgcn_rcpf(1.0f + __builtin_amdgcn_exp2f(-1.44269504f * x)); }
; __device__ __forceinline__ f32x2 gelu_pk(f32x2 v) {
;     const f32x2 av = __builtin_elementwise_abs(v), d = av * 0.2316418882f + 1.0f;
;     f32x2 t; t.x = __builtin_amdgcn_rcpf(d.x); t.y = __builtin_amdgcn_rcpf(d.y);
;     f32x2 q = t * 0.5307027145f + (-0.7265760135f); q = q * t + 0.7107068705f; q = q * t + (-0.142248368f); q = q * t + 0.127414796f; q = q * t;
;     const f32x2 s = (v * v) * (-0.72134752044f);
;     f32x2 e; e.x = __builtin_amdgcn_exp2f(s.x); e.y = __builtin_amdgcn_exp2f(s.y);
;     const f32x2 m = v * (q * e), r = v - m;
;     f32x2 o; o.x = v.x < 0.f ? m.x : r.x; o.y = v.y < 0.f ? m.y : r.y; return o;
; }
; __device__ __forceinline__ f32x4 gelu4(f32x4 v) { f32x2 a = gelu_pk((f32x2){v[0], v[1]}), b = gelu_pk((f32x2){v[2], v[3]}); return (f32x4){a.x, a.y, b.x, b.y}; }
; __device__ __forceinline__ f32x4 sigm4(f32x4 v) { return (f32x4){sigmoid_f(v[0]), sigmoid_f(v[1]), sigmoid_f(v[2]), sigmoid_f(v[3])}; }
; __device__ __forceinline__ f32x4 silu4(f32x4 v) { return v * sigm4(v); }
;     __device__ __forceinline__ void operator()(const f32x4 (&acc)[2][2][4][2], const pg8::Unit& u, int wr, int wc, int fr, int fq) const {
;     ...
;             bf16_t* base = PJ + T_P + 128 * pn + wc * 32 + 8 * fq;
; #pragma unroll
;             for (int ai = 0; ai < 2; ++ai)
; #pragma unroll
;                 for (int m = 0; m < 4; ++m) {
;                     bf16_t* rowp = base + (size_t)(row0 + ai * 128 + m * 16) * 1024;
;                     const f32x4 v0 = gelu4(acc[ai][0][m][0]) * silu4(acc[ai][1][m][0]), v1 = gelu4(acc[ai][0][m][1]) * silu4(acc[ai][1][m][1]);
;                     u32x4 w; w.x = cvt_pk_bf16(v0[0], v0[1]); w.y = cvt_pk_bf16(v0[2], v0[3]); w.z = cvt_pk_bf16(v1[0], v1[1]); w.w = cvt_pk_bf16(v1[2], v1[3]);
;                     __builtin_nontemporal_store(w, (u32x4*)rowp);
	v_pk_mul_f32 v[46:47], v[48:49], s[74:75] op_sel_hi:[1,0]
	v_pk_fma_f32 v[44:45], v[50:51], v[44:45], s[36:37] op_sel_hi:[1,1,0]
	v_exp_f32_e32 v46, v46
	v_exp_f32_e32 v47, v47
	v_pk_fma_f32 v[44:45], v[50:51], v[44:45], s[50:51] op_sel_hi:[1,1,0]
	v_mul_f32_e32 v48, 0xbfb8aa3b, v32
	v_pk_fma_f32 v[44:45], v[50:51], v[44:45], s[72:73] op_sel_hi:[1,1,0]
	v_exp_f32_e32 v48, v48
	v_mul_f32_e32 v49, 0xbfb8aa3b, v33
	v_pk_mul_f32 v[44:45], v[50:51], v[44:45]
	v_exp_f32_e32 v49, v49
	v_pk_mul_f32 v[44:45], v[46:47], v[44:45]
	v_max_f32_e32 v240, 0, v38
	v_max_f32_e32 v241, 0, v39
	v_fma_f32 v38, -|v38|, v44, v240
	v_fma_f32 v39, -|v39|, v45, v241
	s_nop 0
	v_add_f32_e32 v44, 1.0, v48
	v_mul_f32_e32 v46, 0xbfb8aa3b, v34
	v_rcp_f32_e32 v48, v44
	v_add_f32_e32 v44, 1.0, v49
	v_exp_f32_e32 v46, v46
	v_mul_f32_e32 v49, 0xbfb8aa3b, v35
	v_exp_f32_e32 v51, v49
	v_rcp_f32_e32 v49, v44
	v_add_f32_e32 v44, 1.0, v46
	v_rcp_f32_e32 v50, v44
	v_add_f32_e32 v44, 1.0, v51
	v_rcp_f32_e32 v51, v44
	v_pk_mul_f32 v[32:33], v[32:33], v[48:49]
	v_pk_mul_f32 v[34:35], v[34:35], v[50:51]
	s_nop 0
	v_pk_mul_f32 v[38:39], v[38:39], v[34:35]
	v_pk_mul_f32 v[34:35], v[36:37], v[32:33]
	v_fma_f32 v36, |v28|, s28, 1.0
	v_fma_f32 v37, |v29|, s28, 1.0
	v_cvt_pk_bf16_f32 v32, v40, v41
	v_cvt_pk_bf16_f32 v33, v42, v43
	v_cvt_pk_bf16_f32 v34, v34, v35
	v_cvt_pk_bf16_f32 v35, v38, v39
	v_add_co_u32_e32 v38, vcc, s6, v148
	v_rcp_f32_e32 v36, v36
	v_rcp_f32_e32 v37, v37
	v_addc_co_u32_e32 v39, vcc, 0, v149, vcc
	global_store_dwordx4 v[38:39], v[32:35], off nt
	s_nop 1
	v_pk_mul_f32 v[34:35], v[28:29], v[28:29]
	s_nop 0
	v_pk_fma_f32 v[32:33], v[36:37], s[30:31], v[150:151] op_sel_hi:[1,0,0]
	v_pk_mul_f32 v[34:35], v[34:35], s[74:75] op_sel_hi:[1,0]
	v_pk_fma_f32 v[32:33], v[36:37], v[32:33], s[36:37] op_sel_hi:[1,1,0]
	v_exp_f32_e32 v34, v34
	v_exp_f32_e32 v35, v35
	v_pk_fma_f32 v[32:33], v[36:37], v[32:33], s[50:51] op_sel_hi:[1,1,0]
	v_fma_f32 v38, |v30|, s28, 1.0
	v_fma_f32 v39, |v31|, s28, 1.0
	v_pk_fma_f32 v[32:33], v[36:37], v[32:33], s[72:73] op_sel_hi:[1,1,0]
	v_rcp_f32_e32 v38, v38
	v_pk_mul_f32 v[32:33], v[36:37], v[32:33]
	v_rcp_f32_e32 v39, v39
	v_pk_mul_f32 v[32:33], v[34:35], v[32:33]
	v_max_f32_e32 v240, 0, v28
	v_max_f32_e32 v241, 0, v29
	v_fma_f32 v28, -|v28|, v32, v240
	v_fma_f32 v29, -|v29|, v33, v241
	v_pk_mul_f32 v[36:37], v[30:31], v[30:31]
	s_mov_b32 s6, 0x50000
	s_nop 0
	v_pk_fma_f32 v[32:33], v[38:39], s[30:31], v[150:151] op_sel_hi:[1,0,0]
	v_pk_mul_f32 v[34:35], v[36:37], s[74:75] op_sel_hi:[1,0]
	v_pk_fma_f32 v[32:33], v[38:39], v[32:33], s[36:37] op_sel_hi:[1,1,0]
	v_exp_f32_e32 v34, v34
	v_exp_f32_e32 v35, v35
	v_pk_fma_f32 v[32:33], v[38:39], v[32:33], s[50:51] op_sel_hi:[1,1,0]
	s_nop 0
	v_pk_fma_f32 v[32:33], v[38:39], v[32:33], s[72:73] op_sel_hi:[1,1,0]
	s_nop 0
	v_pk_mul_f32 v[32:33], v[38:39], v[32:33]
	s_nop 0
	v_pk_mul_f32 v[32:33], v[34:35], v[32:33]
	s_nop 0
	v_max_f32_e32 v240, 0, v30
	v_max_f32_e32 v241, 0, v31
	v_fma_f32 v30, -|v30|, v32, v240
	v_fma_f32 v31, -|v31|, v33, v241
	s_nop 0
	v_mul_f32_e32 v34, 0xbfb8aa3b, v25
	v_mul_f32_e32 v32, 0xbfb8aa3b, v24
	v_exp_f32_e32 v34, v34
	v_exp_f32_e32 v32, v32
	s_nop 0
	v_add_f32_e32 v32, 1.0, v32
	s_nop 0
	v_add_f32_e32 v33, 1.0, v34
	v_mul_f32_e32 v34, 0xbfb8aa3b, v26
	v_mul_f32_e32 v35, 0xbfb8aa3b, v27
	v_exp_f32_e32 v34, v34
	v_exp_f32_e32 v35, v35
	v_rcp_f32_e32 v32, v32
	v_rcp_f32_e32 v33, v33
	v_add_f32_e32 v34, 1.0, v34
	v_add_f32_e32 v35, 1.0, v35
	v_rcp_f32_e32 v34, v34
	v_rcp_f32_e32 v35, v35
	v_pk_mul_f32 v[24:25], v[24:25], v[32:33]
	v_fma_f32 v32, |v20|, s28, 1.0
	v_fma_f32 v33, |v21|, s28, 1.0
	v_pk_mul_f32 v[26:27], v[26:27], v[34:35]
	v_rcp_f32_e32 v32, v32
	v_rcp_f32_e32 v33, v33
	v_pk_mul_f32 v[26:27], v[30:31], v[26:27]
	v_pk_mul_f32 v[30:31], v[20:21], v[20:21]
	v_pk_mul_f32 v[24:25], v[28:29], v[24:25]
	v_pk_fma_f32 v[28:29], v[32:33], s[30:31], v[150:151] op_sel_hi:[1,0,0]
	v_pk_mul_f32 v[30:31], v[30:31], s[74:75] op_sel_hi:[1,0]
	v_pk_fma_f32 v[28:29], v[32:33], v[28:29], s[36:37] op_sel_hi:[1,1,0]
	v_exp_f32_e32 v30, v30
	v_exp_f32_e32 v31, v31
	v_pk_fma_f32 v[28:29], v[32:33], v[28:29], s[50:51] op_sel_hi:[1,1,0]
	s_nop 0
	v_pk_fma_f32 v[28:29], v[32:33], v[28:29], s[72:73] op_sel_hi:[1,1,0]
	v_fma_f32 v34, |v22|, s28, 1.0
	v_fma_f32 v35, |v23|, s28, 1.0
	v_pk_mul_f32 v[28:29], v[32:33], v[28:29]
	v_rcp_f32_e32 v34, v34
	v_rcp_f32_e32 v35, v35
	v_pk_mul_f32 v[28:29], v[30:31], v[28:29]
	v_max_f32_e32 v240, 0, v20
	v_max_f32_e32 v241, 0, v21
	v_fma_f32 v20, -|v20|, v28, v240
	v_fma_f32 v21, -|v21|, v29, v241
	v_pk_mul_f32 v[32:33], v[22:23], v[22:23]
	s_nop 1
	v_pk_fma_f32 v[28:29], v[34:35], s[30:31], v[150:151] op_sel_hi:[1,0,0]
	v_pk_mul_f32 v[30:31], v[32:33], s[74:75] op_sel_hi:[1,0]
	v_pk_fma_f32 v[28:29], v[34:35], v[28:29], s[36:37] op_sel_hi:[1,1,0]
	v_exp_f32_e32 v30, v30
	v_exp_f32_e32 v31, v31
	v_pk_fma_f32 v[28:29], v[34:35], v[28:29], s[50:51] op_sel_hi:[1,1,0]
	v_mul_f32_e32 v32, 0xbfb8aa3b, v16
	v_pk_fma_f32 v[28:29], v[34:35], v[28:29], s[72:73] op_sel_hi:[1,1,0]
	v_exp_f32_e32 v32, v32
	v_mul_f32_e32 v33, 0xbfb8aa3b, v17
	v_pk_mul_f32 v[28:29], v[34:35], v[28:29]
	v_exp_f32_e32 v33, v33
	v_pk_mul_f32 v[28:29], v[30:31], v[28:29]
	v_max_f32_e32 v240, 0, v22
	v_max_f32_e32 v241, 0, v23
	v_fma_f32 v22, -|v22|, v28, v240
	v_fma_f32 v23, -|v23|, v29, v241
	s_nop 0
	v_add_f32_e32 v28, 1.0, v32
	v_mul_f32_e32 v30, 0xbfb8aa3b, v18
; __device__ __forceinline__ unsigned cvt_pk_bf16(float lo, float hi) { unsigned r; asm volatile("v_cvt_pk_bf16_f32 %0, %1, %2" : "=v"(r) : "v"(lo), "v"(hi)); return r; }
; __device__ __forceinline__ float sigmoid_f(float x) { return __builtin_amdgcn_rcpf(1.0f + __builtin_amdgcn_exp2f(-1.44269504f * x)); }
; __device__ __forceinline__ f32x2 gelu_pk(f32x2 v) {
;     const f32x2 av = __builtin_elementwise_abs(v), d = av * 0.2316418882f + 1.0f;
;     f32x2 t; t.x = __builtin_amdgcn_rcpf(d.x); t.y = __builtin_amdgcn_rcpf(d.y);
;     f32x2 q = t * 0.5307027145f + (-0.7265760135f); q = q * t + 0.7107068705f; q = q * t + (-0.142248368f); q = q * t + 0.127414796f; q = q * t;
;     const f32x2 s = (v * v) * (-0.72134752044f);
;     f32x2 e; e.x = __builtin_amdgcn_exp2f(s.x); e.y = __builtin_amdgcn_exp2f(s.y);
;     const f32x2 m = v * (q * e), r = v - m;
;     f32x2 o; o.x = v.x < 0.f ? m.x : r.x; o.y = v.y < 0.f ? m.y : r.y; return o;
; }
; __device__ __forceinline__ f32x4 gelu4(f32x4 v) { f32x2 a = gelu_pk((f32x2){v[0], v[1]}), b = gelu_pk((f32x2){v[2], v[3]}); return (f32x4){a.x, a.y, b.x, b.y}; }
; __device__ __forceinline__ f32x4 sigm4(f32x4 v) { return (f32x4){sigmoid_f(v[0]), sigmoid_f(v[1]), sigmoid_f(v[2]), sigmoid_f(v[3])}; }
; __device__ __forceinline__ f32x4 silu4(f32x4 v) { return v * sigm4(v); }
;     __device__ __forceinline__ void operator()(const f32x4 (&acc)[2][2][4][2], const pg8::Unit& u, int wr, int wc, int fr, int fq) const {
;     ...
;             bf16_t* base = PJ + T_P + 128 * pn + wc * 32 + 8 * fq;
; #pragma unroll
;             for (int ai = 0; ai < 2; ++ai)
; #pragma unroll
;                 for (int m = 0; m < 4; ++m) {
;                     bf16_t* rowp = base + (size_t)(row0 + ai * 128 + m * 16) * 1024;
;                     const f32x4 v0 = gelu4(acc[ai][0][m][0]) * silu4(acc[ai][1][m][0]), v1 = gelu4(acc[ai][0][m][1]) * silu4(acc[ai][1][m][1]);
;                     u32x4 w; w.x = cvt_pk_bf16(v0[0], v0[1]); w.y = cvt_pk_bf16(v0[2], v0[3]); w.z = cvt_pk_bf16(v1[0], v1[1]); w.w = cvt_pk_bf16(v1[2], v1[3]);
;                     __builtin_nontemporal_store(w, (u32x4*)rowp);
	v_rcp_f32_e32 v32, v28
	v_add_f32_e32 v28, 1.0, v33
	v_exp_f32_e32 v30, v30
	v_mul_f32_e32 v33, 0xbfb8aa3b, v19
	v_exp_f32_e32 v35, v33
	v_rcp_f32_e32 v33, v28
	v_add_f32_e32 v28, 1.0, v30
	v_rcp_f32_e32 v34, v28
	v_add_f32_e32 v28, 1.0, v35
	v_rcp_f32_e32 v35, v28
	v_pk_mul_f32 v[16:17], v[16:17], v[32:33]
	v_pk_mul_f32 v[18:19], v[18:19], v[34:35]
	s_nop 0
	v_pk_mul_f32 v[22:23], v[22:23], v[18:19]
	v_pk_mul_f32 v[18:19], v[20:21], v[16:17]
	v_fma_f32 v20, |v12|, s28, 1.0
	v_fma_f32 v21, |v13|, s28, 1.0
	v_cvt_pk_bf16_f32 v16, v24, v25
	v_cvt_pk_bf16_f32 v17, v26, v27
	v_cvt_pk_bf16_f32 v18, v18, v19
	v_cvt_pk_bf16_f32 v19, v22, v23
	v_add_co_u32_e32 v22, vcc, s6, v148
	v_rcp_f32_e32 v20, v20
	v_rcp_f32_e32 v21, v21
	v_addc_co_u32_e32 v23, vcc, 0, v149, vcc
	global_store_dwordx4 v[22:23], v[16:19], off nt
	s_nop 1
	v_pk_mul_f32 v[18:19], v[12:13], v[12:13]
	s_nop 0
	v_pk_fma_f32 v[16:17], v[20:21], s[30:31], v[150:151] op_sel_hi:[1,0,0]
	v_pk_mul_f32 v[18:19], v[18:19], s[74:75] op_sel_hi:[1,0]
	v_pk_fma_f32 v[16:17], v[20:21], v[16:17], s[36:37] op_sel_hi:[1,1,0]
	v_exp_f32_e32 v18, v18
	v_exp_f32_e32 v19, v19
	v_pk_fma_f32 v[16:17], v[20:21], v[16:17], s[50:51] op_sel_hi:[1,1,0]
	v_fma_f32 v22, |v14|, s28, 1.0
	v_fma_f32 v23, |v15|, s28, 1.0
	v_pk_fma_f32 v[16:17], v[20:21], v[16:17], s[72:73] op_sel_hi:[1,1,0]
	v_rcp_f32_e32 v22, v22
	v_pk_mul_f32 v[16:17], v[20:21], v[16:17]
	v_rcp_f32_e32 v23, v23
	v_pk_mul_f32 v[16:17], v[18:19], v[16:17]
	v_max_f32_e32 v240, 0, v12
	v_max_f32_e32 v241, 0, v13
	v_fma_f32 v12, -|v12|, v16, v240
	v_fma_f32 v13, -|v13|, v17, v241
	v_pk_mul_f32 v[20:21], v[14:15], v[14:15]
	s_nop 1
	v_pk_fma_f32 v[16:17], v[22:23], s[30:31], v[150:151] op_sel_hi:[1,0,0]
	v_pk_mul_f32 v[18:19], v[20:21], s[74:75] op_sel_hi:[1,0]
	v_pk_fma_f32 v[16:17], v[22:23], v[16:17], s[36:37] op_sel_hi:[1,1,0]
	v_exp_f32_e32 v18, v18
	v_exp_f32_e32 v19, v19
	v_pk_fma_f32 v[16:17], v[22:23], v[16:17], s[50:51] op_sel_hi:[1,1,0]
	s_nop 0
	v_pk_fma_f32 v[16:17], v[22:23], v[16:17], s[72:73] op_sel_hi:[1,1,0]
	s_nop 0
	v_pk_mul_f32 v[16:17], v[22:23], v[16:17]
	s_nop 0
	v_pk_mul_f32 v[16:17], v[18:19], v[16:17]
	s_nop 0
	v_max_f32_e32 v240, 0, v14
	v_max_f32_e32 v241, 0, v15
	v_fma_f32 v14, -|v14|, v16, v240
	v_fma_f32 v15, -|v15|, v17, v241
	s_nop 0
	v_mul_f32_e32 v18, 0xbfb8aa3b, v9
	v_mul_f32_e32 v16, 0xbfb8aa3b, v8
	v_exp_f32_e32 v18, v18
	v_exp_f32_e32 v16, v16
	s_nop 0
	v_add_f32_e32 v16, 1.0, v16
	s_nop 0
	v_add_f32_e32 v17, 1.0, v18
	v_mul_f32_e32 v18, 0xbfb8aa3b, v10
	v_mul_f32_e32 v19, 0xbfb8aa3b, v11
	v_exp_f32_e32 v18, v18
	v_exp_f32_e32 v19, v19
	v_rcp_f32_e32 v16, v16
	v_rcp_f32_e32 v17, v17
	v_add_f32_e32 v18, 1.0, v18
	v_add_f32_e32 v19, 1.0, v19
	v_rcp_f32_e32 v18, v18
	v_rcp_f32_e32 v19, v19
	v_pk_mul_f32 v[8:9], v[8:9], v[16:17]
	v_fma_f32 v16, |v4|, s28, 1.0
	v_fma_f32 v17, |v5|, s28, 1.0
	v_pk_mul_f32 v[10:11], v[10:11], v[18:19]
	v_rcp_f32_e32 v16, v16
	v_rcp_f32_e32 v17, v17
	v_pk_mul_f32 v[10:11], v[14:15], v[10:11]
	v_pk_mul_f32 v[14:15], v[4:5], v[4:5]
	v_pk_mul_f32 v[8:9], v[12:13], v[8:9]
	v_pk_fma_f32 v[12:13], v[16:17], s[30:31], v[150:151] op_sel_hi:[1,0,0]
	v_pk_mul_f32 v[14:15], v[14:15], s[74:75] op_sel_hi:[1,0]
	v_pk_fma_f32 v[12:13], v[16:17], v[12:13], s[36:37] op_sel_hi:[1,1,0]
	v_exp_f32_e32 v14, v14
	v_exp_f32_e32 v15, v15
	v_pk_fma_f32 v[12:13], v[16:17], v[12:13], s[50:51] op_sel_hi:[1,1,0]
	s_nop 0
	v_pk_fma_f32 v[12:13], v[16:17], v[12:13], s[72:73] op_sel_hi:[1,1,0]
	v_fma_f32 v18, |v6|, s28, 1.0
	v_fma_f32 v19, |v7|, s28, 1.0
	v_pk_mul_f32 v[12:13], v[16:17], v[12:13]
	v_rcp_f32_e32 v18, v18
	v_rcp_f32_e32 v19, v19
	v_pk_mul_f32 v[12:13], v[14:15], v[12:13]
	v_max_f32_e32 v240, 0, v4
	v_max_f32_e32 v241, 0, v5
	v_fma_f32 v4, -|v4|, v12, v240
	v_fma_f32 v5, -|v5|, v13, v241
	v_pk_mul_f32 v[16:17], v[6:7], v[6:7]
	s_nop 1
	v_pk_fma_f32 v[12:13], v[18:19], s[30:31], v[150:151] op_sel_hi:[1,0,0]
	v_pk_mul_f32 v[14:15], v[16:17], s[74:75] op_sel_hi:[1,0]
	v_pk_fma_f32 v[12:13], v[18:19], v[12:13], s[36:37] op_sel_hi:[1,1,0]
	v_exp_f32_e32 v14, v14
	v_exp_f32_e32 v15, v15
	v_pk_fma_f32 v[12:13], v[18:19], v[12:13], s[50:51] op_sel_hi:[1,1,0]
	v_mul_f32_e32 v16, 0xbfb8aa3b, v0
	v_pk_fma_f32 v[12:13], v[18:19], v[12:13], s[72:73] op_sel_hi:[1,1,0]
	v_exp_f32_e32 v16, v16
	v_mul_f32_e32 v17, 0xbfb8aa3b, v1
	v_pk_mul_f32 v[12:13], v[18:19], v[12:13]
	v_exp_f32_e32 v17, v17
	v_pk_mul_f32 v[12:13], v[14:15], v[12:13]
	v_max_f32_e32 v240, 0, v6
	v_max_f32_e32 v241, 0, v7
	v_fma_f32 v6, -|v6|, v12, v240
	v_fma_f32 v7, -|v7|, v13, v241
	s_nop 0
	v_add_f32_e32 v12, 1.0, v16
	v_mul_f32_e32 v14, 0xbfb8aa3b, v2
	v_rcp_f32_e32 v16, v12
	v_add_f32_e32 v12, 1.0, v17
	v_exp_f32_e32 v14, v14
	v_mul_f32_e32 v17, 0xbfb8aa3b, v3
	v_exp_f32_e32 v19, v17
	v_rcp_f32_e32 v17, v12
	v_add_f32_e32 v12, 1.0, v14
	v_rcp_f32_e32 v18, v12
	v_add_f32_e32 v12, 1.0, v19
	v_rcp_f32_e32 v19, v12
	v_pk_mul_f32 v[0:1], v[0:1], v[16:17]
	v_pk_mul_f32 v[2:3], v[2:3], v[18:19]
	s_nop 0
	v_pk_mul_f32 v[6:7], v[6:7], v[2:3]
	v_pk_mul_f32 v[2:3], v[4:5], v[0:1]
	v_add_co_u32_e32 v4, vcc, 0x58000, v148
	v_cvt_pk_bf16_f32 v0, v8, v9
	v_cvt_pk_bf16_f32 v1, v10, v11
	v_cvt_pk_bf16_f32 v2, v2, v3
	v_cvt_pk_bf16_f32 v3, v6, v7
	s_nop 1
	v_addc_co_u32_e32 v5, vcc, 0, v149, vcc
	s_waitcnt vmcnt(7)
	global_store_dwordx4 v[4:5], v[0:3], off nt
	s_andn2_b64 vcc, exec, s[4:5]
	s_mov_b64 s[4:5], -1
	s_cbranch_vccnz .LBB0_152
